# GEMM main loops: per-cluster s_setprio toggles removed, one static priority raise for the younger wave half per phase
# baseline (speedup 1.0000x reference)
.LBB0_410:
	s_cmp_lt_i32 s68, 3
	s_cselect_b64 s[4:5], -1, 0
	s_and_b64 s[4:5], s[4:5], s[0:1]
	s_andn2_b64 vcc, exec, s[4:5]
	s_cbranch_vccnz .LBB0_431
	v_readfirstlane_b32 s101, v145
	s_cmp_lt_u32 s101, 4
	s_cbranch_scc1 .Lprio_2
	s_setprio 1
.Lprio_2:
	s_cmpk_gt_i32 s2, 0x1ff
	v_readfirstlane_b32 s1, v146
	s_cbranch_scc1 .LBB0_431
	v_lshrrev_b32_e32 v13, 1, v146
	v_lshrrev_b32_e32 v2, 5, v146
	v_and_b32_e32 v11, 24, v13
	v_and_b32_e32 v2, 4, v2
	v_bfe_u32 v3, v146, 2, 2
	s_add_u32 s3, s30, 0x1f000000
	v_lshlrev_b32_e32 v0, 4, v146
	v_and_b32_e32 v1, 32, v146
	v_bfe_u32 v10, v146, 2, 4
	v_or3_b32 v2, v2, v3, v11
	v_lshrrev_b32_e32 v3, 3, v146
	s_movk_i32 s0, 0x70
	s_addc_u32 s33, s31, 0
	v_bitop3_b32 v8, v0, v1, 48 bitop3:0x6c
	v_and_b32_e32 v9, 64, v146
	v_and_or_b32 v4, v3, s0, v10
	s_movk_i32 s0, 0x60
	v_add_u32_e32 v12, 0x2000, v0
	s_waitcnt lgkmcnt(0)
	s_add_u32 s40, s30, 0x2f00000
	v_or_b32_e32 v1, v8, v9
	v_and_or_b32 v3, v3, s0, v2
	v_lshrrev_b32_e32 v0, 7, v12
	s_movk_i32 s0, 0xf0
	s_addc_u32 s41, s31, 0
	v_lshl_or_b32 v130, v3, 12, v1
	v_and_or_b32 v3, v0, s0, v10
	s_movk_i32 s0, 0xe0
	s_ashr_i32 s43, s2, 31
	v_and_or_b32 v0, v0, s0, v2
	s_lshr_b32 s0, s43, 29
	s_add_i32 s0, s2, s0
	s_and_b32 s6, s0, -8
	s_lshr_b32 s10, s1, 6
	s_sub_i32 s6, s2, s6
	s_lshr_b32 s12, s1, 8
	s_lshl_b32 s42, s10, 10
	s_lshl_b32 s8, s6, 6
	s_ashr_i32 s0, s0, 3
	s_mul_i32 s7, s6, 0x41
	s_cmp_lt_i32 s6, 0
	s_cselect_b32 s6, s7, s8
	s_add_i32 s0, s6, s0
	s_ashr_i32 s6, s0, 31
	s_lshr_b32 s6, s6, 26
	s_add_i32 s6, s0, s6
	s_ashr_i32 s7, s6, 6
	s_andn2_b32 s6, s6, 63
	s_sub_i32 s6, s0, s6
	s_bfe_i32 s0, s6, 0x80000
	s_bfe_u32 s0, s0, 0x3000c
	s_add_i32 s8, s6, s0
	s_bfe_i32 s0, s8, 0x80000
	s_and_b32 s8, s8, 0xf8
	s_sub_i32 s6, s6, s8
	s_lshl_b32 s7, s7, 3
	s_sext_i32_i16 s0, s0
	s_sext_i32_i8 s6, s6
	s_lshr_b32 s0, s0, 3
	s_add_i32 s20, s7, s6
	s_ashr_i32 s21, s20, 31
	s_bfe_i64 s[8:9], s[0:1], 0x100000
	s_lshl_b64 s[6:7], s[20:21], 20
	s_lshl_b64 s[8:9], s[8:9], 20
	s_add_u32 s38, s40, s8
	s_addc_u32 s39, s41, s9
	s_add_i32 s21, s42, 0
	s_add_i32 m0, s21, 0x10000
	v_lshl_or_b32 v134, v0, 12, v1
	global_load_lds_dwordx4 v130, s[38:39]
	s_add_i32 m0, s21, 0x12000
	s_add_u32 s8, s38, 0x80000
	global_load_lds_dwordx4 v134, s[38:39]
	s_addc_u32 s9, s39, 0
	s_add_i32 m0, s21, 0x14000
	v_lshl_or_b32 v128, v4, 12, v1
	global_load_lds_dwordx4 v130, s[8:9]
	s_add_i32 m0, s21, 0x16000
	s_add_u32 s26, s3, s6
	s_addc_u32 s27, s33, s7
	s_add_i32 s44, s21, 0x2000
	global_load_lds_dwordx4 v134, s[8:9]
	s_mov_b32 m0, s21
	s_add_u32 s6, s26, 0x80000
	v_lshl_or_b32 v132, v3, 12, v1
	global_load_lds_dwordx4 v128, s[26:27]
	s_mov_b32 m0, s44
	s_addc_u32 s7, s27, 0
	s_add_i32 s45, s21, 0x4000
	global_load_lds_dwordx4 v132, s[26:27]
	s_mov_b32 m0, s45
	s_add_i32 s50, s21, 0x6000
	global_load_lds_dwordx4 v128, s[6:7]
	s_mov_b32 m0, s50
	v_mov_b32_e32 v137, 0
	global_load_lds_dwordx4 v132, s[6:7]
	v_mov_b32_e32 v131, v137
	v_mov_b32_e32 v135, v137
	v_mov_b32_e32 v129, v137
	v_mov_b32_e32 v133, v137
	s_cmp_eq_u32 s12, 1
	s_mov_b32 s51, 0
	v_lshl_add_u64 v[6:7], s[38:39], 0, v[130:131]
	v_lshl_add_u64 v[4:5], s[38:39], 0, v[134:135]
	v_lshl_add_u64 v[0:1], s[26:27], 0, v[128:129]
	s_cselect_b64 s[6:7], -1, 0
	s_cmp_lg_u32 s12, 1
	v_lshl_add_u64 v[2:3], s[26:27], 0, v[132:133]
	s_cbranch_scc1 .LBB0_414
	s_barrier

.LBB0_424:
	ds_read_b128 v[156:159], v153
	ds_read_b128 v[160:163], v153 offset:1024
	ds_read_b128 v[164:167], v153 offset:2048
	ds_read_b128 v[168:171], v153 offset:3072
	ds_read_b128 v[172:175], v154
	ds_read_b128 v[176:179], v154 offset:1024
	ds_read_b128 v[180:183], v154 offset:2048
	ds_read_b128 v[184:187], v154 offset:3072
	s_add_u32 s34, s26, 0xfff80080
	s_addc_u32 s35, s27, -1
	s_cmp_eq_u32 s63, 28
	s_cselect_b32 s35, s17, s35
	s_cselect_b32 s34, s59, s34
	s_cselect_b32 s39, s15, s62
	s_cselect_b32 s38, s60, s61
	v_lshl_add_u64 v[220:221], s[26:27], 0, v[138:139]
	s_add_i32 m0, s21, 0xc000
	ds_read_b128 v[188:191], v155
	ds_read_b128 v[192:195], v155 offset:1024
	ds_read_b128 v[196:199], v155 offset:2048
	ds_read_b128 v[200:203], v155 offset:3072
	ds_read_b128 v[204:207], v155 offset:4096
	ds_read_b128 v[208:211], v155 offset:5120
	ds_read_b128 v[212:215], v155 offset:6144
	ds_read_b128 v[216:219], v155 offset:7168
	global_load_lds_dwordx4 v[220:221], off
	v_lshl_add_u64 v[220:221], s[26:27], 0, v[140:141]
	s_add_i32 m0, s21, 0xe000
	s_nop 0
	global_load_lds_dwordx4 v[220:221], off
	s_waitcnt vmcnt(8)
	s_waitcnt lgkmcnt(0)
	s_barrier
	s_waitcnt lgkmcnt(0)
	v_mfma_f32_16x16x32_bf16 v[124:127], v[156:159], v[188:191], v[124:127]
	v_mfma_f32_16x16x32_bf16 v[120:123], v[164:167], v[188:191], v[120:123]
	v_mfma_f32_16x16x32_bf16 v[116:119], v[156:159], v[196:199], v[116:119]
	v_mfma_f32_16x16x32_bf16 v[108:111], v[164:167], v[196:199], v[108:111]
	v_mfma_f32_16x16x32_bf16 v[100:103], v[156:159], v[204:207], v[100:103]
	v_mfma_f32_16x16x32_bf16 v[96:99], v[164:167], v[204:207], v[96:99]
	v_mfma_f32_16x16x32_bf16 v[84:87], v[156:159], v[212:215], v[84:87]
	v_mfma_f32_16x16x32_bf16 v[80:83], v[164:167], v[212:215], v[80:83]
	v_mfma_f32_16x16x32_bf16 v[124:127], v[160:163], v[192:195], v[124:127]
	v_mfma_f32_16x16x32_bf16 v[120:123], v[168:171], v[192:195], v[120:123]
	v_mfma_f32_16x16x32_bf16 v[116:119], v[160:163], v[200:203], v[116:119]
	v_mfma_f32_16x16x32_bf16 v[108:111], v[168:171], v[200:203], v[108:111]
	v_mfma_f32_16x16x32_bf16 v[100:103], v[160:163], v[208:211], v[100:103]
	v_mfma_f32_16x16x32_bf16 v[96:99], v[168:171], v[208:211], v[96:99]
	v_mfma_f32_16x16x32_bf16 v[84:87], v[160:163], v[216:219], v[84:87]
	v_mfma_f32_16x16x32_bf16 v[80:83], v[168:171], v[216:219], v[80:83]
	v_mfma_f32_16x16x32_bf16 v[112:115], v[172:175], v[188:191], v[112:115]
	v_mfma_f32_16x16x32_bf16 v[104:107], v[180:183], v[188:191], v[104:107]
	v_mfma_f32_16x16x32_bf16 v[92:95], v[172:175], v[196:199], v[92:95]
	v_mfma_f32_16x16x32_bf16 v[88:91], v[180:183], v[196:199], v[88:91]
	v_mfma_f32_16x16x32_bf16 v[76:79], v[172:175], v[204:207], v[76:79]
	v_mfma_f32_16x16x32_bf16 v[72:75], v[180:183], v[204:207], v[72:75]
	v_mfma_f32_16x16x32_bf16 v[68:71], v[172:175], v[212:215], v[68:71]
	v_mfma_f32_16x16x32_bf16 v[64:67], v[180:183], v[212:215], v[64:67]
	v_mfma_f32_16x16x32_bf16 v[112:115], v[176:179], v[192:195], v[112:115]
	v_mfma_f32_16x16x32_bf16 v[104:107], v[184:187], v[192:195], v[104:107]
	v_mfma_f32_16x16x32_bf16 v[92:95], v[176:179], v[200:203], v[92:95]
	v_mfma_f32_16x16x32_bf16 v[88:91], v[184:187], v[200:203], v[88:91]
	v_mfma_f32_16x16x32_bf16 v[76:79], v[176:179], v[208:211], v[76:79]
	v_mfma_f32_16x16x32_bf16 v[72:75], v[184:187], v[208:211], v[72:75]
	v_mfma_f32_16x16x32_bf16 v[68:71], v[176:179], v[216:219], v[68:71]
	v_mfma_f32_16x16x32_bf16 v[64:67], v[184:187], v[216:219], v[64:67]
	s_barrier
	s_add_i32 s64, s56, s42
	v_lshl_add_u64 v[220:221], s[38:39], 0, v[130:131]
	s_mov_b32 m0, s64
	ds_read_b128 v[188:191], v155 offset:16384
	ds_read_b128 v[192:195], v155 offset:17408
	ds_read_b128 v[196:199], v155 offset:18432
	ds_read_b128 v[200:203], v155 offset:19456
	ds_read_b128 v[204:207], v155 offset:20480
	ds_read_b128 v[208:211], v155 offset:21504
	ds_read_b128 v[212:215], v155 offset:22528
	ds_read_b128 v[216:219], v155 offset:23552
	global_load_lds_dwordx4 v[220:221], off
	s_add_i32 m0, s64, 0x2000
	s_add_u32 s64, s38, 0x80000
	v_lshl_add_u64 v[222:223], s[38:39], 0, v[134:135]
	s_addc_u32 s65, s39, 0
	s_add_i32 s72, s57, s42
	global_load_lds_dwordx4 v[222:223], off
	v_lshl_add_u64 v[224:225], s[64:65], 0, v[130:131]
	s_mov_b32 m0, s72
	v_lshl_add_u64 v[226:227], s[34:35], 0, v[132:133]
	global_load_lds_dwordx4 v[224:225], off
	v_lshl_add_u64 v[224:225], s[64:65], 0, v[134:135]
	s_add_i32 m0, s72, 0x2000
	s_nop 0
	global_load_lds_dwordx4 v[224:225], off
	v_lshl_add_u64 v[224:225], s[34:35], 0, v[128:129]
	s_mov_b32 m0, s21
	s_nop 0
	global_load_lds_dwordx4 v[224:225], off
	s_mov_b32 m0, s44
	s_nop 0
	global_load_lds_dwordx4 v[226:227], off
	s_waitcnt vmcnt(8)
	s_waitcnt lgkmcnt(0)
	s_barrier
	s_waitcnt lgkmcnt(0)
	v_mfma_f32_16x16x32_bf16 v[60:63], v[156:159], v[188:191], v[60:63]
	v_mfma_f32_16x16x32_bf16 v[56:59], v[164:167], v[188:191], v[56:59]
	v_mfma_f32_16x16x32_bf16 v[52:55], v[156:159], v[196:199], v[52:55]
	v_mfma_f32_16x16x32_bf16 v[48:51], v[164:167], v[196:199], v[48:51]
	v_mfma_f32_16x16x32_bf16 v[36:39], v[156:159], v[204:207], v[36:39]
	v_mfma_f32_16x16x32_bf16 v[32:35], v[164:167], v[204:207], v[32:35]
	v_mfma_f32_16x16x32_bf16 v[20:23], v[156:159], v[212:215], v[20:23]
	v_mfma_f32_16x16x32_bf16 v[16:19], v[164:167], v[212:215], v[16:19]
	v_mfma_f32_16x16x32_bf16 v[60:63], v[160:163], v[192:195], v[60:63]
	v_mfma_f32_16x16x32_bf16 v[56:59], v[168:171], v[192:195], v[56:59]
	v_mfma_f32_16x16x32_bf16 v[52:55], v[160:163], v[200:203], v[52:55]
	v_mfma_f32_16x16x32_bf16 v[48:51], v[168:171], v[200:203], v[48:51]
	v_mfma_f32_16x16x32_bf16 v[36:39], v[160:163], v[208:211], v[36:39]
	v_mfma_f32_16x16x32_bf16 v[32:35], v[168:171], v[208:211], v[32:35]
	v_mfma_f32_16x16x32_bf16 v[20:23], v[160:163], v[216:219], v[20:23]
	v_mfma_f32_16x16x32_bf16 v[16:19], v[168:171], v[216:219], v[16:19]
	v_mfma_f32_16x16x32_bf16 v[44:47], v[172:175], v[188:191], v[44:47]
	v_mfma_f32_16x16x32_bf16 v[40:43], v[180:183], v[188:191], v[40:43]
	v_mfma_f32_16x16x32_bf16 v[28:31], v[172:175], v[196:199], v[28:31]
	v_mfma_f32_16x16x32_bf16 v[24:27], v[180:183], v[196:199], v[24:27]
	v_mfma_f32_16x16x32_bf16 v[12:15], v[172:175], v[204:207], v[12:15]
	v_mfma_f32_16x16x32_bf16 v[8:11], v[180:183], v[204:207], v[8:11]
	v_mfma_f32_16x16x32_bf16 v[4:7], v[172:175], v[212:215], v[4:7]
	v_mfma_f32_16x16x32_bf16 v[0:3], v[180:183], v[212:215], v[0:3]
	v_mfma_f32_16x16x32_bf16 v[44:47], v[176:179], v[192:195], v[44:47]
	v_mfma_f32_16x16x32_bf16 v[40:43], v[184:187], v[192:195], v[40:43]
	v_mfma_f32_16x16x32_bf16 v[28:31], v[176:179], v[200:203], v[28:31]
	v_mfma_f32_16x16x32_bf16 v[24:27], v[184:187], v[200:203], v[24:27]
	v_mfma_f32_16x16x32_bf16 v[12:15], v[176:179], v[208:211], v[12:15]
	v_mfma_f32_16x16x32_bf16 v[8:11], v[184:187], v[208:211], v[8:11]
	v_mfma_f32_16x16x32_bf16 v[4:7], v[176:179], v[216:219], v[4:7]
	v_mfma_f32_16x16x32_bf16 v[0:3], v[184:187], v[216:219], v[0:3]
	s_barrier
	s_add_i32 s64, 0, 0x18000
	s_add_i32 s65, 0, 0x1c000
	v_add_u32_e32 v168, s64, v149
	v_add_u32_e32 v184, s65, v149
	ds_read_b128 v[156:159], v168
	ds_read_b128 v[160:163], v168 offset:1024
	ds_read_b128 v[164:167], v168 offset:2048
	ds_read_b128 v[168:171], v168 offset:3072
	ds_read_b128 v[172:175], v184
	ds_read_b128 v[176:179], v184 offset:1024
	ds_read_b128 v[180:183], v184 offset:2048
	ds_read_b128 v[184:187], v184 offset:3072
	s_add_u32 s34, s34, 0x80000
	s_addc_u32 s35, s35, 0
	s_mov_b32 m0, s45
	v_lshl_add_u64 v[228:229], s[34:35], 0, v[128:129]
	ds_read_b128 v[188:191], v155 offset:32768
	ds_read_b128 v[192:195], v155 offset:33792
	ds_read_b128 v[196:199], v155 offset:34816
	ds_read_b128 v[200:203], v155 offset:35840
	ds_read_b128 v[204:207], v155 offset:36864
	ds_read_b128 v[208:211], v155 offset:37888
	ds_read_b128 v[212:215], v155 offset:38912
	ds_read_b128 v[216:219], v155 offset:39936
	global_load_lds_dwordx4 v[228:229], off
	v_lshl_add_u64 v[228:229], s[34:35], 0, v[132:133]
	s_mov_b32 m0, s50
	s_nop 0
	global_load_lds_dwordx4 v[228:229], off
	s_waitcnt vmcnt(8)
	s_waitcnt lgkmcnt(0)
	s_barrier
	s_waitcnt lgkmcnt(0)
	v_mfma_f32_16x16x32_bf16 v[124:127], v[156:159], v[188:191], v[124:127]
	v_mfma_f32_16x16x32_bf16 v[120:123], v[164:167], v[188:191], v[120:123]
	v_mfma_f32_16x16x32_bf16 v[116:119], v[156:159], v[196:199], v[116:119]
	v_mfma_f32_16x16x32_bf16 v[108:111], v[164:167], v[196:199], v[108:111]
	v_mfma_f32_16x16x32_bf16 v[100:103], v[156:159], v[204:207], v[100:103]
	v_mfma_f32_16x16x32_bf16 v[96:99], v[164:167], v[204:207], v[96:99]
	v_mfma_f32_16x16x32_bf16 v[84:87], v[156:159], v[212:215], v[84:87]
	v_mfma_f32_16x16x32_bf16 v[80:83], v[164:167], v[212:215], v[80:83]
	v_mfma_f32_16x16x32_bf16 v[124:127], v[160:163], v[192:195], v[124:127]
	v_mfma_f32_16x16x32_bf16 v[120:123], v[168:171], v[192:195], v[120:123]
	v_mfma_f32_16x16x32_bf16 v[116:119], v[160:163], v[200:203], v[116:119]
	v_mfma_f32_16x16x32_bf16 v[108:111], v[168:171], v[200:203], v[108:111]
	v_mfma_f32_16x16x32_bf16 v[100:103], v[160:163], v[208:211], v[100:103]
	v_mfma_f32_16x16x32_bf16 v[96:99], v[168:171], v[208:211], v[96:99]
	v_mfma_f32_16x16x32_bf16 v[84:87], v[160:163], v[216:219], v[84:87]
	v_mfma_f32_16x16x32_bf16 v[80:83], v[168:171], v[216:219], v[80:83]
	v_mfma_f32_16x16x32_bf16 v[112:115], v[172:175], v[188:191], v[112:115]
	v_mfma_f32_16x16x32_bf16 v[104:107], v[180:183], v[188:191], v[104:107]
	v_mfma_f32_16x16x32_bf16 v[92:95], v[172:175], v[196:199], v[92:95]
	v_mfma_f32_16x16x32_bf16 v[88:91], v[180:183], v[196:199], v[88:91]
	v_mfma_f32_16x16x32_bf16 v[76:79], v[172:175], v[204:207], v[76:79]
	v_mfma_f32_16x16x32_bf16 v[72:75], v[180:183], v[204:207], v[72:75]
	v_mfma_f32_16x16x32_bf16 v[68:71], v[172:175], v[212:215], v[68:71]
	v_mfma_f32_16x16x32_bf16 v[64:67], v[180:183], v[212:215], v[64:67]
	v_mfma_f32_16x16x32_bf16 v[112:115], v[176:179], v[192:195], v[112:115]
	v_mfma_f32_16x16x32_bf16 v[104:107], v[184:187], v[192:195], v[104:107]
	v_mfma_f32_16x16x32_bf16 v[92:95], v[176:179], v[200:203], v[92:95]
	v_mfma_f32_16x16x32_bf16 v[88:91], v[184:187], v[200:203], v[88:91]
	v_mfma_f32_16x16x32_bf16 v[76:79], v[176:179], v[208:211], v[76:79]
	v_mfma_f32_16x16x32_bf16 v[72:75], v[184:187], v[208:211], v[72:75]
	v_mfma_f32_16x16x32_bf16 v[68:71], v[176:179], v[216:219], v[68:71]
	v_mfma_f32_16x16x32_bf16 v[64:67], v[184:187], v[216:219], v[64:67]
	s_barrier
	s_add_i32 s34, s64, s42
	v_lshl_add_u64 v[220:221], v[220:221], 0, s[10:11]
	s_mov_b32 m0, s34
	ds_read_b128 v[188:191], v155 offset:49152
	ds_read_b128 v[192:195], v155 offset:50176
	ds_read_b128 v[196:199], v155 offset:51200
	ds_read_b128 v[200:203], v155 offset:52224
	ds_read_b128 v[204:207], v155 offset:53248
	ds_read_b128 v[208:211], v155 offset:54272
	ds_read_b128 v[212:215], v155 offset:55296
	ds_read_b128 v[216:219], v155 offset:56320
	global_load_lds_dwordx4 v[220:221], off
	s_add_i32 m0, s34, 0x2000
	s_add_u32 s34, s38, 0x80080
	v_lshl_add_u64 v[220:221], v[222:223], 0, s[10:11]
	s_addc_u32 s35, s39, 0
	s_add_i32 s38, s65, s42
	global_load_lds_dwordx4 v[220:221], off
	v_lshl_add_u64 v[220:221], s[34:35], 0, v[130:131]
	s_mov_b32 m0, s38
	s_nop 0
	global_load_lds_dwordx4 v[220:221], off
	v_lshl_add_u64 v[220:221], s[34:35], 0, v[134:135]
	s_add_i32 m0, s38, 0x2000
	s_nop 0
	global_load_lds_dwordx4 v[220:221], off
	v_lshl_add_u64 v[220:221], v[224:225], 0, s[10:11]
	s_mov_b32 m0, s53
	s_nop 0
	global_load_lds_dwordx4 v[220:221], off
	v_lshl_add_u64 v[220:221], v[226:227], 0, s[10:11]
	s_mov_b32 m0, s54
	s_nop 0
	global_load_lds_dwordx4 v[220:221], off
	s_waitcnt vmcnt(8)
	s_waitcnt lgkmcnt(0)
	s_barrier
	s_waitcnt lgkmcnt(0)
	v_mfma_f32_16x16x32_bf16 v[60:63], v[156:159], v[188:191], v[60:63]
	v_mfma_f32_16x16x32_bf16 v[56:59], v[164:167], v[188:191], v[56:59]
	v_mfma_f32_16x16x32_bf16 v[52:55], v[156:159], v[196:199], v[52:55]
	v_mfma_f32_16x16x32_bf16 v[48:51], v[164:167], v[196:199], v[48:51]
	v_mfma_f32_16x16x32_bf16 v[36:39], v[156:159], v[204:207], v[36:39]
	v_mfma_f32_16x16x32_bf16 v[32:35], v[164:167], v[204:207], v[32:35]
	v_mfma_f32_16x16x32_bf16 v[20:23], v[156:159], v[212:215], v[20:23]
	v_mfma_f32_16x16x32_bf16 v[16:19], v[164:167], v[212:215], v[16:19]
	v_mfma_f32_16x16x32_bf16 v[60:63], v[160:163], v[192:195], v[60:63]
	v_mfma_f32_16x16x32_bf16 v[56:59], v[168:171], v[192:195], v[56:59]
	v_mfma_f32_16x16x32_bf16 v[52:55], v[160:163], v[200:203], v[52:55]
	v_mfma_f32_16x16x32_bf16 v[48:51], v[168:171], v[200:203], v[48:51]
	v_mfma_f32_16x16x32_bf16 v[36:39], v[160:163], v[208:211], v[36:39]
	v_mfma_f32_16x16x32_bf16 v[32:35], v[168:171], v[208:211], v[32:35]
	v_mfma_f32_16x16x32_bf16 v[20:23], v[160:163], v[216:219], v[20:23]
	v_mfma_f32_16x16x32_bf16 v[16:19], v[168:171], v[216:219], v[16:19]
	v_mfma_f32_16x16x32_bf16 v[44:47], v[172:175], v[188:191], v[44:47]
	v_mfma_f32_16x16x32_bf16 v[40:43], v[180:183], v[188:191], v[40:43]
	v_mfma_f32_16x16x32_bf16 v[28:31], v[172:175], v[196:199], v[28:31]
	v_mfma_f32_16x16x32_bf16 v[24:27], v[180:183], v[196:199], v[24:27]
	v_mfma_f32_16x16x32_bf16 v[12:15], v[172:175], v[204:207], v[12:15]
	v_mfma_f32_16x16x32_bf16 v[8:11], v[180:183], v[204:207], v[8:11]
	v_mfma_f32_16x16x32_bf16 v[4:7], v[172:175], v[212:215], v[4:7]
	v_mfma_f32_16x16x32_bf16 v[0:3], v[180:183], v[212:215], v[0:3]
	v_mfma_f32_16x16x32_bf16 v[44:47], v[176:179], v[192:195], v[44:47]
	v_mfma_f32_16x16x32_bf16 v[40:43], v[184:187], v[192:195], v[40:43]
	v_mfma_f32_16x16x32_bf16 v[28:31], v[176:179], v[200:203], v[28:31]
	v_mfma_f32_16x16x32_bf16 v[24:27], v[184:187], v[200:203], v[24:27]
	v_mfma_f32_16x16x32_bf16 v[12:15], v[176:179], v[208:211], v[12:15]
	v_mfma_f32_16x16x32_bf16 v[8:11], v[184:187], v[208:211], v[8:11]
	v_mfma_f32_16x16x32_bf16 v[4:7], v[176:179], v[216:219], v[4:7]
	v_mfma_f32_16x16x32_bf16 v[0:3], v[184:187], v[216:219], v[0:3]
	s_barrier
	s_add_i32 s63, s63, 2
	s_add_u32 s26, s26, 0x100
	s_addc_u32 s27, s27, 0
	s_add_u32 s61, s61, 0x100
	s_addc_u32 s62, s62, 0
	s_cmp_gt_u32 s63, 29
	s_cbranch_scc0 .LBB0_424
	s_and_b64 vcc, exec, s[12:13]
	s_cbranch_vccz .LBB0_427
	s_barrier

.LBB0_431:
	s_setprio 0
	s_cmp_gt_i32 s69, 3
	s_cselect_b64 s[0:1], -1, 0
	s_and_b64 s[4:5], s[4:5], s[0:1]
	s_andn2_b64 vcc, exec, s[4:5]
	s_cbranch_vccnz .LBB0_481
	s_waitcnt vmcnt(0)
	v_cmp_eq_u32_e32 vcc, 0, v146
	s_waitcnt vmcnt(0) lgkmcnt(0)
	s_barrier
	s_and_saveexec_b64 s[4:5], vcc
	s_cbranch_execz .LBB0_480
	s_add_i32 s3, 0, 0x23fc0
	v_mov_b32_e32 v0, s3
	s_waitcnt vmcnt(0) expcnt(0) lgkmcnt(0)
	ds_read_b32 v2, v0
	s_add_i32 s3, 0, 0x23fc4
	v_mov_b32_e32 v0, s3
	ds_read_b32 v0, v0
	s_waitcnt lgkmcnt(1)
	v_cmp_ne_u32_e32 vcc, 0, v2
	s_cbranch_vccnz .LBB0_448
	s_add_u32 s6, s30, 0x32200
	s_addc_u32 s7, s31, 0
	s_add_u32 s8, s30, 0x32400
	s_addc_u32 s9, s31, 0
	s_add_u32 s10, s30, 0x32500
	s_addc_u32 s11, s31, 0
	s_add_u32 s12, s30, 0x32600
	s_addc_u32 s13, s31, 0
	s_add_u32 s14, s30, 0x32700
	s_addc_u32 s15, s31, 0
	s_add_u32 s16, s30, 0x32800
	s_addc_u32 s17, s31, 0
	s_add_u32 s20, s30, 0x32900
	s_addc_u32 s21, s31, 0
	s_add_u32 s22, s30, 0x32a00
	s_addc_u32 s23, s31, 0
	s_add_u32 s24, s30, 0x32b00
	s_addc_u32 s25, s31, 0
	s_add_u32 s26, s30, 0x32c00
	s_addc_u32 s27, s31, 0
	s_add_u32 s34, s30, 0x32d00
	s_addc_u32 s35, s31, 0
	s_add_u32 s38, s30, 0x32e00
	s_addc_u32 s39, s31, 0
	s_add_u32 s40, s30, 0x32f00
	s_addc_u32 s41, s31, 0
	s_add_u32 s42, s30, 0x33000
	s_addc_u32 s43, s31, 0
	s_add_u32 s44, s30, 0x33100
	s_addc_u32 s45, s31, 0
	s_add_u32 s50, s30, 0x33200
	s_addc_u32 s51, s31, 0
	s_mul_i32 s3, s71, s85
	s_add_u32 s52, s30, 0x33300
	s_mul_i32 s3, s3, s70
	s_addc_u32 s53, s31, 0
	s_mov_b32 s33, 1
	v_mov_b32_e32 v16, 0
	s_branch .LBB0_436

.LBB0_673:
	s_cmp_lt_i32 s68, 5
	s_cselect_b64 s[4:5], -1, 0
	s_and_b64 s[4:5], s[4:5], s[0:1]
	s_andn2_b64 vcc, exec, s[4:5]
	s_cbranch_vccnz .LBB0_694
	v_readfirstlane_b32 s101, v145
	s_cmp_lt_u32 s101, 4
	s_cbranch_scc1 .Lprio_4
	s_setprio 1
.Lprio_4:
	s_cmpk_gt_i32 s2, 0x3ff
	v_readfirstlane_b32 s1, v146
	s_cbranch_scc1 .LBB0_694
	v_lshrrev_b32_e32 v2, 1, v146
	v_and_b32_e32 v11, 24, v2
	v_lshrrev_b32_e32 v2, 5, v146
	v_and_b32_e32 v2, 4, v2
	v_bfe_u32 v3, v146, 2, 2
	s_add_u32 s3, s30, 0x27000000
	v_lshlrev_b32_e32 v0, 4, v146
	v_and_b32_e32 v1, 32, v146
	v_bfe_u32 v10, v146, 2, 4
	v_or3_b32 v2, v2, v3, v11
	v_lshrrev_b32_e32 v3, 3, v146
	s_movk_i32 s0, 0x70
	s_addc_u32 s17, s31, 0
	v_bitop3_b32 v8, v0, v1, 48 bitop3:0x6c
	v_and_b32_e32 v9, 64, v146
	v_and_or_b32 v4, v3, s0, v10
	s_movk_i32 s0, 0x60
	v_add_u32_e32 v12, 0x2000, v0
	s_waitcnt lgkmcnt(0)
	s_add_u32 s44, s30, 0x3700000
	v_or_b32_e32 v1, v8, v9
	v_and_or_b32 v3, v3, s0, v2
	v_lshrrev_b32_e32 v0, 7, v12
	s_movk_i32 s0, 0xf0
	s_addc_u32 s45, s31, 0
	v_lshl_or_b32 v152, v3, 12, v1
	v_and_or_b32 v3, v0, s0, v10
	s_movk_i32 s0, 0xe0
	s_ashr_i32 s51, s2, 31
	v_and_or_b32 v0, v0, s0, v2
	s_lshr_b32 s0, s51, 29
	s_add_i32 s0, s2, s0
	s_and_b32 s6, s0, -8
	s_lshr_b32 s12, s1, 6
	s_sub_i32 s6, s2, s6
	s_lshr_b32 s14, s1, 8
	s_lshl_b32 s50, s12, 10
	s_lshl_b32 s8, s6, 7
	s_ashr_i32 s0, s0, 3
	s_mul_i32 s7, s6, 0x81
	s_cmp_lt_i32 s6, 0
	s_cselect_b32 s6, s7, s8
	s_add_i32 s0, s6, s0
	s_ashr_i32 s6, s0, 31
	s_lshr_b32 s6, s6, 25
	s_add_i32 s6, s0, s6
	s_ashr_i32 s7, s6, 7
	s_and_b32 s6, s6, 0xffffff80
	s_sub_i32 s6, s0, s6
	s_bfe_i32 s0, s6, 0x80000
	s_bfe_u32 s0, s0, 0x3000c
	s_add_i32 s8, s6, s0
	s_bfe_i32 s0, s8, 0x80000
	s_and_b32 s8, s8, 0xf8
	s_sub_i32 s6, s6, s8
	s_lshl_b32 s7, s7, 3
	s_sext_i32_i16 s0, s0
	s_sext_i32_i8 s6, s6
	s_lshr_b32 s0, s0, 3
	s_add_i32 s38, s7, s6
	s_ashr_i32 s39, s38, 31
	s_bfe_i64 s[8:9], s[0:1], 0x100000
	s_lshl_b64 s[6:7], s[38:39], 20
	s_lshl_b64 s[8:9], s[8:9], 20
	s_add_u32 s42, s44, s8
	s_addc_u32 s43, s45, s9
	s_add_i32 s39, s50, 0
	s_add_i32 m0, s39, 0x10000
	v_lshl_or_b32 v156, v0, 12, v1
	global_load_lds_dwordx4 v152, s[42:43]
	s_add_i32 m0, s39, 0x12000
	s_add_u32 s8, s42, 0x80000
	global_load_lds_dwordx4 v156, s[42:43]
	s_addc_u32 s9, s43, 0
	s_add_i32 m0, s39, 0x14000
	v_lshl_or_b32 v150, v4, 12, v1
	global_load_lds_dwordx4 v152, s[8:9]
	s_add_i32 m0, s39, 0x16000
	s_add_u32 s40, s3, s6
	s_addc_u32 s41, s17, s7
	s_add_i32 s52, s39, 0x2000
	global_load_lds_dwordx4 v156, s[8:9]
	s_mov_b32 m0, s39
	s_add_u32 s6, s40, 0x80000
	v_lshl_or_b32 v154, v3, 12, v1
	global_load_lds_dwordx4 v150, s[40:41]
	s_mov_b32 m0, s52
	s_addc_u32 s7, s41, 0
	s_add_i32 s53, s39, 0x4000
	global_load_lds_dwordx4 v154, s[40:41]
	s_mov_b32 m0, s53
	s_add_i32 s54, s39, 0x6000
	global_load_lds_dwordx4 v150, s[6:7]
	s_mov_b32 m0, s54
	v_mov_b32_e32 v153, 0
	global_load_lds_dwordx4 v154, s[6:7]
	v_mov_b32_e32 v157, v153
	v_mov_b32_e32 v151, v153
	v_mov_b32_e32 v155, v153
	s_cmp_eq_u32 s14, 1
	s_mov_b32 s55, 0
	v_lshl_add_u64 v[6:7], s[42:43], 0, v[152:153]
	v_lshl_add_u64 v[4:5], s[42:43], 0, v[156:157]
	v_lshl_add_u64 v[0:1], s[40:41], 0, v[150:151]
	s_cselect_b64 s[6:7], -1, 0
	s_cmp_lg_u32 s14, 1
	v_lshl_add_u64 v[2:3], s[40:41], 0, v[154:155]
	s_cbranch_scc1 .LBB0_677
	s_barrier

.LBB0_687:
	ds_read_b128 v[80:83], v173
	ds_read_b128 v[84:87], v173 offset:1024
	ds_read_b128 v[88:91], v173 offset:2048
	ds_read_b128 v[92:95], v173 offset:3072
	ds_read_b128 v[166:169], v174
	ds_read_b128 v[176:179], v174 offset:1024
	ds_read_b128 v[180:183], v174 offset:2048
	ds_read_b128 v[184:187], v174 offset:3072
	s_add_u32 s34, s40, 0xfff80080
	s_addc_u32 s35, s41, -1
	s_cmp_eq_u32 s72, 28
	s_cselect_b32 s35, s23, s35
	s_cselect_b32 s34, s64, s34
	s_cselect_b32 s43, s21, s67
	s_cselect_b32 s42, s65, s66
	v_lshl_add_u64 v[170:171], s[40:41], 0, v[158:159]
	s_add_i32 m0, s39, 0xc000
	ds_read_b128 v[188:191], v175
	ds_read_b128 v[192:195], v175 offset:1024
	ds_read_b128 v[196:199], v175 offset:2048
	ds_read_b128 v[200:203], v175 offset:3072
	ds_read_b128 v[204:207], v175 offset:4096
	ds_read_b128 v[208:211], v175 offset:5120
	ds_read_b128 v[212:215], v175 offset:6144
	ds_read_b128 v[216:219], v175 offset:7168
	global_load_lds_dwordx4 v[170:171], off
	v_lshl_add_u64 v[170:171], s[40:41], 0, v[160:161]
	s_add_i32 m0, s39, 0xe000
	s_nop 0
	global_load_lds_dwordx4 v[170:171], off
	s_waitcnt vmcnt(8)
	s_waitcnt lgkmcnt(0)
	s_barrier
	s_waitcnt lgkmcnt(0)
	v_mfma_f32_16x16x32_bf16 v[140:143], v[80:83], v[188:191], v[140:143]
	v_mfma_f32_16x16x32_bf16 v[136:139], v[88:91], v[188:191], v[136:139]
	v_mfma_f32_16x16x32_bf16 v[124:127], v[80:83], v[196:199], v[124:127]
	v_mfma_f32_16x16x32_bf16 v[120:123], v[88:91], v[196:199], v[120:123]
	v_mfma_f32_16x16x32_bf16 v[108:111], v[80:83], v[204:207], v[108:111]
	v_mfma_f32_16x16x32_bf16 v[104:107], v[88:91], v[204:207], v[104:107]
	v_mfma_f32_16x16x32_bf16 v[76:79], v[80:83], v[212:215], v[76:79]
	v_mfma_f32_16x16x32_bf16 v[72:75], v[88:91], v[212:215], v[72:75]
	v_mfma_f32_16x16x32_bf16 v[140:143], v[84:87], v[192:195], v[140:143]
	v_mfma_f32_16x16x32_bf16 v[136:139], v[92:95], v[192:195], v[136:139]
	v_mfma_f32_16x16x32_bf16 v[124:127], v[84:87], v[200:203], v[124:127]
	v_mfma_f32_16x16x32_bf16 v[120:123], v[92:95], v[200:203], v[120:123]
	v_mfma_f32_16x16x32_bf16 v[108:111], v[84:87], v[208:211], v[108:111]
	v_mfma_f32_16x16x32_bf16 v[104:107], v[92:95], v[208:211], v[104:107]
	v_mfma_f32_16x16x32_bf16 v[76:79], v[84:87], v[216:219], v[76:79]
	v_mfma_f32_16x16x32_bf16 v[72:75], v[92:95], v[216:219], v[72:75]
	v_mfma_f32_16x16x32_bf16 v[132:135], v[166:169], v[188:191], v[132:135]
	v_mfma_f32_16x16x32_bf16 v[128:131], v[180:183], v[188:191], v[128:131]
	v_mfma_f32_16x16x32_bf16 v[116:119], v[166:169], v[196:199], v[116:119]
	v_mfma_f32_16x16x32_bf16 v[112:115], v[180:183], v[196:199], v[112:115]
	v_mfma_f32_16x16x32_bf16 v[100:103], v[166:169], v[204:207], v[100:103]
	v_mfma_f32_16x16x32_bf16 v[96:99], v[180:183], v[204:207], v[96:99]
	v_mfma_f32_16x16x32_bf16 v[68:71], v[166:169], v[212:215], v[68:71]
	v_mfma_f32_16x16x32_bf16 v[64:67], v[180:183], v[212:215], v[64:67]
	v_mfma_f32_16x16x32_bf16 v[132:135], v[176:179], v[192:195], v[132:135]
	v_mfma_f32_16x16x32_bf16 v[128:131], v[184:187], v[192:195], v[128:131]
	v_mfma_f32_16x16x32_bf16 v[116:119], v[176:179], v[200:203], v[116:119]
	v_mfma_f32_16x16x32_bf16 v[112:115], v[184:187], v[200:203], v[112:115]
	v_mfma_f32_16x16x32_bf16 v[100:103], v[176:179], v[208:211], v[100:103]
	v_mfma_f32_16x16x32_bf16 v[96:99], v[184:187], v[208:211], v[96:99]
	v_mfma_f32_16x16x32_bf16 v[68:71], v[176:179], v[216:219], v[68:71]
	v_mfma_f32_16x16x32_bf16 v[64:67], v[184:187], v[216:219], v[64:67]
	s_barrier
	s_add_i32 s73, s62, s50
	v_lshl_add_u64 v[170:171], s[42:43], 0, v[152:153]
	s_mov_b32 m0, s73
	ds_read_b128 v[188:191], v175 offset:16384
	ds_read_b128 v[192:195], v175 offset:17408
	ds_read_b128 v[196:199], v175 offset:18432
	ds_read_b128 v[200:203], v175 offset:19456
	ds_read_b128 v[204:207], v175 offset:20480
	ds_read_b128 v[208:211], v175 offset:21504
	ds_read_b128 v[212:215], v175 offset:22528
	ds_read_b128 v[216:219], v175 offset:23552
	global_load_lds_dwordx4 v[170:171], off
	s_add_i32 m0, s73, 0x2000
	s_add_u32 s74, s42, 0x80000
	v_lshl_add_u64 v[220:221], s[42:43], 0, v[156:157]
	s_addc_u32 s75, s43, 0
	s_add_i32 s73, s63, s50
	global_load_lds_dwordx4 v[220:221], off
	v_lshl_add_u64 v[222:223], s[74:75], 0, v[152:153]
	s_mov_b32 m0, s73
	v_lshl_add_u64 v[224:225], s[34:35], 0, v[154:155]
	global_load_lds_dwordx4 v[222:223], off
	v_lshl_add_u64 v[222:223], s[74:75], 0, v[156:157]
	s_add_i32 m0, s73, 0x2000
	s_nop 0
	global_load_lds_dwordx4 v[222:223], off
	v_lshl_add_u64 v[222:223], s[34:35], 0, v[150:151]
	s_mov_b32 m0, s39
	s_nop 0
	global_load_lds_dwordx4 v[222:223], off
	s_mov_b32 m0, s52
	s_nop 0
	global_load_lds_dwordx4 v[224:225], off
	s_waitcnt vmcnt(8)
	s_waitcnt lgkmcnt(0)
	s_barrier
	s_waitcnt lgkmcnt(0)
	v_mfma_f32_16x16x32_bf16 v[60:63], v[80:83], v[188:191], v[60:63]
	v_mfma_f32_16x16x32_bf16 v[56:59], v[88:91], v[188:191], v[56:59]
	v_mfma_f32_16x16x32_bf16 v[44:47], v[80:83], v[196:199], v[44:47]
	v_mfma_f32_16x16x32_bf16 v[40:43], v[88:91], v[196:199], v[40:43]
	v_mfma_f32_16x16x32_bf16 v[28:31], v[80:83], v[204:207], v[28:31]
	v_mfma_f32_16x16x32_bf16 v[24:27], v[88:91], v[204:207], v[24:27]
	v_mfma_f32_16x16x32_bf16 v[12:15], v[80:83], v[212:215], v[12:15]
	v_mfma_f32_16x16x32_bf16 v[8:11], v[88:91], v[212:215], v[8:11]
	v_mfma_f32_16x16x32_bf16 v[60:63], v[84:87], v[192:195], v[60:63]
	v_mfma_f32_16x16x32_bf16 v[56:59], v[92:95], v[192:195], v[56:59]
	v_mfma_f32_16x16x32_bf16 v[44:47], v[84:87], v[200:203], v[44:47]
	v_mfma_f32_16x16x32_bf16 v[40:43], v[92:95], v[200:203], v[40:43]
	v_mfma_f32_16x16x32_bf16 v[28:31], v[84:87], v[208:211], v[28:31]
	v_mfma_f32_16x16x32_bf16 v[24:27], v[92:95], v[208:211], v[24:27]
	v_mfma_f32_16x16x32_bf16 v[12:15], v[84:87], v[216:219], v[12:15]
	v_mfma_f32_16x16x32_bf16 v[8:11], v[92:95], v[216:219], v[8:11]
	v_mfma_f32_16x16x32_bf16 v[52:55], v[166:169], v[188:191], v[52:55]
	v_mfma_f32_16x16x32_bf16 v[48:51], v[180:183], v[188:191], v[48:51]
	v_mfma_f32_16x16x32_bf16 v[36:39], v[166:169], v[196:199], v[36:39]
	v_mfma_f32_16x16x32_bf16 v[32:35], v[180:183], v[196:199], v[32:35]
	v_mfma_f32_16x16x32_bf16 v[20:23], v[166:169], v[204:207], v[20:23]
	v_mfma_f32_16x16x32_bf16 v[16:19], v[180:183], v[204:207], v[16:19]
	v_mfma_f32_16x16x32_bf16 v[4:7], v[166:169], v[212:215], v[4:7]
	v_mfma_f32_16x16x32_bf16 v[0:3], v[180:183], v[212:215], v[0:3]
	v_mfma_f32_16x16x32_bf16 v[52:55], v[176:179], v[192:195], v[52:55]
	v_mfma_f32_16x16x32_bf16 v[48:51], v[184:187], v[192:195], v[48:51]
	v_mfma_f32_16x16x32_bf16 v[36:39], v[176:179], v[200:203], v[36:39]
	v_mfma_f32_16x16x32_bf16 v[32:35], v[184:187], v[200:203], v[32:35]
	v_mfma_f32_16x16x32_bf16 v[20:23], v[176:179], v[208:211], v[20:23]
	v_mfma_f32_16x16x32_bf16 v[16:19], v[184:187], v[208:211], v[16:19]
	v_mfma_f32_16x16x32_bf16 v[4:7], v[176:179], v[216:219], v[4:7]
	v_mfma_f32_16x16x32_bf16 v[0:3], v[184:187], v[216:219], v[0:3]
	s_barrier
	s_add_i32 s73, 0, 0x18000
	s_add_i32 s74, 0, 0x1c000
	v_add_u32_e32 v92, s73, v149
	v_add_u32_e32 v184, s74, v149
	ds_read_b128 v[80:83], v92
	ds_read_b128 v[84:87], v92 offset:1024
	ds_read_b128 v[88:91], v92 offset:2048
	ds_read_b128 v[92:95], v92 offset:3072
	ds_read_b128 v[166:169], v184
	ds_read_b128 v[176:179], v184 offset:1024
	ds_read_b128 v[180:183], v184 offset:2048
	ds_read_b128 v[184:187], v184 offset:3072
	s_add_u32 s34, s34, 0x80000
	s_addc_u32 s35, s35, 0
	s_mov_b32 m0, s53
	v_lshl_add_u64 v[226:227], s[34:35], 0, v[150:151]
	ds_read_b128 v[188:191], v175 offset:32768
	ds_read_b128 v[192:195], v175 offset:33792
	ds_read_b128 v[196:199], v175 offset:34816
	ds_read_b128 v[200:203], v175 offset:35840
	ds_read_b128 v[204:207], v175 offset:36864
	ds_read_b128 v[208:211], v175 offset:37888
	ds_read_b128 v[212:215], v175 offset:38912
	ds_read_b128 v[216:219], v175 offset:39936
	global_load_lds_dwordx4 v[226:227], off
	v_lshl_add_u64 v[226:227], s[34:35], 0, v[154:155]
	s_mov_b32 m0, s54
	s_nop 0
	global_load_lds_dwordx4 v[226:227], off
	s_waitcnt vmcnt(8)
	s_waitcnt lgkmcnt(0)
	s_barrier
	s_waitcnt lgkmcnt(0)
	v_mfma_f32_16x16x32_bf16 v[140:143], v[80:83], v[188:191], v[140:143]
	v_mfma_f32_16x16x32_bf16 v[136:139], v[88:91], v[188:191], v[136:139]
	v_mfma_f32_16x16x32_bf16 v[124:127], v[80:83], v[196:199], v[124:127]
	v_mfma_f32_16x16x32_bf16 v[120:123], v[88:91], v[196:199], v[120:123]
	v_mfma_f32_16x16x32_bf16 v[108:111], v[80:83], v[204:207], v[108:111]
	v_mfma_f32_16x16x32_bf16 v[104:107], v[88:91], v[204:207], v[104:107]
	v_mfma_f32_16x16x32_bf16 v[76:79], v[80:83], v[212:215], v[76:79]
	v_mfma_f32_16x16x32_bf16 v[72:75], v[88:91], v[212:215], v[72:75]
	v_mfma_f32_16x16x32_bf16 v[140:143], v[84:87], v[192:195], v[140:143]
	v_mfma_f32_16x16x32_bf16 v[136:139], v[92:95], v[192:195], v[136:139]
	v_mfma_f32_16x16x32_bf16 v[124:127], v[84:87], v[200:203], v[124:127]
	v_mfma_f32_16x16x32_bf16 v[120:123], v[92:95], v[200:203], v[120:123]
	v_mfma_f32_16x16x32_bf16 v[108:111], v[84:87], v[208:211], v[108:111]
	v_mfma_f32_16x16x32_bf16 v[104:107], v[92:95], v[208:211], v[104:107]
	v_mfma_f32_16x16x32_bf16 v[76:79], v[84:87], v[216:219], v[76:79]
	v_mfma_f32_16x16x32_bf16 v[72:75], v[92:95], v[216:219], v[72:75]
	v_mfma_f32_16x16x32_bf16 v[132:135], v[166:169], v[188:191], v[132:135]
	v_mfma_f32_16x16x32_bf16 v[128:131], v[180:183], v[188:191], v[128:131]
	v_mfma_f32_16x16x32_bf16 v[116:119], v[166:169], v[196:199], v[116:119]
	v_mfma_f32_16x16x32_bf16 v[112:115], v[180:183], v[196:199], v[112:115]
	v_mfma_f32_16x16x32_bf16 v[100:103], v[166:169], v[204:207], v[100:103]
	v_mfma_f32_16x16x32_bf16 v[96:99], v[180:183], v[204:207], v[96:99]
	v_mfma_f32_16x16x32_bf16 v[68:71], v[166:169], v[212:215], v[68:71]
	v_mfma_f32_16x16x32_bf16 v[64:67], v[180:183], v[212:215], v[64:67]
	v_mfma_f32_16x16x32_bf16 v[132:135], v[176:179], v[192:195], v[132:135]
	v_mfma_f32_16x16x32_bf16 v[128:131], v[184:187], v[192:195], v[128:131]
	v_mfma_f32_16x16x32_bf16 v[116:119], v[176:179], v[200:203], v[116:119]
	v_mfma_f32_16x16x32_bf16 v[112:115], v[184:187], v[200:203], v[112:115]
	v_mfma_f32_16x16x32_bf16 v[100:103], v[176:179], v[208:211], v[100:103]
	v_mfma_f32_16x16x32_bf16 v[96:99], v[184:187], v[208:211], v[96:99]
	v_mfma_f32_16x16x32_bf16 v[68:71], v[176:179], v[216:219], v[68:71]
	v_mfma_f32_16x16x32_bf16 v[64:67], v[184:187], v[216:219], v[64:67]
	s_barrier
	s_add_i32 s34, s73, s50
	v_lshl_add_u64 v[170:171], v[170:171], 0, s[12:13]
	s_mov_b32 m0, s34
	ds_read_b128 v[188:191], v175 offset:49152
	ds_read_b128 v[192:195], v175 offset:50176
	ds_read_b128 v[196:199], v175 offset:51200
	ds_read_b128 v[200:203], v175 offset:52224
	ds_read_b128 v[204:207], v175 offset:53248
	ds_read_b128 v[208:211], v175 offset:54272
	ds_read_b128 v[212:215], v175 offset:55296
	ds_read_b128 v[216:219], v175 offset:56320
	global_load_lds_dwordx4 v[170:171], off
	s_add_i32 m0, s34, 0x2000
	s_add_u32 s34, s42, 0x80080
	v_lshl_add_u64 v[170:171], v[220:221], 0, s[12:13]
	s_addc_u32 s35, s43, 0
	s_add_i32 s42, s74, s50
	global_load_lds_dwordx4 v[170:171], off
	v_lshl_add_u64 v[170:171], s[34:35], 0, v[152:153]
	s_mov_b32 m0, s42
	s_nop 0
	global_load_lds_dwordx4 v[170:171], off
	v_lshl_add_u64 v[170:171], s[34:35], 0, v[156:157]
	s_add_i32 m0, s42, 0x2000
	s_nop 0
	global_load_lds_dwordx4 v[170:171], off
	v_lshl_add_u64 v[170:171], v[222:223], 0, s[12:13]
	s_mov_b32 m0, s59
	s_nop 0
	global_load_lds_dwordx4 v[170:171], off
	v_lshl_add_u64 v[170:171], v[224:225], 0, s[12:13]
	s_mov_b32 m0, s60
	s_nop 0
	global_load_lds_dwordx4 v[170:171], off
	s_waitcnt vmcnt(8)
	s_waitcnt lgkmcnt(0)
	s_barrier
	s_waitcnt lgkmcnt(0)
	v_mfma_f32_16x16x32_bf16 v[60:63], v[80:83], v[188:191], v[60:63]
	v_mfma_f32_16x16x32_bf16 v[56:59], v[88:91], v[188:191], v[56:59]
	v_mfma_f32_16x16x32_bf16 v[44:47], v[80:83], v[196:199], v[44:47]
	v_mfma_f32_16x16x32_bf16 v[40:43], v[88:91], v[196:199], v[40:43]
	v_mfma_f32_16x16x32_bf16 v[28:31], v[80:83], v[204:207], v[28:31]
	v_mfma_f32_16x16x32_bf16 v[24:27], v[88:91], v[204:207], v[24:27]
	v_mfma_f32_16x16x32_bf16 v[12:15], v[80:83], v[212:215], v[12:15]
	v_mfma_f32_16x16x32_bf16 v[8:11], v[88:91], v[212:215], v[8:11]
	v_mfma_f32_16x16x32_bf16 v[60:63], v[84:87], v[192:195], v[60:63]
	v_mfma_f32_16x16x32_bf16 v[56:59], v[92:95], v[192:195], v[56:59]
	v_mfma_f32_16x16x32_bf16 v[44:47], v[84:87], v[200:203], v[44:47]
	v_mfma_f32_16x16x32_bf16 v[40:43], v[92:95], v[200:203], v[40:43]
	v_mfma_f32_16x16x32_bf16 v[28:31], v[84:87], v[208:211], v[28:31]
	v_mfma_f32_16x16x32_bf16 v[24:27], v[92:95], v[208:211], v[24:27]
	v_mfma_f32_16x16x32_bf16 v[12:15], v[84:87], v[216:219], v[12:15]
	v_mfma_f32_16x16x32_bf16 v[8:11], v[92:95], v[216:219], v[8:11]
	v_mfma_f32_16x16x32_bf16 v[52:55], v[166:169], v[188:191], v[52:55]
	v_mfma_f32_16x16x32_bf16 v[48:51], v[180:183], v[188:191], v[48:51]
	v_mfma_f32_16x16x32_bf16 v[36:39], v[166:169], v[196:199], v[36:39]
	v_mfma_f32_16x16x32_bf16 v[32:35], v[180:183], v[196:199], v[32:35]
	v_mfma_f32_16x16x32_bf16 v[20:23], v[166:169], v[204:207], v[20:23]
	v_mfma_f32_16x16x32_bf16 v[16:19], v[180:183], v[204:207], v[16:19]
	v_mfma_f32_16x16x32_bf16 v[4:7], v[166:169], v[212:215], v[4:7]
	v_mfma_f32_16x16x32_bf16 v[0:3], v[180:183], v[212:215], v[0:3]
	v_mfma_f32_16x16x32_bf16 v[52:55], v[176:179], v[192:195], v[52:55]
	v_mfma_f32_16x16x32_bf16 v[48:51], v[184:187], v[192:195], v[48:51]
	v_mfma_f32_16x16x32_bf16 v[36:39], v[176:179], v[200:203], v[36:39]
	v_mfma_f32_16x16x32_bf16 v[32:35], v[184:187], v[200:203], v[32:35]
	v_mfma_f32_16x16x32_bf16 v[20:23], v[176:179], v[208:211], v[20:23]
	v_mfma_f32_16x16x32_bf16 v[16:19], v[184:187], v[208:211], v[16:19]
	v_mfma_f32_16x16x32_bf16 v[4:7], v[176:179], v[216:219], v[4:7]
	v_mfma_f32_16x16x32_bf16 v[0:3], v[184:187], v[216:219], v[0:3]
	s_barrier
	s_add_i32 s72, s72, 2
	s_add_u32 s40, s40, 0x100
	s_addc_u32 s41, s41, 0
	s_add_u32 s66, s66, 0x100
	s_addc_u32 s67, s67, 0
	s_cmp_gt_u32 s72, 29
	s_cbranch_scc0 .LBB0_687
	s_and_b64 vcc, exec, s[14:15]
	s_cbranch_vccz .LBB0_690
	s_barrier

.LBB0_694:
	s_setprio 0
	s_cmp_gt_i32 s69, 5
	s_cselect_b64 s[0:1], -1, 0
	s_and_b64 s[4:5], s[4:5], s[0:1]
	s_andn2_b64 vcc, exec, s[4:5]
	s_cbranch_vccnz .LBB0_744
	s_waitcnt vmcnt(0)
	v_cmp_eq_u32_e32 vcc, 0, v146
	s_waitcnt vmcnt(0) lgkmcnt(0)
	s_barrier
	s_and_saveexec_b64 s[4:5], vcc
	s_cbranch_execz .LBB0_743
	s_add_i32 s3, 0, 0x23fc0
	v_mov_b32_e32 v0, s3
	s_waitcnt vmcnt(0) expcnt(0) lgkmcnt(0)
	ds_read_b32 v2, v0
	s_add_i32 s3, 0, 0x23fc4
	v_mov_b32_e32 v0, s3
	ds_read_b32 v0, v0
	s_waitcnt lgkmcnt(1)
	v_cmp_ne_u32_e32 vcc, 0, v2
	s_cbranch_vccnz .LBB0_711
	s_add_u32 s6, s30, 0x32200
	s_addc_u32 s7, s31, 0
	s_add_u32 s8, s30, 0x32400
	s_addc_u32 s9, s31, 0
	s_add_u32 s10, s30, 0x32500
	s_addc_u32 s11, s31, 0
	s_add_u32 s12, s30, 0x32600
	s_addc_u32 s13, s31, 0
	s_add_u32 s14, s30, 0x32700
	s_addc_u32 s15, s31, 0
	s_add_u32 s16, s30, 0x32800
	s_addc_u32 s17, s31, 0
	s_add_u32 s18, s30, 0x32900
	s_addc_u32 s19, s31, 0
	s_add_u32 s20, s30, 0x32a00
	s_addc_u32 s21, s31, 0
	s_add_u32 s22, s30, 0x32b00
	s_addc_u32 s23, s31, 0
	s_add_u32 s24, s30, 0x32c00
	s_addc_u32 s25, s31, 0
	s_add_u32 s26, s30, 0x32d00
	s_addc_u32 s27, s31, 0
	s_add_u32 s34, s30, 0x32e00
	s_addc_u32 s35, s31, 0
	s_add_u32 s36, s30, 0x32f00
	s_addc_u32 s37, s31, 0
	s_add_u32 s38, s30, 0x33000
	s_addc_u32 s39, s31, 0
	s_add_u32 s40, s30, 0x33100
	s_addc_u32 s41, s31, 0
	s_add_u32 s42, s30, 0x33200
	s_addc_u32 s43, s31, 0
	s_mul_i32 s3, s71, s85
	s_add_u32 s44, s30, 0x33300
	s_mul_i32 s3, s3, s70
	s_addc_u32 s45, s31, 0
	s_mov_b32 s33, 1
	v_mov_b32_e32 v16, 0
	s_branch .LBB0_699

.LBB0_801:
	s_cmp_lt_i32 s68, 7
	s_cselect_b64 s[4:5], -1, 0
	s_and_b64 s[4:5], s[4:5], s[0:1]
	s_andn2_b64 vcc, exec, s[4:5]
	s_cbranch_vccnz .LBB0_818
	v_readfirstlane_b32 s101, v145
	s_cmp_lt_u32 s101, 4
	s_cbranch_scc1 .Lprio_6
	s_setprio 1
.Lprio_6:
	s_cmpk_gt_i32 s2, 0xaff
	v_readfirstlane_b32 s1, v146
	s_cbranch_scc1 .LBB0_818
	v_lshrrev_b32_e32 v2, 1, v146
	v_and_b32_e32 v11, 24, v2
	v_lshrrev_b32_e32 v2, 5, v146
	v_and_b32_e32 v2, 4, v2
	v_bfe_u32 v3, v146, 2, 2
	s_add_u32 s3, s30, 0x1f000000
	v_lshlrev_b32_e32 v0, 4, v146
	v_and_b32_e32 v1, 32, v146
	v_bfe_u32 v10, v146, 2, 4
	v_or3_b32 v2, v2, v3, v11
	v_lshrrev_b32_e32 v3, 3, v146
	s_movk_i32 s0, 0x70
	s_addc_u32 s33, s31, 0
	v_bitop3_b32 v8, v0, v1, 48 bitop3:0x6c
	v_and_b32_e32 v9, 64, v146
	v_and_or_b32 v4, v3, s0, v10
	s_movk_i32 s0, 0x60
	v_add_u32_e32 v12, 0x2000, v0
	s_waitcnt lgkmcnt(0)
	s_add_u32 s36, s30, 0x4700000
	v_or_b32_e32 v1, v8, v9
	v_and_or_b32 v3, v3, s0, v2
	v_lshrrev_b32_e32 v0, 7, v12
	s_movk_i32 s0, 0xf0
	s_addc_u32 s37, s31, 0
	v_lshl_or_b32 v130, v3, 12, v1
	v_and_or_b32 v3, v0, s0, v10
	s_movk_i32 s0, 0xe0
	s_ashr_i32 s39, s2, 31
	v_and_or_b32 v0, v0, s0, v2
	s_lshr_b32 s0, s39, 29
	s_add_i32 s0, s2, s0
	s_lshr_b32 s10, s1, 6
	s_ashr_i32 s6, s0, 3
	s_and_b32 s0, s0, -8
	s_lshr_b32 s12, s1, 8
	s_lshl_b32 s38, s10, 10
	s_sub_i32 s0, s2, s0
	s_cmp_lt_i32 s0, 0
	s_movk_i32 s40, 0x161
	s_cselect_b32 s7, s40, 0x160
	s_mul_i32 s0, s0, s7
	s_add_i32 s0, s0, s6
	s_mul_hi_i32 s6, s0, 0x2e8ba2e9
	s_lshr_b32 s7, s6, 31
	s_ashr_i32 s6, s6, 6
	s_add_i32 s6, s6, s7
	s_lshl_b32 s7, s6, 3
	s_mulk_i32 s6, 0x160
	s_sub_i32 s6, s0, s6
	s_sext_i32_i16 s0, s6
	s_bfe_u32 s0, s0, 0x3001c
	s_add_i32 s8, s6, s0
	s_sext_i32_i16 s0, s8
	s_and_b32 s8, s8, 0xfff8
	s_sub_i32 s6, s6, s8
	s_sext_i32_i16 s6, s6
	s_lshr_b32 s0, s0, 3
	s_add_i32 s22, s7, s6
	s_ashr_i32 s23, s22, 31
	s_bfe_i64 s[8:9], s[0:1], 0x100000
	s_lshl_b64 s[6:7], s[22:23], 20
	s_lshl_b64 s[8:9], s[8:9], 20
	s_add_u32 s26, s36, s8
	s_addc_u32 s27, s37, s9
	s_add_i32 s23, s38, 0
	s_add_i32 m0, s23, 0x10000
	v_lshl_or_b32 v134, v0, 12, v1
	global_load_lds_dwordx4 v130, s[26:27]
	s_add_i32 m0, s23, 0x12000
	s_add_u32 s8, s26, 0x80000
	global_load_lds_dwordx4 v134, s[26:27]
	s_addc_u32 s9, s27, 0
	s_add_i32 m0, s23, 0x14000
	v_lshl_or_b32 v128, v4, 12, v1
	global_load_lds_dwordx4 v130, s[8:9]
	s_add_i32 m0, s23, 0x16000
	s_add_u32 s24, s3, s6
	s_addc_u32 s25, s33, s7
	s_add_i32 s41, s23, 0x2000
	global_load_lds_dwordx4 v134, s[8:9]
	s_mov_b32 m0, s23
	s_add_u32 s6, s24, 0x80000
	v_lshl_or_b32 v132, v3, 12, v1
	global_load_lds_dwordx4 v128, s[24:25]
	s_mov_b32 m0, s41
	s_addc_u32 s7, s25, 0
	s_add_i32 s42, s23, 0x4000
	global_load_lds_dwordx4 v132, s[24:25]
	s_mov_b32 m0, s42
	s_add_i32 s43, s23, 0x6000
	global_load_lds_dwordx4 v128, s[6:7]
	s_mov_b32 m0, s43
	v_mov_b32_e32 v131, 0
	global_load_lds_dwordx4 v132, s[6:7]
	v_mov_b32_e32 v135, v131
	v_mov_b32_e32 v129, v131
	v_mov_b32_e32 v133, v131
	s_cmp_eq_u32 s12, 1
	s_mov_b32 s44, 0
	v_lshl_add_u64 v[6:7], s[26:27], 0, v[130:131]
	v_lshl_add_u64 v[4:5], s[26:27], 0, v[134:135]
	v_lshl_add_u64 v[0:1], s[24:25], 0, v[128:129]
	s_cselect_b64 s[6:7], -1, 0
	s_cmp_lg_u32 s12, 1
	v_lshl_add_u64 v[2:3], s[24:25], 0, v[132:133]
	s_cbranch_scc1 .LBB0_805
	s_barrier

.LBB0_811:
	ds_read_b128 v[154:157], v151
	ds_read_b128 v[158:161], v151 offset:1024
	ds_read_b128 v[162:165], v151 offset:2048
	ds_read_b128 v[166:169], v151 offset:3072
	ds_read_b128 v[170:173], v152
	ds_read_b128 v[174:177], v152 offset:1024
	ds_read_b128 v[178:181], v152 offset:2048
	ds_read_b128 v[182:185], v152 offset:3072
	s_add_u32 s26, s24, 0xfff80080
	s_addc_u32 s27, s25, -1
	s_cmp_eq_u32 s61, 28
	s_cselect_b32 s35, s17, s27
	s_cselect_b32 s34, s57, s26
	s_cselect_b32 s27, s15, s60
	s_cselect_b32 s26, s58, s59
	v_lshl_add_u64 v[218:219], s[24:25], 0, v[136:137]
	s_add_i32 m0, s23, 0xc000
	ds_read_b128 v[186:189], v153
	ds_read_b128 v[190:193], v153 offset:1024
	ds_read_b128 v[194:197], v153 offset:2048
	ds_read_b128 v[198:201], v153 offset:3072
	ds_read_b128 v[202:205], v153 offset:4096
	ds_read_b128 v[206:209], v153 offset:5120
	ds_read_b128 v[210:213], v153 offset:6144
	ds_read_b128 v[214:217], v153 offset:7168
	global_load_lds_dwordx4 v[218:219], off
	v_lshl_add_u64 v[218:219], s[24:25], 0, v[138:139]
	s_add_i32 m0, s23, 0xe000
	s_nop 0
	global_load_lds_dwordx4 v[218:219], off
	s_waitcnt vmcnt(8)
	s_waitcnt lgkmcnt(0)
	s_barrier
	s_waitcnt lgkmcnt(0)
	v_mfma_f32_16x16x32_bf16 v[124:127], v[154:157], v[186:189], v[124:127]
	v_mfma_f32_16x16x32_bf16 v[120:123], v[162:165], v[186:189], v[120:123]
	v_mfma_f32_16x16x32_bf16 v[108:111], v[154:157], v[194:197], v[108:111]
	v_mfma_f32_16x16x32_bf16 v[104:107], v[162:165], v[194:197], v[104:107]
	v_mfma_f32_16x16x32_bf16 v[92:95], v[154:157], v[202:205], v[92:95]
	v_mfma_f32_16x16x32_bf16 v[88:91], v[162:165], v[202:205], v[88:91]
	v_mfma_f32_16x16x32_bf16 v[76:79], v[154:157], v[210:213], v[76:79]
	v_mfma_f32_16x16x32_bf16 v[72:75], v[162:165], v[210:213], v[72:75]
	v_mfma_f32_16x16x32_bf16 v[124:127], v[158:161], v[190:193], v[124:127]
	v_mfma_f32_16x16x32_bf16 v[120:123], v[166:169], v[190:193], v[120:123]
	v_mfma_f32_16x16x32_bf16 v[108:111], v[158:161], v[198:201], v[108:111]
	v_mfma_f32_16x16x32_bf16 v[104:107], v[166:169], v[198:201], v[104:107]
	v_mfma_f32_16x16x32_bf16 v[92:95], v[158:161], v[206:209], v[92:95]
	v_mfma_f32_16x16x32_bf16 v[88:91], v[166:169], v[206:209], v[88:91]
	v_mfma_f32_16x16x32_bf16 v[76:79], v[158:161], v[214:217], v[76:79]
	v_mfma_f32_16x16x32_bf16 v[72:75], v[166:169], v[214:217], v[72:75]
	v_mfma_f32_16x16x32_bf16 v[116:119], v[170:173], v[186:189], v[116:119]
	v_mfma_f32_16x16x32_bf16 v[112:115], v[178:181], v[186:189], v[112:115]
	v_mfma_f32_16x16x32_bf16 v[100:103], v[170:173], v[194:197], v[100:103]
	v_mfma_f32_16x16x32_bf16 v[96:99], v[178:181], v[194:197], v[96:99]
	v_mfma_f32_16x16x32_bf16 v[84:87], v[170:173], v[202:205], v[84:87]
	v_mfma_f32_16x16x32_bf16 v[80:83], v[178:181], v[202:205], v[80:83]
	v_mfma_f32_16x16x32_bf16 v[68:71], v[170:173], v[210:213], v[68:71]
	v_mfma_f32_16x16x32_bf16 v[64:67], v[178:181], v[210:213], v[64:67]
	v_mfma_f32_16x16x32_bf16 v[116:119], v[174:177], v[190:193], v[116:119]
	v_mfma_f32_16x16x32_bf16 v[112:115], v[182:185], v[190:193], v[112:115]
	v_mfma_f32_16x16x32_bf16 v[100:103], v[174:177], v[198:201], v[100:103]
	v_mfma_f32_16x16x32_bf16 v[96:99], v[182:185], v[198:201], v[96:99]
	v_mfma_f32_16x16x32_bf16 v[84:87], v[174:177], v[206:209], v[84:87]
	v_mfma_f32_16x16x32_bf16 v[80:83], v[182:185], v[206:209], v[80:83]
	v_mfma_f32_16x16x32_bf16 v[68:71], v[174:177], v[214:217], v[68:71]
	v_mfma_f32_16x16x32_bf16 v[64:67], v[182:185], v[214:217], v[64:67]
	s_barrier
	s_add_i32 s62, s53, s38
	v_lshl_add_u64 v[218:219], s[26:27], 0, v[130:131]
	s_mov_b32 m0, s62
	ds_read_b128 v[186:189], v153 offset:16384
	ds_read_b128 v[190:193], v153 offset:17408
	ds_read_b128 v[194:197], v153 offset:18432
	ds_read_b128 v[198:201], v153 offset:19456
	ds_read_b128 v[202:205], v153 offset:20480
	ds_read_b128 v[206:209], v153 offset:21504
	ds_read_b128 v[210:213], v153 offset:22528
	ds_read_b128 v[214:217], v153 offset:23552
	global_load_lds_dwordx4 v[218:219], off
	s_add_i32 m0, s62, 0x2000
	s_add_u32 s62, s26, 0x80000
	v_lshl_add_u64 v[220:221], s[26:27], 0, v[134:135]
	s_addc_u32 s63, s27, 0
	s_add_i32 s64, s54, s38
	global_load_lds_dwordx4 v[220:221], off
	v_lshl_add_u64 v[222:223], s[62:63], 0, v[130:131]
	s_mov_b32 m0, s64
	v_lshl_add_u64 v[224:225], s[34:35], 0, v[132:133]
	global_load_lds_dwordx4 v[222:223], off
	v_lshl_add_u64 v[222:223], s[62:63], 0, v[134:135]
	s_add_i32 m0, s64, 0x2000
	s_nop 0
	global_load_lds_dwordx4 v[222:223], off
	v_lshl_add_u64 v[222:223], s[34:35], 0, v[128:129]
	s_mov_b32 m0, s23
	s_nop 0
	global_load_lds_dwordx4 v[222:223], off
	s_mov_b32 m0, s41
	s_nop 0
	global_load_lds_dwordx4 v[224:225], off
	s_waitcnt vmcnt(8)
	s_waitcnt lgkmcnt(0)
	s_barrier
	s_waitcnt lgkmcnt(0)
	v_mfma_f32_16x16x32_bf16 v[60:63], v[154:157], v[186:189], v[60:63]
	v_mfma_f32_16x16x32_bf16 v[56:59], v[162:165], v[186:189], v[56:59]
	v_mfma_f32_16x16x32_bf16 v[44:47], v[154:157], v[194:197], v[44:47]
	v_mfma_f32_16x16x32_bf16 v[40:43], v[162:165], v[194:197], v[40:43]
	v_mfma_f32_16x16x32_bf16 v[28:31], v[154:157], v[202:205], v[28:31]
	v_mfma_f32_16x16x32_bf16 v[24:27], v[162:165], v[202:205], v[24:27]
	v_mfma_f32_16x16x32_bf16 v[12:15], v[154:157], v[210:213], v[12:15]
	v_mfma_f32_16x16x32_bf16 v[8:11], v[162:165], v[210:213], v[8:11]
	v_mfma_f32_16x16x32_bf16 v[60:63], v[158:161], v[190:193], v[60:63]
	v_mfma_f32_16x16x32_bf16 v[56:59], v[166:169], v[190:193], v[56:59]
	v_mfma_f32_16x16x32_bf16 v[44:47], v[158:161], v[198:201], v[44:47]
	v_mfma_f32_16x16x32_bf16 v[40:43], v[166:169], v[198:201], v[40:43]
	v_mfma_f32_16x16x32_bf16 v[28:31], v[158:161], v[206:209], v[28:31]
	v_mfma_f32_16x16x32_bf16 v[24:27], v[166:169], v[206:209], v[24:27]
	v_mfma_f32_16x16x32_bf16 v[12:15], v[158:161], v[214:217], v[12:15]
	v_mfma_f32_16x16x32_bf16 v[8:11], v[166:169], v[214:217], v[8:11]
	v_mfma_f32_16x16x32_bf16 v[52:55], v[170:173], v[186:189], v[52:55]
	v_mfma_f32_16x16x32_bf16 v[48:51], v[178:181], v[186:189], v[48:51]
	v_mfma_f32_16x16x32_bf16 v[36:39], v[170:173], v[194:197], v[36:39]
	v_mfma_f32_16x16x32_bf16 v[32:35], v[178:181], v[194:197], v[32:35]
	v_mfma_f32_16x16x32_bf16 v[20:23], v[170:173], v[202:205], v[20:23]
	v_mfma_f32_16x16x32_bf16 v[16:19], v[178:181], v[202:205], v[16:19]
	v_mfma_f32_16x16x32_bf16 v[4:7], v[170:173], v[210:213], v[4:7]
	v_mfma_f32_16x16x32_bf16 v[0:3], v[178:181], v[210:213], v[0:3]
	v_mfma_f32_16x16x32_bf16 v[52:55], v[174:177], v[190:193], v[52:55]
	v_mfma_f32_16x16x32_bf16 v[48:51], v[182:185], v[190:193], v[48:51]
	v_mfma_f32_16x16x32_bf16 v[36:39], v[174:177], v[198:201], v[36:39]
	v_mfma_f32_16x16x32_bf16 v[32:35], v[182:185], v[198:201], v[32:35]
	v_mfma_f32_16x16x32_bf16 v[20:23], v[174:177], v[206:209], v[20:23]
	v_mfma_f32_16x16x32_bf16 v[16:19], v[182:185], v[206:209], v[16:19]
	v_mfma_f32_16x16x32_bf16 v[4:7], v[174:177], v[214:217], v[4:7]
	v_mfma_f32_16x16x32_bf16 v[0:3], v[182:185], v[214:217], v[0:3]
	s_barrier
	s_add_i32 s62, 0, 0x18000
	s_add_i32 s63, 0, 0x1c000
	v_add_u32_e32 v166, s62, v149
	v_add_u32_e32 v182, s63, v149
	ds_read_b128 v[154:157], v166
	ds_read_b128 v[158:161], v166 offset:1024
	ds_read_b128 v[162:165], v166 offset:2048
	ds_read_b128 v[166:169], v166 offset:3072
	ds_read_b128 v[170:173], v182
	ds_read_b128 v[174:177], v182 offset:1024
	ds_read_b128 v[178:181], v182 offset:2048
	ds_read_b128 v[182:185], v182 offset:3072
	s_add_u32 s34, s34, 0x80000
	s_addc_u32 s35, s35, 0
	s_mov_b32 m0, s42
	v_lshl_add_u64 v[226:227], s[34:35], 0, v[128:129]
	ds_read_b128 v[186:189], v153 offset:32768
	ds_read_b128 v[190:193], v153 offset:33792
	ds_read_b128 v[194:197], v153 offset:34816
	ds_read_b128 v[198:201], v153 offset:35840
	ds_read_b128 v[202:205], v153 offset:36864
	ds_read_b128 v[206:209], v153 offset:37888
	ds_read_b128 v[210:213], v153 offset:38912
	ds_read_b128 v[214:217], v153 offset:39936
	global_load_lds_dwordx4 v[226:227], off
	v_lshl_add_u64 v[226:227], s[34:35], 0, v[132:133]
	s_mov_b32 m0, s43
	s_nop 0
	global_load_lds_dwordx4 v[226:227], off
	s_waitcnt vmcnt(8)
	s_waitcnt lgkmcnt(0)
	s_barrier
	s_waitcnt lgkmcnt(0)
	v_mfma_f32_16x16x32_bf16 v[124:127], v[154:157], v[186:189], v[124:127]
	v_mfma_f32_16x16x32_bf16 v[120:123], v[162:165], v[186:189], v[120:123]
	v_mfma_f32_16x16x32_bf16 v[108:111], v[154:157], v[194:197], v[108:111]
	v_mfma_f32_16x16x32_bf16 v[104:107], v[162:165], v[194:197], v[104:107]
	v_mfma_f32_16x16x32_bf16 v[92:95], v[154:157], v[202:205], v[92:95]
	v_mfma_f32_16x16x32_bf16 v[88:91], v[162:165], v[202:205], v[88:91]
	v_mfma_f32_16x16x32_bf16 v[76:79], v[154:157], v[210:213], v[76:79]
	v_mfma_f32_16x16x32_bf16 v[72:75], v[162:165], v[210:213], v[72:75]
	v_mfma_f32_16x16x32_bf16 v[124:127], v[158:161], v[190:193], v[124:127]
	v_mfma_f32_16x16x32_bf16 v[120:123], v[166:169], v[190:193], v[120:123]
	v_mfma_f32_16x16x32_bf16 v[108:111], v[158:161], v[198:201], v[108:111]
	v_mfma_f32_16x16x32_bf16 v[104:107], v[166:169], v[198:201], v[104:107]
	v_mfma_f32_16x16x32_bf16 v[92:95], v[158:161], v[206:209], v[92:95]
	v_mfma_f32_16x16x32_bf16 v[88:91], v[166:169], v[206:209], v[88:91]
	v_mfma_f32_16x16x32_bf16 v[76:79], v[158:161], v[214:217], v[76:79]
	v_mfma_f32_16x16x32_bf16 v[72:75], v[166:169], v[214:217], v[72:75]
	v_mfma_f32_16x16x32_bf16 v[116:119], v[170:173], v[186:189], v[116:119]
	v_mfma_f32_16x16x32_bf16 v[112:115], v[178:181], v[186:189], v[112:115]
	v_mfma_f32_16x16x32_bf16 v[100:103], v[170:173], v[194:197], v[100:103]
	v_mfma_f32_16x16x32_bf16 v[96:99], v[178:181], v[194:197], v[96:99]
	v_mfma_f32_16x16x32_bf16 v[84:87], v[170:173], v[202:205], v[84:87]
	v_mfma_f32_16x16x32_bf16 v[80:83], v[178:181], v[202:205], v[80:83]
	v_mfma_f32_16x16x32_bf16 v[68:71], v[170:173], v[210:213], v[68:71]
	v_mfma_f32_16x16x32_bf16 v[64:67], v[178:181], v[210:213], v[64:67]
	v_mfma_f32_16x16x32_bf16 v[116:119], v[174:177], v[190:193], v[116:119]
	v_mfma_f32_16x16x32_bf16 v[112:115], v[182:185], v[190:193], v[112:115]
	v_mfma_f32_16x16x32_bf16 v[100:103], v[174:177], v[198:201], v[100:103]
	v_mfma_f32_16x16x32_bf16 v[96:99], v[182:185], v[198:201], v[96:99]
	v_mfma_f32_16x16x32_bf16 v[84:87], v[174:177], v[206:209], v[84:87]
	v_mfma_f32_16x16x32_bf16 v[80:83], v[182:185], v[206:209], v[80:83]
	v_mfma_f32_16x16x32_bf16 v[68:71], v[174:177], v[214:217], v[68:71]
	v_mfma_f32_16x16x32_bf16 v[64:67], v[182:185], v[214:217], v[64:67]
	s_barrier
	s_add_i32 s34, s62, s38
	v_lshl_add_u64 v[218:219], v[218:219], 0, s[10:11]
	s_mov_b32 m0, s34
	ds_read_b128 v[186:189], v153 offset:49152
	ds_read_b128 v[190:193], v153 offset:50176
	ds_read_b128 v[194:197], v153 offset:51200
	ds_read_b128 v[198:201], v153 offset:52224
	ds_read_b128 v[202:205], v153 offset:53248
	ds_read_b128 v[206:209], v153 offset:54272
	ds_read_b128 v[210:213], v153 offset:55296
	ds_read_b128 v[214:217], v153 offset:56320
	global_load_lds_dwordx4 v[218:219], off
	s_add_i32 m0, s34, 0x2000
	s_add_u32 s26, s26, 0x80080
	v_lshl_add_u64 v[218:219], v[220:221], 0, s[10:11]
	s_addc_u32 s27, s27, 0
	s_add_i32 s34, s63, s38
	global_load_lds_dwordx4 v[218:219], off
	v_lshl_add_u64 v[218:219], s[26:27], 0, v[130:131]
	s_mov_b32 m0, s34
	s_nop 0
	global_load_lds_dwordx4 v[218:219], off
	v_lshl_add_u64 v[218:219], s[26:27], 0, v[134:135]
	s_add_i32 m0, s34, 0x2000
	s_nop 0
	global_load_lds_dwordx4 v[218:219], off
	v_lshl_add_u64 v[218:219], v[222:223], 0, s[10:11]
	s_mov_b32 m0, s50
	s_nop 0
	global_load_lds_dwordx4 v[218:219], off
	v_lshl_add_u64 v[218:219], v[224:225], 0, s[10:11]
	s_mov_b32 m0, s51
	s_nop 0
	global_load_lds_dwordx4 v[218:219], off
	s_waitcnt vmcnt(8)
	s_waitcnt lgkmcnt(0)
	s_barrier
	s_waitcnt lgkmcnt(0)
	v_mfma_f32_16x16x32_bf16 v[60:63], v[154:157], v[186:189], v[60:63]
	v_mfma_f32_16x16x32_bf16 v[56:59], v[162:165], v[186:189], v[56:59]
	v_mfma_f32_16x16x32_bf16 v[44:47], v[154:157], v[194:197], v[44:47]
	v_mfma_f32_16x16x32_bf16 v[40:43], v[162:165], v[194:197], v[40:43]
	v_mfma_f32_16x16x32_bf16 v[28:31], v[154:157], v[202:205], v[28:31]
	v_mfma_f32_16x16x32_bf16 v[24:27], v[162:165], v[202:205], v[24:27]
	v_mfma_f32_16x16x32_bf16 v[12:15], v[154:157], v[210:213], v[12:15]
	v_mfma_f32_16x16x32_bf16 v[8:11], v[162:165], v[210:213], v[8:11]
	v_mfma_f32_16x16x32_bf16 v[60:63], v[158:161], v[190:193], v[60:63]
	v_mfma_f32_16x16x32_bf16 v[56:59], v[166:169], v[190:193], v[56:59]
	v_mfma_f32_16x16x32_bf16 v[44:47], v[158:161], v[198:201], v[44:47]
	v_mfma_f32_16x16x32_bf16 v[40:43], v[166:169], v[198:201], v[40:43]
	v_mfma_f32_16x16x32_bf16 v[28:31], v[158:161], v[206:209], v[28:31]
	v_mfma_f32_16x16x32_bf16 v[24:27], v[166:169], v[206:209], v[24:27]
	v_mfma_f32_16x16x32_bf16 v[12:15], v[158:161], v[214:217], v[12:15]
	v_mfma_f32_16x16x32_bf16 v[8:11], v[166:169], v[214:217], v[8:11]
	v_mfma_f32_16x16x32_bf16 v[52:55], v[170:173], v[186:189], v[52:55]
	v_mfma_f32_16x16x32_bf16 v[48:51], v[178:181], v[186:189], v[48:51]
	v_mfma_f32_16x16x32_bf16 v[36:39], v[170:173], v[194:197], v[36:39]
	v_mfma_f32_16x16x32_bf16 v[32:35], v[178:181], v[194:197], v[32:35]
	v_mfma_f32_16x16x32_bf16 v[20:23], v[170:173], v[202:205], v[20:23]
	v_mfma_f32_16x16x32_bf16 v[16:19], v[178:181], v[202:205], v[16:19]
	v_mfma_f32_16x16x32_bf16 v[4:7], v[170:173], v[210:213], v[4:7]
	v_mfma_f32_16x16x32_bf16 v[0:3], v[178:181], v[210:213], v[0:3]
	v_mfma_f32_16x16x32_bf16 v[52:55], v[174:177], v[190:193], v[52:55]
	v_mfma_f32_16x16x32_bf16 v[48:51], v[182:185], v[190:193], v[48:51]
	v_mfma_f32_16x16x32_bf16 v[36:39], v[174:177], v[198:201], v[36:39]
	v_mfma_f32_16x16x32_bf16 v[32:35], v[182:185], v[198:201], v[32:35]
	v_mfma_f32_16x16x32_bf16 v[20:23], v[174:177], v[206:209], v[20:23]
	v_mfma_f32_16x16x32_bf16 v[16:19], v[182:185], v[206:209], v[16:19]
	v_mfma_f32_16x16x32_bf16 v[4:7], v[174:177], v[214:217], v[4:7]
	v_mfma_f32_16x16x32_bf16 v[0:3], v[182:185], v[214:217], v[0:3]
	s_barrier
	s_add_i32 s61, s61, 2
	s_add_u32 s24, s24, 0x100
	s_addc_u32 s25, s25, 0
	s_add_u32 s59, s59, 0x100
	s_addc_u32 s60, s60, 0
	s_cmp_gt_u32 s61, 29
	s_cbranch_scc0 .LBB0_811
	s_and_b64 vcc, exec, s[12:13]
	s_cbranch_vccz .LBB0_814
	s_barrier

.LBB0_818:
	s_setprio 0
	s_cmp_gt_i32 s69, 7
	s_cselect_b64 s[0:1], -1, 0
	s_and_b64 s[4:5], s[4:5], s[0:1]
	s_andn2_b64 vcc, exec, s[4:5]
	s_cbranch_vccnz .LBB0_868
	s_waitcnt vmcnt(0)
	v_cmp_eq_u32_e32 vcc, 0, v146
	s_waitcnt vmcnt(0) lgkmcnt(0)
	s_barrier
	s_and_saveexec_b64 s[4:5], vcc
	s_cbranch_execz .LBB0_867
	s_add_i32 s3, 0, 0x23fc0
	v_mov_b32_e32 v0, s3
	s_waitcnt vmcnt(0) expcnt(0) lgkmcnt(0)
	ds_read_b32 v2, v0
	s_add_i32 s3, 0, 0x23fc4
	v_mov_b32_e32 v0, s3
	ds_read_b32 v0, v0
	s_waitcnt lgkmcnt(1)
	v_cmp_ne_u32_e32 vcc, 0, v2
	s_cbranch_vccnz .LBB0_835
	s_add_u32 s6, s30, 0x32200
	s_addc_u32 s7, s31, 0
	s_add_u32 s8, s30, 0x32400
	s_addc_u32 s9, s31, 0
	s_add_u32 s10, s30, 0x32500
	s_addc_u32 s11, s31, 0
	s_add_u32 s12, s30, 0x32600
	s_addc_u32 s13, s31, 0
	s_add_u32 s14, s30, 0x32700
	s_addc_u32 s15, s31, 0
	s_add_u32 s16, s30, 0x32800
	s_addc_u32 s17, s31, 0
	s_add_u32 s18, s30, 0x32900
	s_addc_u32 s19, s31, 0
	s_add_u32 s20, s30, 0x32a00
	s_addc_u32 s21, s31, 0
	s_add_u32 s22, s30, 0x32b00
	s_addc_u32 s23, s31, 0
	s_add_u32 s24, s30, 0x32c00
	s_addc_u32 s25, s31, 0
	s_add_u32 s26, s30, 0x32d00
	s_addc_u32 s27, s31, 0
	s_add_u32 s34, s30, 0x32e00
	s_addc_u32 s35, s31, 0
	s_add_u32 s36, s30, 0x32f00
	s_addc_u32 s37, s31, 0
	s_add_u32 s38, s30, 0x33000
	s_addc_u32 s39, s31, 0
	s_add_u32 s40, s30, 0x33100
	s_addc_u32 s41, s31, 0
	s_add_u32 s42, s30, 0x33200
	s_addc_u32 s43, s31, 0
	s_mul_i32 s3, s71, s85
	s_add_u32 s44, s30, 0x33300
	s_mul_i32 s3, s3, s70
	s_addc_u32 s45, s31, 0
	s_mov_b32 s33, 1
	v_mov_b32_e32 v16, 0
	s_branch .LBB0_823

.LBB0_868:
	s_cmp_lt_i32 s68, 8
	s_cselect_b64 s[4:5], -1, 0
	s_and_b64 s[6:7], s[4:5], s[0:1]
	s_andn2_b64 vcc, exec, s[6:7]
	s_cbranch_vccnz .LBB0_893
	v_readfirstlane_b32 s101, v145
	s_cmp_lt_u32 s101, 4
	s_cbranch_scc1 .Lprio_7
	s_setprio 1
.Lprio_7:
	s_cmpk_gt_i32 s2, 0x1ff
	v_readfirstlane_b32 s0, v146
	s_cbranch_scc1 .LBB0_893
	s_add_u32 s3, s30, 0x23000000
	s_addc_u32 s21, s31, 0
	v_lshrrev_b32_e32 v3, 1, v146
	s_waitcnt lgkmcnt(0)
	s_add_u32 s36, s30, 0x9f00000
	v_and_b32_e32 v10, 24, v3
	v_lshrrev_b32_e32 v3, 5, v146
	s_addc_u32 s37, s31, 0
	v_and_b32_e32 v3, 4, v3
	v_bfe_u32 v4, v146, 2, 2
	s_ashr_i32 s39, s2, 31
	v_lshlrev_b32_e32 v0, 4, v146
	v_and_b32_e32 v1, 32, v146
	v_bfe_u32 v2, v146, 2, 4
	v_or3_b32 v3, v3, v4, v10
	v_lshrrev_b32_e32 v4, 3, v146
	s_movk_i32 s1, 0x70
	s_lshr_b32 s4, s39, 29
	v_bitop3_b32 v8, v0, v1, 48 bitop3:0x6c
	v_and_or_b32 v5, v4, s1, v2
	s_movk_i32 s1, 0x60
	v_add_u32_e32 v0, 0x2000, v0
	s_add_i32 s4, s2, s4
	v_and_or_b32 v4, v4, s1, v3
	v_lshrrev_b32_e32 v0, 7, v0
	s_movk_i32 s1, 0xf0
	s_and_b32 s8, s4, -8
	v_and_or_b32 v2, v0, s1, v2
	s_movk_i32 s1, 0xe0
	s_lshr_b32 s5, s0, 6
	s_sub_i32 s8, s2, s8
	v_and_or_b32 v0, v0, s1, v3
	s_lshr_b32 s1, s0, 8
	s_lshl_b32 s38, s5, 10
	s_lshl_b32 s10, s8, 6
	s_ashr_i32 s4, s4, 3
	s_mul_i32 s9, s8, 0x41
	s_cmp_lt_i32 s8, 0
	s_cselect_b32 s8, s9, s10
	s_add_i32 s4, s8, s4
	s_ashr_i32 s8, s4, 31
	s_lshr_b32 s8, s8, 26
	s_add_i32 s8, s4, s8
	s_ashr_i32 s9, s8, 6
	s_andn2_b32 s8, s8, 63
	s_sub_i32 s8, s4, s8
	s_bfe_i32 s4, s8, 0x80000
	s_bfe_u32 s4, s4, 0x3000c
	s_add_i32 s10, s8, s4
	s_bfe_i32 s4, s10, 0x80000
	s_and_b32 s10, s10, 0xf8
	s_sub_i32 s8, s8, s10
	s_lshl_b32 s9, s9, 3
	s_sext_i32_i16 s11, s4
	s_sext_i32_i8 s8, s8
	v_and_b32_e32 v9, 64, v146
	s_add_i32 s33, s9, s8
	s_ashr_i32 s8, s11, 3
	v_or_b32_e32 v1, v8, v9
	s_lshr_b32 s4, s11, 3
	s_mul_hi_i32 s9, s8, 0x2c0000
	s_mul_i32 s8, s8, 0x2c0000
	v_lshrrev_b32_e32 v1, 1, v1
	v_mul_u32_u24_e32 v4, 0x1600, v4
	s_add_u32 s26, s36, s8
	v_or_b32_e32 v4, v4, v1
	s_addc_u32 s27, s37, s9
	s_add_i32 s40, s38, 0
	v_lshlrev_b32_e32 v152, 1, v4
	v_mul_u32_u24_e32 v0, 0x1600, v0
	s_add_i32 m0, s40, 0x10000
	v_or_b32_e32 v0, v0, v1
	global_load_lds_dwordx4 v152, s[26:27]
	s_add_i32 m0, s40, 0x12000
	v_lshlrev_b32_e32 v156, 1, v0
	s_add_u32 s8, s26, 0x160000
	global_load_lds_dwordx4 v156, s[26:27]
	s_addc_u32 s9, s27, 0
	s_add_i32 m0, s40, 0x14000
	s_mul_i32 s12, s33, 0x2c0000
	global_load_lds_dwordx4 v152, s[8:9]
	s_add_i32 m0, s40, 0x16000
	v_mul_u32_u24_e32 v11, 0x1600, v5
	s_mul_hi_i32 s10, s33, 0x2c0000
	s_add_u32 s24, s3, s12
	v_or_b32_e32 v5, v1, v11
	v_mul_u32_u24_e32 v12, 0x1600, v2
	s_addc_u32 s25, s21, s10
	s_add_i32 s41, s40, 0x2000
	v_lshlrev_b32_e32 v150, 1, v5
	v_or_b32_e32 v2, v12, v1
	global_load_lds_dwordx4 v156, s[8:9]
	s_mov_b32 m0, s40
	s_add_u32 s8, s24, 0x160000
	v_lshlrev_b32_e32 v154, 1, v2
	global_load_lds_dwordx4 v150, s[24:25]
	s_mov_b32 m0, s41
	s_addc_u32 s9, s25, 0
	s_add_i32 s42, s40, 0x4000
	global_load_lds_dwordx4 v154, s[24:25]
	s_mov_b32 m0, s42
	s_add_i32 s43, s40, 0x6000
	global_load_lds_dwordx4 v150, s[8:9]
	s_mov_b32 m0, s43
	v_mov_b32_e32 v153, 0
	global_load_lds_dwordx4 v154, s[8:9]
	v_mov_b32_e32 v157, v153
	v_mov_b32_e32 v151, v153
	v_mov_b32_e32 v155, v153
	s_cmp_eq_u32 s1, 1
	s_mov_b32 s44, 0
	v_lshl_add_u64 v[6:7], s[26:27], 0, v[152:153]
	v_lshl_add_u64 v[4:5], s[26:27], 0, v[156:157]
	v_lshl_add_u64 v[0:1], s[24:25], 0, v[150:151]
	s_cselect_b64 s[8:9], -1, 0
	s_cmp_lg_u32 s1, 1
	v_lshl_add_u64 v[2:3], s[24:25], 0, v[154:155]
	s_cbranch_scc1 .LBB0_872
	s_barrier

.LBB0_886:
	ds_read_b128 v[128:131], v195
	ds_read_b128 v[132:135], v195 offset:1024
	ds_read_b128 v[136:139], v195 offset:2048
	ds_read_b128 v[140:143], v195 offset:3072
	ds_read_b128 v[166:169], v196
	ds_read_b128 v[170:173], v196 offset:1024
	ds_read_b128 v[174:177], v196 offset:2048
	ds_read_b128 v[178:181], v196 offset:3072
	s_add_u32 s26, s24, 0xffea0080
	s_addc_u32 s27, s25, -1
	s_cmpk_eq_i32 s62, 0x54
	s_cselect_b32 s35, s5, s27
	s_cselect_b32 s34, s4, s26
	s_cselect_b32 s27, s23, s61
	s_cselect_b32 s26, s22, s60
	v_lshl_add_u64 v[218:219], s[24:25], 0, v[158:159]
	s_add_i32 m0, s40, 0xc000
	ds_read_b128 v[182:185], v197
	ds_read_b128 v[186:189], v197 offset:1024
	ds_read_b128 v[190:193], v197 offset:2048
	ds_read_b128 v[198:201], v197 offset:3072
	ds_read_b128 v[202:205], v197 offset:4096
	ds_read_b128 v[206:209], v197 offset:5120
	ds_read_b128 v[210:213], v197 offset:6144
	ds_read_b128 v[214:217], v197 offset:7168
	global_load_lds_dwordx4 v[218:219], off
	v_lshl_add_u64 v[218:219], s[24:25], 0, v[160:161]
	s_add_i32 m0, s40, 0xe000
	s_nop 0
	global_load_lds_dwordx4 v[218:219], off
	s_waitcnt vmcnt(8)
	s_waitcnt lgkmcnt(0)
	s_barrier
	s_waitcnt lgkmcnt(0)
	v_mfma_f32_16x16x32_bf16 v[124:127], v[128:131], v[182:185], v[124:127]
	v_mfma_f32_16x16x32_bf16 v[120:123], v[136:139], v[182:185], v[120:123]
	v_mfma_f32_16x16x32_bf16 v[116:119], v[128:131], v[190:193], v[116:119]
	v_mfma_f32_16x16x32_bf16 v[112:115], v[136:139], v[190:193], v[112:115]
	v_mfma_f32_16x16x32_bf16 v[108:111], v[128:131], v[202:205], v[108:111]
	v_mfma_f32_16x16x32_bf16 v[104:107], v[136:139], v[202:205], v[104:107]
	v_mfma_f32_16x16x32_bf16 v[100:103], v[128:131], v[210:213], v[100:103]
	v_mfma_f32_16x16x32_bf16 v[96:99], v[136:139], v[210:213], v[96:99]
	v_mfma_f32_16x16x32_bf16 v[124:127], v[132:135], v[186:189], v[124:127]
	v_mfma_f32_16x16x32_bf16 v[120:123], v[140:143], v[186:189], v[120:123]
	v_mfma_f32_16x16x32_bf16 v[116:119], v[132:135], v[198:201], v[116:119]
	v_mfma_f32_16x16x32_bf16 v[112:115], v[140:143], v[198:201], v[112:115]
	v_mfma_f32_16x16x32_bf16 v[108:111], v[132:135], v[206:209], v[108:111]
	v_mfma_f32_16x16x32_bf16 v[104:107], v[140:143], v[206:209], v[104:107]
	v_mfma_f32_16x16x32_bf16 v[100:103], v[132:135], v[214:217], v[100:103]
	v_mfma_f32_16x16x32_bf16 v[96:99], v[140:143], v[214:217], v[96:99]
	v_mfma_f32_16x16x32_bf16 v[60:63], v[166:169], v[182:185], v[60:63]
	v_mfma_f32_16x16x32_bf16 v[56:59], v[174:177], v[182:185], v[56:59]
	v_mfma_f32_16x16x32_bf16 v[52:55], v[166:169], v[190:193], v[52:55]
	v_mfma_f32_16x16x32_bf16 v[48:51], v[174:177], v[190:193], v[48:51]
	v_mfma_f32_16x16x32_bf16 v[44:47], v[166:169], v[202:205], v[44:47]
	v_mfma_f32_16x16x32_bf16 v[40:43], v[174:177], v[202:205], v[40:43]
	v_mfma_f32_16x16x32_bf16 v[36:39], v[166:169], v[210:213], v[36:39]
	v_mfma_f32_16x16x32_bf16 v[32:35], v[174:177], v[210:213], v[32:35]
	v_mfma_f32_16x16x32_bf16 v[60:63], v[170:173], v[186:189], v[60:63]
	v_mfma_f32_16x16x32_bf16 v[56:59], v[178:181], v[186:189], v[56:59]
	v_mfma_f32_16x16x32_bf16 v[52:55], v[170:173], v[198:201], v[52:55]
	v_mfma_f32_16x16x32_bf16 v[48:51], v[178:181], v[198:201], v[48:51]
	v_mfma_f32_16x16x32_bf16 v[44:47], v[170:173], v[206:209], v[44:47]
	v_mfma_f32_16x16x32_bf16 v[40:43], v[178:181], v[206:209], v[40:43]
	v_mfma_f32_16x16x32_bf16 v[36:39], v[170:173], v[214:217], v[36:39]
	v_mfma_f32_16x16x32_bf16 v[32:35], v[178:181], v[214:217], v[32:35]
	s_barrier
	s_add_i32 s63, s55, s38
	v_lshl_add_u64 v[218:219], s[26:27], 0, v[152:153]
	s_mov_b32 m0, s63
	ds_read_b128 v[182:185], v197 offset:16384
	ds_read_b128 v[186:189], v197 offset:17408
	ds_read_b128 v[190:193], v197 offset:18432
	ds_read_b128 v[198:201], v197 offset:19456
	ds_read_b128 v[202:205], v197 offset:20480
	ds_read_b128 v[206:209], v197 offset:21504
	ds_read_b128 v[210:213], v197 offset:22528
	ds_read_b128 v[214:217], v197 offset:23552
	global_load_lds_dwordx4 v[218:219], off
	s_add_i32 m0, s63, 0x2000
	s_add_u32 s64, s26, 0x160000
	v_lshl_add_u64 v[220:221], s[26:27], 0, v[156:157]
	s_addc_u32 s65, s27, 0
	s_add_i32 s63, s56, s38
	global_load_lds_dwordx4 v[220:221], off
	v_lshl_add_u64 v[222:223], s[64:65], 0, v[152:153]
	s_mov_b32 m0, s63
	v_lshl_add_u64 v[224:225], s[34:35], 0, v[154:155]
	global_load_lds_dwordx4 v[222:223], off
	v_lshl_add_u64 v[222:223], s[64:65], 0, v[156:157]
	s_add_i32 m0, s63, 0x2000
	s_nop 0
	global_load_lds_dwordx4 v[222:223], off
	v_lshl_add_u64 v[222:223], s[34:35], 0, v[150:151]
	s_mov_b32 m0, s40
	s_nop 0
	global_load_lds_dwordx4 v[222:223], off
	s_mov_b32 m0, s41
	s_nop 0
	global_load_lds_dwordx4 v[224:225], off
	s_waitcnt vmcnt(8)
	s_waitcnt lgkmcnt(0)
	s_barrier
	s_waitcnt lgkmcnt(0)
	v_mfma_f32_16x16x32_bf16 v[92:95], v[128:131], v[182:185], v[92:95]
	v_mfma_f32_16x16x32_bf16 v[88:91], v[136:139], v[182:185], v[88:91]
	v_mfma_f32_16x16x32_bf16 v[84:87], v[128:131], v[190:193], v[84:87]
	v_mfma_f32_16x16x32_bf16 v[80:83], v[136:139], v[190:193], v[80:83]
	v_mfma_f32_16x16x32_bf16 v[76:79], v[128:131], v[202:205], v[76:79]
	v_mfma_f32_16x16x32_bf16 v[72:75], v[136:139], v[202:205], v[72:75]
	v_mfma_f32_16x16x32_bf16 v[68:71], v[128:131], v[210:213], v[68:71]
	v_mfma_f32_16x16x32_bf16 v[64:67], v[136:139], v[210:213], v[64:67]
	v_mfma_f32_16x16x32_bf16 v[92:95], v[132:135], v[186:189], v[92:95]
	v_mfma_f32_16x16x32_bf16 v[88:91], v[140:143], v[186:189], v[88:91]
	v_mfma_f32_16x16x32_bf16 v[84:87], v[132:135], v[198:201], v[84:87]
	v_mfma_f32_16x16x32_bf16 v[80:83], v[140:143], v[198:201], v[80:83]
	v_mfma_f32_16x16x32_bf16 v[76:79], v[132:135], v[206:209], v[76:79]
	v_mfma_f32_16x16x32_bf16 v[72:75], v[140:143], v[206:209], v[72:75]
	v_mfma_f32_16x16x32_bf16 v[68:71], v[132:135], v[214:217], v[68:71]
	v_mfma_f32_16x16x32_bf16 v[64:67], v[140:143], v[214:217], v[64:67]
	v_mfma_f32_16x16x32_bf16 v[28:31], v[166:169], v[182:185], v[28:31]
	v_mfma_f32_16x16x32_bf16 v[24:27], v[174:177], v[182:185], v[24:27]
	v_mfma_f32_16x16x32_bf16 v[20:23], v[166:169], v[190:193], v[20:23]
	v_mfma_f32_16x16x32_bf16 v[16:19], v[174:177], v[190:193], v[16:19]
	v_mfma_f32_16x16x32_bf16 v[12:15], v[166:169], v[202:205], v[12:15]
	v_mfma_f32_16x16x32_bf16 v[8:11], v[174:177], v[202:205], v[8:11]
	v_mfma_f32_16x16x32_bf16 v[4:7], v[166:169], v[210:213], v[4:7]
	v_mfma_f32_16x16x32_bf16 v[0:3], v[174:177], v[210:213], v[0:3]
	v_mfma_f32_16x16x32_bf16 v[28:31], v[170:173], v[186:189], v[28:31]
	v_mfma_f32_16x16x32_bf16 v[24:27], v[178:181], v[186:189], v[24:27]
	v_mfma_f32_16x16x32_bf16 v[20:23], v[170:173], v[198:201], v[20:23]
	v_mfma_f32_16x16x32_bf16 v[16:19], v[178:181], v[198:201], v[16:19]
	v_mfma_f32_16x16x32_bf16 v[12:15], v[170:173], v[206:209], v[12:15]
	v_mfma_f32_16x16x32_bf16 v[8:11], v[178:181], v[206:209], v[8:11]
	v_mfma_f32_16x16x32_bf16 v[4:7], v[170:173], v[214:217], v[4:7]
	v_mfma_f32_16x16x32_bf16 v[0:3], v[178:181], v[214:217], v[0:3]
	s_barrier
	s_add_i32 s63, 0, 0x18000
	s_add_i32 s64, 0, 0x1c000
	v_add_u32_e32 v140, s63, v149
	v_add_u32_e32 v178, s64, v149
	ds_read_b128 v[128:131], v140
	ds_read_b128 v[132:135], v140 offset:1024
	ds_read_b128 v[136:139], v140 offset:2048
	ds_read_b128 v[140:143], v140 offset:3072
	ds_read_b128 v[166:169], v178
	ds_read_b128 v[170:173], v178 offset:1024
	ds_read_b128 v[174:177], v178 offset:2048
	ds_read_b128 v[178:181], v178 offset:3072
	s_add_u32 s34, s34, 0x160000
	s_addc_u32 s35, s35, 0
	s_mov_b32 m0, s42
	v_lshl_add_u64 v[226:227], s[34:35], 0, v[150:151]
	ds_read_b128 v[182:185], v197 offset:32768
	ds_read_b128 v[186:189], v197 offset:33792
	ds_read_b128 v[190:193], v197 offset:34816
	ds_read_b128 v[198:201], v197 offset:35840
	ds_read_b128 v[202:205], v197 offset:36864
	ds_read_b128 v[206:209], v197 offset:37888
	ds_read_b128 v[210:213], v197 offset:38912
	ds_read_b128 v[214:217], v197 offset:39936
	global_load_lds_dwordx4 v[226:227], off
	v_lshl_add_u64 v[226:227], s[34:35], 0, v[154:155]
	s_mov_b32 m0, s43
	s_nop 0
	global_load_lds_dwordx4 v[226:227], off
	s_waitcnt vmcnt(8)
	s_waitcnt lgkmcnt(0)
	s_barrier
	s_waitcnt lgkmcnt(0)
	v_mfma_f32_16x16x32_bf16 v[124:127], v[128:131], v[182:185], v[124:127]
	v_mfma_f32_16x16x32_bf16 v[120:123], v[136:139], v[182:185], v[120:123]
	v_mfma_f32_16x16x32_bf16 v[116:119], v[128:131], v[190:193], v[116:119]
	v_mfma_f32_16x16x32_bf16 v[112:115], v[136:139], v[190:193], v[112:115]
	v_mfma_f32_16x16x32_bf16 v[108:111], v[128:131], v[202:205], v[108:111]
	v_mfma_f32_16x16x32_bf16 v[104:107], v[136:139], v[202:205], v[104:107]
	v_mfma_f32_16x16x32_bf16 v[100:103], v[128:131], v[210:213], v[100:103]
	v_mfma_f32_16x16x32_bf16 v[96:99], v[136:139], v[210:213], v[96:99]
	v_mfma_f32_16x16x32_bf16 v[124:127], v[132:135], v[186:189], v[124:127]
	v_mfma_f32_16x16x32_bf16 v[120:123], v[140:143], v[186:189], v[120:123]
	v_mfma_f32_16x16x32_bf16 v[116:119], v[132:135], v[198:201], v[116:119]
	v_mfma_f32_16x16x32_bf16 v[112:115], v[140:143], v[198:201], v[112:115]
	v_mfma_f32_16x16x32_bf16 v[108:111], v[132:135], v[206:209], v[108:111]
	v_mfma_f32_16x16x32_bf16 v[104:107], v[140:143], v[206:209], v[104:107]
	v_mfma_f32_16x16x32_bf16 v[100:103], v[132:135], v[214:217], v[100:103]
	v_mfma_f32_16x16x32_bf16 v[96:99], v[140:143], v[214:217], v[96:99]
	v_mfma_f32_16x16x32_bf16 v[60:63], v[166:169], v[182:185], v[60:63]
	v_mfma_f32_16x16x32_bf16 v[56:59], v[174:177], v[182:185], v[56:59]
	v_mfma_f32_16x16x32_bf16 v[52:55], v[166:169], v[190:193], v[52:55]
	v_mfma_f32_16x16x32_bf16 v[48:51], v[174:177], v[190:193], v[48:51]
	v_mfma_f32_16x16x32_bf16 v[44:47], v[166:169], v[202:205], v[44:47]
	v_mfma_f32_16x16x32_bf16 v[40:43], v[174:177], v[202:205], v[40:43]
	v_mfma_f32_16x16x32_bf16 v[36:39], v[166:169], v[210:213], v[36:39]
	v_mfma_f32_16x16x32_bf16 v[32:35], v[174:177], v[210:213], v[32:35]
	v_mfma_f32_16x16x32_bf16 v[60:63], v[170:173], v[186:189], v[60:63]
	v_mfma_f32_16x16x32_bf16 v[56:59], v[178:181], v[186:189], v[56:59]
	v_mfma_f32_16x16x32_bf16 v[52:55], v[170:173], v[198:201], v[52:55]
	v_mfma_f32_16x16x32_bf16 v[48:51], v[178:181], v[198:201], v[48:51]
	v_mfma_f32_16x16x32_bf16 v[44:47], v[170:173], v[206:209], v[44:47]
	v_mfma_f32_16x16x32_bf16 v[40:43], v[178:181], v[206:209], v[40:43]
	v_mfma_f32_16x16x32_bf16 v[36:39], v[170:173], v[214:217], v[36:39]
	v_mfma_f32_16x16x32_bf16 v[32:35], v[178:181], v[214:217], v[32:35]
	s_barrier
	s_add_i32 s34, s63, s38
	v_lshl_add_u64 v[218:219], v[218:219], 0, s[16:17]
	s_mov_b32 m0, s34
	ds_read_b128 v[182:185], v197 offset:49152
	ds_read_b128 v[186:189], v197 offset:50176
	ds_read_b128 v[190:193], v197 offset:51200
	ds_read_b128 v[198:201], v197 offset:52224
	ds_read_b128 v[202:205], v197 offset:53248
	ds_read_b128 v[206:209], v197 offset:54272
	ds_read_b128 v[210:213], v197 offset:55296
	ds_read_b128 v[214:217], v197 offset:56320
	global_load_lds_dwordx4 v[218:219], off
	s_add_i32 m0, s34, 0x2000
	s_add_u32 s26, s26, 0x160080
	v_lshl_add_u64 v[218:219], v[220:221], 0, s[16:17]
	s_addc_u32 s27, s27, 0
	s_add_i32 s34, s64, s38
	global_load_lds_dwordx4 v[218:219], off
	v_lshl_add_u64 v[218:219], s[26:27], 0, v[152:153]
	s_mov_b32 m0, s34
	s_nop 0
	global_load_lds_dwordx4 v[218:219], off
	v_lshl_add_u64 v[218:219], s[26:27], 0, v[156:157]
	s_add_i32 m0, s34, 0x2000
	s_nop 0
	global_load_lds_dwordx4 v[218:219], off
	v_lshl_add_u64 v[218:219], v[222:223], 0, s[16:17]
	s_mov_b32 m0, s52
	s_nop 0
	global_load_lds_dwordx4 v[218:219], off
	v_lshl_add_u64 v[218:219], v[224:225], 0, s[16:17]
	s_mov_b32 m0, s53
	s_nop 0
	global_load_lds_dwordx4 v[218:219], off
	s_waitcnt vmcnt(8)
	s_waitcnt lgkmcnt(0)
	s_barrier
	s_waitcnt lgkmcnt(0)
	v_mfma_f32_16x16x32_bf16 v[92:95], v[128:131], v[182:185], v[92:95]
	v_mfma_f32_16x16x32_bf16 v[88:91], v[136:139], v[182:185], v[88:91]
	v_mfma_f32_16x16x32_bf16 v[84:87], v[128:131], v[190:193], v[84:87]
	v_mfma_f32_16x16x32_bf16 v[80:83], v[136:139], v[190:193], v[80:83]
	v_mfma_f32_16x16x32_bf16 v[76:79], v[128:131], v[202:205], v[76:79]
	v_mfma_f32_16x16x32_bf16 v[72:75], v[136:139], v[202:205], v[72:75]
	v_mfma_f32_16x16x32_bf16 v[68:71], v[128:131], v[210:213], v[68:71]
	v_mfma_f32_16x16x32_bf16 v[64:67], v[136:139], v[210:213], v[64:67]
	v_mfma_f32_16x16x32_bf16 v[92:95], v[132:135], v[186:189], v[92:95]
	v_mfma_f32_16x16x32_bf16 v[88:91], v[140:143], v[186:189], v[88:91]
	v_mfma_f32_16x16x32_bf16 v[84:87], v[132:135], v[198:201], v[84:87]
	v_mfma_f32_16x16x32_bf16 v[80:83], v[140:143], v[198:201], v[80:83]
	v_mfma_f32_16x16x32_bf16 v[76:79], v[132:135], v[206:209], v[76:79]
	v_mfma_f32_16x16x32_bf16 v[72:75], v[140:143], v[206:209], v[72:75]
	v_mfma_f32_16x16x32_bf16 v[68:71], v[132:135], v[214:217], v[68:71]
	v_mfma_f32_16x16x32_bf16 v[64:67], v[140:143], v[214:217], v[64:67]
	v_mfma_f32_16x16x32_bf16 v[28:31], v[166:169], v[182:185], v[28:31]
	v_mfma_f32_16x16x32_bf16 v[24:27], v[174:177], v[182:185], v[24:27]
	v_mfma_f32_16x16x32_bf16 v[20:23], v[166:169], v[190:193], v[20:23]
	v_mfma_f32_16x16x32_bf16 v[16:19], v[174:177], v[190:193], v[16:19]
	v_mfma_f32_16x16x32_bf16 v[12:15], v[166:169], v[202:205], v[12:15]
	v_mfma_f32_16x16x32_bf16 v[8:11], v[174:177], v[202:205], v[8:11]
	v_mfma_f32_16x16x32_bf16 v[4:7], v[166:169], v[210:213], v[4:7]
	v_mfma_f32_16x16x32_bf16 v[0:3], v[174:177], v[210:213], v[0:3]
	v_mfma_f32_16x16x32_bf16 v[28:31], v[170:173], v[186:189], v[28:31]
	v_mfma_f32_16x16x32_bf16 v[24:27], v[178:181], v[186:189], v[24:27]
	v_mfma_f32_16x16x32_bf16 v[20:23], v[170:173], v[198:201], v[20:23]
	v_mfma_f32_16x16x32_bf16 v[16:19], v[178:181], v[198:201], v[16:19]
	v_mfma_f32_16x16x32_bf16 v[12:15], v[170:173], v[206:209], v[12:15]
	v_mfma_f32_16x16x32_bf16 v[8:11], v[178:181], v[206:209], v[8:11]
	v_mfma_f32_16x16x32_bf16 v[4:7], v[170:173], v[214:217], v[4:7]
	v_mfma_f32_16x16x32_bf16 v[0:3], v[178:181], v[214:217], v[0:3]
	s_barrier
	s_add_i32 s62, s62, 2
	s_add_u32 s24, s24, 0x100
	s_addc_u32 s25, s25, 0
	s_add_u32 s60, s60, 0x100
	s_addc_u32 s61, s61, 0
	s_cmpk_gt_u32 s62, 0x55
	s_cbranch_scc0 .LBB0_886
	s_and_b64 vcc, exec, s[18:19]
	s_cbranch_vccz .LBB0_889
	s_barrier

.LBB0_893:
	s_setprio 0
	s_cmp_gt_i32 s69, 8
	s_cselect_b64 s[0:1], -1, 0
	s_and_b64 s[4:5], s[6:7], s[0:1]
	s_andn2_b64 vcc, exec, s[4:5]
	s_cbranch_vccnz .LBB0_943
	s_waitcnt vmcnt(0)
	v_cmp_eq_u32_e32 vcc, 0, v146
	s_waitcnt vmcnt(0) lgkmcnt(0)
	s_barrier
	s_and_saveexec_b64 s[4:5], vcc
	s_cbranch_execz .LBB0_942
	s_add_i32 s3, 0, 0x23fc0
	v_mov_b32_e32 v0, s3
	s_waitcnt vmcnt(0) expcnt(0) lgkmcnt(0)
	ds_read_b32 v2, v0
	s_add_i32 s3, 0, 0x23fc4
	v_mov_b32_e32 v0, s3
	ds_read_b32 v0, v0
	s_waitcnt lgkmcnt(1)
	v_cmp_ne_u32_e32 vcc, 0, v2
	s_cbranch_vccnz .LBB0_910
	s_add_u32 s6, s30, 0x32200
	s_addc_u32 s7, s31, 0
	s_add_u32 s8, s30, 0x32400
	s_addc_u32 s9, s31, 0
	s_add_u32 s10, s30, 0x32500
	s_addc_u32 s11, s31, 0
	s_add_u32 s12, s30, 0x32600
	s_addc_u32 s13, s31, 0
	s_add_u32 s14, s30, 0x32700
	s_addc_u32 s15, s31, 0
	s_add_u32 s16, s30, 0x32800
	s_addc_u32 s17, s31, 0
	s_add_u32 s18, s30, 0x32900
	s_addc_u32 s19, s31, 0
	s_add_u32 s20, s30, 0x32a00
	s_addc_u32 s21, s31, 0
	s_add_u32 s22, s30, 0x32b00
	s_addc_u32 s23, s31, 0
	s_add_u32 s24, s30, 0x32c00
	s_addc_u32 s25, s31, 0
	s_add_u32 s26, s30, 0x32d00
	s_addc_u32 s27, s31, 0
	s_add_u32 s34, s30, 0x32e00
	s_addc_u32 s35, s31, 0
	s_add_u32 s36, s30, 0x32f00
	s_addc_u32 s37, s31, 0
	s_add_u32 s38, s30, 0x33000
	s_addc_u32 s39, s31, 0
	s_add_u32 s40, s30, 0x33100
	s_addc_u32 s41, s31, 0
	s_add_u32 s42, s30, 0x33200
	s_addc_u32 s43, s31, 0
	s_mul_i32 s3, s71, s85
	s_add_u32 s44, s30, 0x33300
	s_mul_i32 s3, s3, s70
	s_addc_u32 s45, s31, 0
	s_mov_b32 s33, 1
	v_mov_b32_e32 v16, 0
	s_branch .LBB0_898

.LBB0_1000:
	s_cmp_lt_i32 s68, 10
	s_cselect_b64 s[4:5], -1, 0
	s_and_b64 s[4:5], s[4:5], s[0:1]
	s_andn2_b64 vcc, exec, s[4:5]
	s_cbranch_vccnz .LBB0_1035
	v_readfirstlane_b32 s101, v145
	s_cmp_lt_u32 s101, 4
	s_cbranch_scc1 .Lprio_9
	s_setprio 1
.Lprio_9:
	s_cmpk_gt_i32 s2, 0x73f
	v_readfirstlane_b32 s1, v146
	s_cbranch_scc1 .LBB0_1035
	v_lshrrev_b32_e32 v12, 1, v146
	v_lshrrev_b32_e32 v3, 5, v146
	v_and_b32_e32 v2, 24, v12
	v_and_b32_e32 v3, 4, v3
	v_bfe_u32 v4, v146, 2, 2
	s_add_u32 s3, s30, 0x1f000000
	v_lshlrev_b32_e32 v0, 4, v146
	v_and_b32_e32 v1, 32, v146
	v_bfe_u32 v10, v146, 2, 4
	v_or3_b32 v2, v3, v4, v2
	v_lshrrev_b32_e32 v3, 3, v146
	s_movk_i32 s0, 0x70
	s_addc_u32 s23, s31, 0
	v_bitop3_b32 v8, v0, v1, 48 bitop3:0x6c
	v_and_b32_e32 v9, 64, v146
	v_and_or_b32 v4, v3, s0, v10
	s_movk_i32 s0, 0x60
	v_add_u32_e32 v11, 0x2000, v0
	s_add_u32 s25, s30, 0xcb00000
	v_or_b32_e32 v1, v8, v9
	v_and_or_b32 v3, v3, s0, v2
	v_lshrrev_b32_e32 v0, 7, v11
	s_movk_i32 s0, 0xf0
	s_waitcnt lgkmcnt(0)
	s_addc_u32 s52, s31, 0
	v_lshl_or_b32 v130, v3, 12, v1
	v_and_or_b32 v3, v0, s0, v10
	s_movk_i32 s0, 0xe0
	s_ashr_i32 s54, s2, 31
	v_and_or_b32 v0, v0, s0, v2
	s_lshr_b32 s0, s54, 29
	s_add_i32 s0, s2, s0
	s_lshr_b32 s6, s1, 6
	s_ashr_i32 s7, s0, 3
	s_and_b32 s0, s0, -8
	s_lshr_b32 s14, s1, 8
	s_lshl_b32 s53, s6, 10
	s_sub_i32 s0, s2, s0
	s_cmp_lt_i32 s0, 0
	s_movk_i32 s55, 0xe9
	s_cselect_b32 s8, s55, 0xe8
	s_mul_i32 s0, s0, s8
	s_add_i32 s0, s0, s7
	s_mul_hi_i32 s7, s0, 0x8d3dcb09
	s_add_i32 s7, s7, s0
	s_lshr_b32 s8, s7, 31
	s_ashr_i32 s7, s7, 7
	s_add_i32 s7, s7, s8
	s_lshl_b32 s8, s7, 3
	s_mulk_i32 s7, 0xe8
	s_sub_i32 s7, s0, s7
	s_sext_i32_i16 s0, s7
	s_bfe_u32 s0, s0, 0x3001c
	s_add_i32 s9, s7, s0
	s_sext_i32_i16 s0, s9
	s_and_b32 s9, s9, 0xfff8
	s_sub_i32 s7, s7, s9
	s_sext_i32_i16 s7, s7
	s_lshr_b32 s0, s0, 3
	s_add_i32 s42, s8, s7
	s_ashr_i32 s43, s42, 31
	s_bfe_i64 s[10:11], s[0:1], 0x100000
	s_lshl_b64 s[8:9], s[42:43], 20
	s_lshl_b64 s[10:11], s[10:11], 20
	s_add_u32 s50, s25, s10
	s_addc_u32 s51, s52, s11
	s_add_i32 s43, s53, 0
	s_add_i32 m0, s43, 0x10000
	v_lshl_or_b32 v134, v0, 12, v1
	global_load_lds_dwordx4 v130, s[50:51]
	s_add_i32 m0, s43, 0x12000
	s_add_u32 s10, s50, 0x80000
	global_load_lds_dwordx4 v134, s[50:51]
	s_addc_u32 s11, s51, 0
	s_add_i32 m0, s43, 0x14000
	v_lshl_or_b32 v128, v4, 12, v1
	global_load_lds_dwordx4 v130, s[10:11]
	s_add_i32 m0, s43, 0x16000
	s_add_u32 s44, s3, s8
	s_addc_u32 s45, s23, s9
	s_add_i32 s56, s43, 0x2000
	global_load_lds_dwordx4 v134, s[10:11]
	s_mov_b32 m0, s43
	s_add_u32 s8, s44, 0x80000
	v_lshl_or_b32 v132, v3, 12, v1
	global_load_lds_dwordx4 v128, s[44:45]
	s_mov_b32 m0, s56
	s_addc_u32 s9, s45, 0
	s_add_i32 s57, s43, 0x4000
	global_load_lds_dwordx4 v132, s[44:45]
	s_mov_b32 m0, s57
	s_add_i32 s58, s43, 0x6000
	global_load_lds_dwordx4 v128, s[8:9]
	s_mov_b32 m0, s58
	v_mov_b32_e32 v137, 0
	global_load_lds_dwordx4 v132, s[8:9]
	v_mov_b32_e32 v131, v137
	v_mov_b32_e32 v135, v137
	v_mov_b32_e32 v129, v137
	v_mov_b32_e32 v133, v137
	s_cmp_eq_u32 s14, 1
	s_mov_b32 s7, 0
	v_lshl_add_u64 v[6:7], s[50:51], 0, v[130:131]
	v_lshl_add_u64 v[4:5], s[50:51], 0, v[134:135]
	v_lshl_add_u64 v[0:1], s[44:45], 0, v[128:129]
	s_cselect_b64 s[8:9], -1, 0
	s_cmp_lg_u32 s14, 1
	v_lshl_add_u64 v[2:3], s[44:45], 0, v[132:133]
	s_cbranch_scc1 .LBB0_1004
	s_barrier

.LBB0_1010:
	ds_read_b128 v[162:165], v170
	ds_read_b128 v[174:177], v170 offset:1024
	ds_read_b128 v[178:181], v170 offset:2048
	ds_read_b128 v[182:185], v170 offset:3072
	ds_read_b128 v[186:189], v171
	ds_read_b128 v[190:193], v171 offset:1024
	ds_read_b128 v[194:197], v171 offset:2048
	ds_read_b128 v[198:201], v171 offset:3072
	s_add_u32 s34, s44, 0xfff80080
	s_addc_u32 s35, s45, -1
	s_cmp_eq_u32 s78, 28
	s_cselect_b32 s35, s6, s35
	s_cselect_b32 s34, s33, s34
	s_cselect_b32 s51, s27, s77
	s_cselect_b32 s50, s37, s76
	v_lshl_add_u64 v[166:167], s[44:45], 0, v[152:153]
	s_add_i32 m0, s43, 0xc000
	ds_read_b128 v[202:205], v172
	ds_read_b128 v[206:209], v172 offset:1024
	ds_read_b128 v[210:213], v172 offset:2048
	ds_read_b128 v[214:217], v172 offset:3072
	ds_read_b128 v[218:221], v172 offset:4096
	ds_read_b128 v[222:225], v172 offset:5120
	ds_read_b128 v[226:229], v172 offset:6144
	ds_read_b128 v[230:233], v172 offset:7168
	global_load_lds_dwordx4 v[166:167], off
	v_lshl_add_u64 v[166:167], s[44:45], 0, v[154:155]
	s_add_i32 m0, s43, 0xe000
	s_nop 0
	global_load_lds_dwordx4 v[166:167], off
	s_waitcnt vmcnt(8)
	s_waitcnt lgkmcnt(0)
	s_barrier
	s_waitcnt lgkmcnt(0)
	v_mfma_f32_16x16x32_bf16 v[124:127], v[162:165], v[202:205], v[124:127]
	v_mfma_f32_16x16x32_bf16 v[120:123], v[178:181], v[202:205], v[120:123]
	v_mfma_f32_16x16x32_bf16 v[108:111], v[162:165], v[210:213], v[108:111]
	v_mfma_f32_16x16x32_bf16 v[104:107], v[178:181], v[210:213], v[104:107]
	v_mfma_f32_16x16x32_bf16 v[92:95], v[162:165], v[218:221], v[92:95]
	v_mfma_f32_16x16x32_bf16 v[88:91], v[178:181], v[218:221], v[88:91]
	v_mfma_f32_16x16x32_bf16 v[76:79], v[162:165], v[226:229], v[76:79]
	v_mfma_f32_16x16x32_bf16 v[72:75], v[178:181], v[226:229], v[72:75]
	v_mfma_f32_16x16x32_bf16 v[124:127], v[174:177], v[206:209], v[124:127]
	v_mfma_f32_16x16x32_bf16 v[120:123], v[182:185], v[206:209], v[120:123]
	v_mfma_f32_16x16x32_bf16 v[108:111], v[174:177], v[214:217], v[108:111]
	v_mfma_f32_16x16x32_bf16 v[104:107], v[182:185], v[214:217], v[104:107]
	v_mfma_f32_16x16x32_bf16 v[92:95], v[174:177], v[222:225], v[92:95]
	v_mfma_f32_16x16x32_bf16 v[88:91], v[182:185], v[222:225], v[88:91]
	v_mfma_f32_16x16x32_bf16 v[76:79], v[174:177], v[230:233], v[76:79]
	v_mfma_f32_16x16x32_bf16 v[72:75], v[182:185], v[230:233], v[72:75]
	v_mfma_f32_16x16x32_bf16 v[116:119], v[186:189], v[202:205], v[116:119]
	v_mfma_f32_16x16x32_bf16 v[112:115], v[194:197], v[202:205], v[112:115]
	v_mfma_f32_16x16x32_bf16 v[100:103], v[186:189], v[210:213], v[100:103]
	v_mfma_f32_16x16x32_bf16 v[96:99], v[194:197], v[210:213], v[96:99]
	v_mfma_f32_16x16x32_bf16 v[84:87], v[186:189], v[218:221], v[84:87]
	v_mfma_f32_16x16x32_bf16 v[80:83], v[194:197], v[218:221], v[80:83]
	v_mfma_f32_16x16x32_bf16 v[68:71], v[186:189], v[226:229], v[68:71]
	v_mfma_f32_16x16x32_bf16 v[64:67], v[194:197], v[226:229], v[64:67]
	v_mfma_f32_16x16x32_bf16 v[116:119], v[190:193], v[206:209], v[116:119]
	v_mfma_f32_16x16x32_bf16 v[112:115], v[198:201], v[206:209], v[112:115]
	v_mfma_f32_16x16x32_bf16 v[100:103], v[190:193], v[214:217], v[100:103]
	v_mfma_f32_16x16x32_bf16 v[96:99], v[198:201], v[214:217], v[96:99]
	v_mfma_f32_16x16x32_bf16 v[84:87], v[190:193], v[222:225], v[84:87]
	v_mfma_f32_16x16x32_bf16 v[80:83], v[198:201], v[222:225], v[80:83]
	v_mfma_f32_16x16x32_bf16 v[68:71], v[190:193], v[230:233], v[68:71]
	v_mfma_f32_16x16x32_bf16 v[64:67], v[198:201], v[230:233], v[64:67]
	s_barrier
	s_add_i32 s79, s66, s53
	v_lshl_add_u64 v[166:167], s[50:51], 0, v[130:131]
	s_mov_b32 m0, s79
	ds_read_b128 v[202:205], v172 offset:16384
	ds_read_b128 v[206:209], v172 offset:17408
	ds_read_b128 v[210:213], v172 offset:18432
	ds_read_b128 v[214:217], v172 offset:19456
	ds_read_b128 v[218:221], v172 offset:20480
	ds_read_b128 v[222:225], v172 offset:21504
	ds_read_b128 v[226:229], v172 offset:22528
	ds_read_b128 v[230:233], v172 offset:23552
	global_load_lds_dwordx4 v[166:167], off
	s_add_i32 m0, s79, 0x2000
	s_add_u32 s80, s50, 0x80000
	v_lshl_add_u64 v[234:235], s[50:51], 0, v[134:135]
	s_addc_u32 s81, s51, 0
	s_add_i32 s79, s67, s53
	global_load_lds_dwordx4 v[234:235], off
	v_lshl_add_u64 v[236:237], s[80:81], 0, v[130:131]
	s_mov_b32 m0, s79
	v_lshl_add_u64 v[238:239], s[34:35], 0, v[132:133]
	global_load_lds_dwordx4 v[236:237], off
	v_lshl_add_u64 v[236:237], s[80:81], 0, v[134:135]
	s_add_i32 m0, s79, 0x2000
	s_nop 0
	global_load_lds_dwordx4 v[236:237], off
	v_lshl_add_u64 v[236:237], s[34:35], 0, v[128:129]
	s_mov_b32 m0, s43
	s_nop 0
	global_load_lds_dwordx4 v[236:237], off
	s_mov_b32 m0, s56
	s_nop 0
	global_load_lds_dwordx4 v[238:239], off
	s_waitcnt vmcnt(8)
	s_waitcnt lgkmcnt(0)
	s_barrier
	s_waitcnt lgkmcnt(0)
	v_mfma_f32_16x16x32_bf16 v[60:63], v[162:165], v[202:205], v[60:63]
	v_mfma_f32_16x16x32_bf16 v[56:59], v[178:181], v[202:205], v[56:59]
	v_mfma_f32_16x16x32_bf16 v[44:47], v[162:165], v[210:213], v[44:47]
	v_mfma_f32_16x16x32_bf16 v[40:43], v[178:181], v[210:213], v[40:43]
	v_mfma_f32_16x16x32_bf16 v[28:31], v[162:165], v[218:221], v[28:31]
	v_mfma_f32_16x16x32_bf16 v[24:27], v[178:181], v[218:221], v[24:27]
	v_mfma_f32_16x16x32_bf16 v[12:15], v[162:165], v[226:229], v[12:15]
	v_mfma_f32_16x16x32_bf16 v[8:11], v[178:181], v[226:229], v[8:11]
	v_mfma_f32_16x16x32_bf16 v[60:63], v[174:177], v[206:209], v[60:63]
	v_mfma_f32_16x16x32_bf16 v[56:59], v[182:185], v[206:209], v[56:59]
	v_mfma_f32_16x16x32_bf16 v[44:47], v[174:177], v[214:217], v[44:47]
	v_mfma_f32_16x16x32_bf16 v[40:43], v[182:185], v[214:217], v[40:43]
	v_mfma_f32_16x16x32_bf16 v[28:31], v[174:177], v[222:225], v[28:31]
	v_mfma_f32_16x16x32_bf16 v[24:27], v[182:185], v[222:225], v[24:27]
	v_mfma_f32_16x16x32_bf16 v[12:15], v[174:177], v[230:233], v[12:15]
	v_mfma_f32_16x16x32_bf16 v[8:11], v[182:185], v[230:233], v[8:11]
	v_mfma_f32_16x16x32_bf16 v[52:55], v[186:189], v[202:205], v[52:55]
	v_mfma_f32_16x16x32_bf16 v[48:51], v[194:197], v[202:205], v[48:51]
	v_mfma_f32_16x16x32_bf16 v[36:39], v[186:189], v[210:213], v[36:39]
	v_mfma_f32_16x16x32_bf16 v[32:35], v[194:197], v[210:213], v[32:35]
	v_mfma_f32_16x16x32_bf16 v[20:23], v[186:189], v[218:221], v[20:23]
	v_mfma_f32_16x16x32_bf16 v[16:19], v[194:197], v[218:221], v[16:19]
	v_mfma_f32_16x16x32_bf16 v[4:7], v[186:189], v[226:229], v[4:7]
	v_mfma_f32_16x16x32_bf16 v[0:3], v[194:197], v[226:229], v[0:3]
	v_mfma_f32_16x16x32_bf16 v[52:55], v[190:193], v[206:209], v[52:55]
	v_mfma_f32_16x16x32_bf16 v[48:51], v[198:201], v[206:209], v[48:51]
	v_mfma_f32_16x16x32_bf16 v[36:39], v[190:193], v[214:217], v[36:39]
	v_mfma_f32_16x16x32_bf16 v[32:35], v[198:201], v[214:217], v[32:35]
	v_mfma_f32_16x16x32_bf16 v[20:23], v[190:193], v[222:225], v[20:23]
	v_mfma_f32_16x16x32_bf16 v[16:19], v[198:201], v[222:225], v[16:19]
	v_mfma_f32_16x16x32_bf16 v[4:7], v[190:193], v[230:233], v[4:7]
	v_mfma_f32_16x16x32_bf16 v[0:3], v[198:201], v[230:233], v[0:3]
	s_barrier
	s_add_i32 s79, 0, 0x18000
	v_add_u32_e32 v161, s79, v168
	s_add_i32 s80, 0, 0x1c000
	ds_read_b128 v[162:165], v161
	ds_read_b128 v[174:177], v161 offset:1024
	ds_read_b128 v[178:181], v161 offset:2048
	ds_read_b128 v[182:185], v161 offset:3072
	v_add_u32_e32 v161, s80, v168
	ds_read_b128 v[186:189], v161
	ds_read_b128 v[190:193], v161 offset:1024
	ds_read_b128 v[194:197], v161 offset:2048
	ds_read_b128 v[198:201], v161 offset:3072
	s_add_u32 s34, s34, 0x80000
	s_addc_u32 s35, s35, 0
	s_mov_b32 m0, s57
	v_lshl_add_u64 v[240:241], s[34:35], 0, v[128:129]
	ds_read_b128 v[202:205], v172 offset:32768
	ds_read_b128 v[206:209], v172 offset:33792
	ds_read_b128 v[210:213], v172 offset:34816
	ds_read_b128 v[214:217], v172 offset:35840
	ds_read_b128 v[218:221], v172 offset:36864
	ds_read_b128 v[222:225], v172 offset:37888
	ds_read_b128 v[226:229], v172 offset:38912
	ds_read_b128 v[230:233], v172 offset:39936
	global_load_lds_dwordx4 v[240:241], off
	v_lshl_add_u64 v[240:241], s[34:35], 0, v[132:133]
	s_mov_b32 m0, s58
	s_nop 0
	global_load_lds_dwordx4 v[240:241], off
	s_waitcnt vmcnt(8)
	s_waitcnt lgkmcnt(0)
	s_barrier
	s_waitcnt lgkmcnt(0)
	v_mfma_f32_16x16x32_bf16 v[124:127], v[162:165], v[202:205], v[124:127]
	v_mfma_f32_16x16x32_bf16 v[120:123], v[178:181], v[202:205], v[120:123]
	v_mfma_f32_16x16x32_bf16 v[108:111], v[162:165], v[210:213], v[108:111]
	v_mfma_f32_16x16x32_bf16 v[104:107], v[178:181], v[210:213], v[104:107]
	v_mfma_f32_16x16x32_bf16 v[92:95], v[162:165], v[218:221], v[92:95]
	v_mfma_f32_16x16x32_bf16 v[88:91], v[178:181], v[218:221], v[88:91]
	v_mfma_f32_16x16x32_bf16 v[76:79], v[162:165], v[226:229], v[76:79]
	v_mfma_f32_16x16x32_bf16 v[72:75], v[178:181], v[226:229], v[72:75]
	v_mfma_f32_16x16x32_bf16 v[124:127], v[174:177], v[206:209], v[124:127]
	v_mfma_f32_16x16x32_bf16 v[120:123], v[182:185], v[206:209], v[120:123]
	v_mfma_f32_16x16x32_bf16 v[108:111], v[174:177], v[214:217], v[108:111]
	v_mfma_f32_16x16x32_bf16 v[104:107], v[182:185], v[214:217], v[104:107]
	v_mfma_f32_16x16x32_bf16 v[92:95], v[174:177], v[222:225], v[92:95]
	v_mfma_f32_16x16x32_bf16 v[88:91], v[182:185], v[222:225], v[88:91]
	v_mfma_f32_16x16x32_bf16 v[76:79], v[174:177], v[230:233], v[76:79]
	v_mfma_f32_16x16x32_bf16 v[72:75], v[182:185], v[230:233], v[72:75]
	v_mfma_f32_16x16x32_bf16 v[116:119], v[186:189], v[202:205], v[116:119]
	v_mfma_f32_16x16x32_bf16 v[112:115], v[194:197], v[202:205], v[112:115]
	v_mfma_f32_16x16x32_bf16 v[100:103], v[186:189], v[210:213], v[100:103]
	v_mfma_f32_16x16x32_bf16 v[96:99], v[194:197], v[210:213], v[96:99]
	v_mfma_f32_16x16x32_bf16 v[84:87], v[186:189], v[218:221], v[84:87]
	v_mfma_f32_16x16x32_bf16 v[80:83], v[194:197], v[218:221], v[80:83]
	v_mfma_f32_16x16x32_bf16 v[68:71], v[186:189], v[226:229], v[68:71]
	v_mfma_f32_16x16x32_bf16 v[64:67], v[194:197], v[226:229], v[64:67]
	v_mfma_f32_16x16x32_bf16 v[116:119], v[190:193], v[206:209], v[116:119]
	v_mfma_f32_16x16x32_bf16 v[112:115], v[198:201], v[206:209], v[112:115]
	v_mfma_f32_16x16x32_bf16 v[100:103], v[190:193], v[214:217], v[100:103]
	v_mfma_f32_16x16x32_bf16 v[96:99], v[198:201], v[214:217], v[96:99]
	v_mfma_f32_16x16x32_bf16 v[84:87], v[190:193], v[222:225], v[84:87]
	v_mfma_f32_16x16x32_bf16 v[80:83], v[198:201], v[222:225], v[80:83]
	v_mfma_f32_16x16x32_bf16 v[68:71], v[190:193], v[230:233], v[68:71]
	v_mfma_f32_16x16x32_bf16 v[64:67], v[198:201], v[230:233], v[64:67]
	s_barrier
	s_add_i32 s34, s79, s53
	v_lshl_add_u64 v[166:167], v[166:167], 0, s[14:15]
	s_mov_b32 m0, s34
	ds_read_b128 v[202:205], v172 offset:49152
	ds_read_b128 v[206:209], v172 offset:50176
	ds_read_b128 v[210:213], v172 offset:51200
	ds_read_b128 v[214:217], v172 offset:52224
	ds_read_b128 v[218:221], v172 offset:53248
	ds_read_b128 v[222:225], v172 offset:54272
	ds_read_b128 v[226:229], v172 offset:55296
	ds_read_b128 v[230:233], v172 offset:56320
	global_load_lds_dwordx4 v[166:167], off
	s_add_i32 m0, s34, 0x2000
	s_add_u32 s34, s50, 0x80080
	v_lshl_add_u64 v[166:167], v[234:235], 0, s[14:15]
	s_addc_u32 s35, s51, 0
	s_add_i32 s50, s80, s53
	global_load_lds_dwordx4 v[166:167], off
	v_lshl_add_u64 v[166:167], s[34:35], 0, v[130:131]
	s_mov_b32 m0, s50
	s_nop 0
	global_load_lds_dwordx4 v[166:167], off
	v_lshl_add_u64 v[166:167], s[34:35], 0, v[134:135]
	s_add_i32 m0, s50, 0x2000
	s_nop 0
	global_load_lds_dwordx4 v[166:167], off
	v_lshl_add_u64 v[166:167], v[236:237], 0, s[14:15]
	s_mov_b32 m0, s61
	s_nop 0
	global_load_lds_dwordx4 v[166:167], off
	v_lshl_add_u64 v[166:167], v[238:239], 0, s[14:15]
	s_mov_b32 m0, s62
	s_nop 0
	global_load_lds_dwordx4 v[166:167], off
	s_waitcnt vmcnt(8)
	s_waitcnt lgkmcnt(0)
	s_barrier
	s_waitcnt lgkmcnt(0)
	v_mfma_f32_16x16x32_bf16 v[60:63], v[162:165], v[202:205], v[60:63]
	v_mfma_f32_16x16x32_bf16 v[56:59], v[178:181], v[202:205], v[56:59]
	v_mfma_f32_16x16x32_bf16 v[44:47], v[162:165], v[210:213], v[44:47]
	v_mfma_f32_16x16x32_bf16 v[40:43], v[178:181], v[210:213], v[40:43]
	v_mfma_f32_16x16x32_bf16 v[28:31], v[162:165], v[218:221], v[28:31]
	v_mfma_f32_16x16x32_bf16 v[24:27], v[178:181], v[218:221], v[24:27]
	v_mfma_f32_16x16x32_bf16 v[12:15], v[162:165], v[226:229], v[12:15]
	v_mfma_f32_16x16x32_bf16 v[8:11], v[178:181], v[226:229], v[8:11]
	v_mfma_f32_16x16x32_bf16 v[60:63], v[174:177], v[206:209], v[60:63]
	v_mfma_f32_16x16x32_bf16 v[56:59], v[182:185], v[206:209], v[56:59]
	v_mfma_f32_16x16x32_bf16 v[44:47], v[174:177], v[214:217], v[44:47]
	v_mfma_f32_16x16x32_bf16 v[40:43], v[182:185], v[214:217], v[40:43]
	v_mfma_f32_16x16x32_bf16 v[28:31], v[174:177], v[222:225], v[28:31]
	v_mfma_f32_16x16x32_bf16 v[24:27], v[182:185], v[222:225], v[24:27]
	v_mfma_f32_16x16x32_bf16 v[12:15], v[174:177], v[230:233], v[12:15]
	v_mfma_f32_16x16x32_bf16 v[8:11], v[182:185], v[230:233], v[8:11]
	v_mfma_f32_16x16x32_bf16 v[52:55], v[186:189], v[202:205], v[52:55]
	v_mfma_f32_16x16x32_bf16 v[48:51], v[194:197], v[202:205], v[48:51]
	v_mfma_f32_16x16x32_bf16 v[36:39], v[186:189], v[210:213], v[36:39]
	v_mfma_f32_16x16x32_bf16 v[32:35], v[194:197], v[210:213], v[32:35]
	v_mfma_f32_16x16x32_bf16 v[20:23], v[186:189], v[218:221], v[20:23]
	v_mfma_f32_16x16x32_bf16 v[16:19], v[194:197], v[218:221], v[16:19]
	v_mfma_f32_16x16x32_bf16 v[4:7], v[186:189], v[226:229], v[4:7]
	v_mfma_f32_16x16x32_bf16 v[0:3], v[194:197], v[226:229], v[0:3]
	v_mfma_f32_16x16x32_bf16 v[52:55], v[190:193], v[206:209], v[52:55]
	v_mfma_f32_16x16x32_bf16 v[48:51], v[198:201], v[206:209], v[48:51]
	v_mfma_f32_16x16x32_bf16 v[36:39], v[190:193], v[214:217], v[36:39]
	v_mfma_f32_16x16x32_bf16 v[32:35], v[198:201], v[214:217], v[32:35]
	v_mfma_f32_16x16x32_bf16 v[20:23], v[190:193], v[222:225], v[20:23]
	v_mfma_f32_16x16x32_bf16 v[16:19], v[198:201], v[222:225], v[16:19]
	v_mfma_f32_16x16x32_bf16 v[4:7], v[190:193], v[230:233], v[4:7]
	v_mfma_f32_16x16x32_bf16 v[0:3], v[198:201], v[230:233], v[0:3]
	s_barrier
	s_add_i32 s78, s78, 2
	s_add_u32 s44, s44, 0x100
	s_addc_u32 s45, s45, 0
	s_add_u32 s76, s76, 0x100
	s_addc_u32 s77, s77, 0
	s_cmp_gt_u32 s78, 29
	s_cbranch_scc0 .LBB0_1010
	s_and_b64 vcc, exec, s[16:17]
	s_cbranch_vccnz .LBB0_1015
	s_cmp_gt_i32 s75, 15
	s_mov_b64 s[34:35], -1
	s_cbranch_scc1 .LBB0_1016

.LBB0_1035:
	s_setprio 0
	s_cmp_gt_i32 s69, 10
	s_cselect_b64 s[0:1], -1, 0
	s_and_b64 s[4:5], s[4:5], s[0:1]
	s_andn2_b64 vcc, exec, s[4:5]
	s_cbranch_vccnz .LBB0_1085
	s_waitcnt vmcnt(0)
	v_cmp_eq_u32_e32 vcc, 0, v146
	s_waitcnt vmcnt(0) lgkmcnt(0)
	s_barrier
	s_and_saveexec_b64 s[4:5], vcc
	s_cbranch_execz .LBB0_1084
	s_add_i32 s3, 0, 0x23fc0
	v_mov_b32_e32 v0, s3
	s_waitcnt vmcnt(0) expcnt(0) lgkmcnt(0)
	ds_read_b32 v2, v0
	s_add_i32 s3, 0, 0x23fc4
	v_mov_b32_e32 v0, s3
	ds_read_b32 v0, v0
	s_waitcnt lgkmcnt(1)
	v_cmp_ne_u32_e32 vcc, 0, v2
	s_cbranch_vccnz .LBB0_1052
	s_add_u32 s6, s30, 0x32200
	s_addc_u32 s7, s31, 0
	s_add_u32 s8, s30, 0x32400
	s_addc_u32 s9, s31, 0
	s_add_u32 s10, s30, 0x32500
	s_addc_u32 s11, s31, 0
	s_add_u32 s12, s30, 0x32600
	s_addc_u32 s13, s31, 0
	s_add_u32 s14, s30, 0x32700
	s_addc_u32 s15, s31, 0
	s_add_u32 s16, s30, 0x32800
	s_addc_u32 s17, s31, 0
	s_add_u32 s18, s30, 0x32900
	s_addc_u32 s19, s31, 0
	s_add_u32 s20, s30, 0x32a00
	s_addc_u32 s21, s31, 0
	s_add_u32 s22, s30, 0x32b00
	s_addc_u32 s23, s31, 0
	s_add_u32 s24, s30, 0x32c00
	s_addc_u32 s25, s31, 0
	s_add_u32 s26, s30, 0x32d00
	s_addc_u32 s27, s31, 0
	s_add_u32 s34, s30, 0x32e00
	s_addc_u32 s35, s31, 0
	s_add_u32 s36, s30, 0x32f00
	s_addc_u32 s37, s31, 0
	s_add_u32 s38, s30, 0x33000
	s_addc_u32 s39, s31, 0
	s_add_u32 s40, s30, 0x33100
	s_addc_u32 s41, s31, 0
	s_add_u32 s42, s30, 0x33200
	s_addc_u32 s43, s31, 0
	s_mul_i32 s3, s71, s85
	s_add_u32 s44, s30, 0x33300
	s_mul_i32 s3, s3, s70
	s_addc_u32 s45, s31, 0
	s_mov_b32 s33, 1
	v_mov_b32_e32 v16, 0
	s_branch .LBB0_1040

.LBB0_2408:
	s_cmp_lt_i32 s68, 13
	s_cselect_b64 s[4:5], -1, 0
	s_and_b64 s[4:5], s[4:5], s[0:1]
	s_andn2_b64 vcc, exec, s[4:5]
	s_cbranch_vccnz .LBB0_2429
	v_readfirstlane_b32 s101, v145
	s_cmp_lt_u32 s101, 4
	s_cbranch_scc1 .Lprio_12
	s_setprio 1
.Lprio_12:
	s_cmpk_gt_i32 s2, 0x1ff
	v_readfirstlane_b32 s1, v146
	s_cbranch_scc1 .LBB0_2429
	v_lshrrev_b32_e32 v2, 1, v146
	v_and_b32_e32 v11, 24, v2
	v_lshrrev_b32_e32 v2, 5, v146
	v_and_b32_e32 v2, 4, v2
	v_bfe_u32 v3, v146, 2, 2
	s_add_u32 s3, s30, 0x1f000000
	v_lshlrev_b32_e32 v0, 4, v146
	v_and_b32_e32 v1, 32, v146
	v_bfe_u32 v10, v146, 2, 4
	v_or3_b32 v2, v2, v3, v11
	v_lshrrev_b32_e32 v3, 3, v146
	s_movk_i32 s0, 0x70
	s_addc_u32 s23, s31, 0
	v_bitop3_b32 v8, v0, v1, 48 bitop3:0x6c
	v_and_b32_e32 v9, 64, v146
	v_and_or_b32 v4, v3, s0, v10
	s_movk_i32 s0, 0x60
	v_add_u32_e32 v12, 0x2000, v0
	s_waitcnt lgkmcnt(0)
	s_add_u32 s50, s30, 0xe800000
	v_or_b32_e32 v1, v8, v9
	v_and_or_b32 v3, v3, s0, v2
	v_lshrrev_b32_e32 v0, 7, v12
	s_movk_i32 s0, 0xf0
	s_addc_u32 s51, s31, 0
	v_lshl_or_b32 v152, v3, 12, v1
	v_and_or_b32 v3, v0, s0, v10
	s_movk_i32 s0, 0xe0
	s_ashr_i32 s53, s2, 31
	v_and_or_b32 v0, v0, s0, v2
	s_lshr_b32 s0, s53, 29
	s_add_i32 s0, s2, s0
	s_and_b32 s6, s0, -8
	s_lshr_b32 s18, s1, 6
	s_sub_i32 s6, s2, s6
	s_lshr_b32 s20, s1, 8
	s_lshl_b32 s52, s18, 10
	s_lshl_b32 s8, s6, 6
	s_ashr_i32 s0, s0, 3
	s_mul_i32 s7, s6, 0x41
	s_cmp_lt_i32 s6, 0
	s_cselect_b32 s6, s7, s8
	s_add_i32 s0, s6, s0
	s_ashr_i32 s6, s0, 31
	s_lshr_b32 s6, s6, 26
	s_add_i32 s6, s0, s6
	s_ashr_i32 s7, s6, 6
	s_andn2_b32 s6, s6, 63
	s_sub_i32 s6, s0, s6
	s_bfe_i32 s0, s6, 0x80000
	s_bfe_u32 s0, s0, 0x3000c
	s_add_i32 s8, s6, s0
	s_bfe_i32 s0, s8, 0x80000
	s_and_b32 s8, s8, 0xf8
	s_sub_i32 s6, s6, s8
	s_lshl_b32 s7, s7, 3
	s_sext_i32_i16 s0, s0
	s_sext_i32_i8 s6, s6
	s_lshr_b32 s0, s0, 3
	s_add_i32 s40, s7, s6
	s_ashr_i32 s41, s40, 31
	s_bfe_i64 s[8:9], s[0:1], 0x100000
	s_lshl_b64 s[6:7], s[40:41], 20
	s_lshl_b64 s[8:9], s[8:9], 20
	s_add_u32 s44, s50, s8
	s_addc_u32 s45, s51, s9
	s_add_i32 s41, s52, 0
	s_add_i32 m0, s41, 0x10000
	v_lshl_or_b32 v156, v0, 12, v1
	global_load_lds_dwordx4 v152, s[44:45]
	s_add_i32 m0, s41, 0x12000
	s_add_u32 s8, s44, 0x80000
	global_load_lds_dwordx4 v156, s[44:45]
	s_addc_u32 s9, s45, 0
	s_add_i32 m0, s41, 0x14000
	v_lshl_or_b32 v150, v4, 12, v1
	global_load_lds_dwordx4 v152, s[8:9]
	s_add_i32 m0, s41, 0x16000
	s_add_u32 s42, s3, s6
	s_addc_u32 s43, s23, s7
	s_add_i32 s54, s41, 0x2000
	global_load_lds_dwordx4 v156, s[8:9]
	s_mov_b32 m0, s41
	s_add_u32 s6, s42, 0x80000
	v_lshl_or_b32 v154, v3, 12, v1
	global_load_lds_dwordx4 v150, s[42:43]
	s_mov_b32 m0, s54
	s_addc_u32 s7, s43, 0
	s_add_i32 s55, s41, 0x4000
	global_load_lds_dwordx4 v154, s[42:43]
	s_mov_b32 m0, s55
	s_add_i32 s56, s41, 0x6000
	global_load_lds_dwordx4 v150, s[6:7]
	s_mov_b32 m0, s56
	v_mov_b32_e32 v153, 0
	global_load_lds_dwordx4 v154, s[6:7]
	v_mov_b32_e32 v157, v153
	v_mov_b32_e32 v151, v153
	v_mov_b32_e32 v155, v153
	s_cmp_eq_u32 s20, 1
	s_mov_b32 s57, 0
	v_lshl_add_u64 v[6:7], s[44:45], 0, v[152:153]
	v_lshl_add_u64 v[4:5], s[44:45], 0, v[156:157]
	v_lshl_add_u64 v[0:1], s[42:43], 0, v[150:151]
	s_cselect_b64 s[6:7], -1, 0
	s_cmp_lg_u32 s20, 1
	v_lshl_add_u64 v[2:3], s[42:43], 0, v[154:155]
	s_cbranch_scc1 .LBB0_2412
	s_barrier

.LBB0_2422:
	ds_read_b128 v[128:131], v193
	ds_read_b128 v[132:135], v193 offset:1024
	ds_read_b128 v[136:139], v193 offset:2048
	ds_read_b128 v[140:143], v193 offset:3072
	ds_read_b128 v[166:169], v194
	ds_read_b128 v[170:173], v194 offset:1024
	ds_read_b128 v[174:177], v194 offset:2048
	ds_read_b128 v[178:181], v194 offset:3072
	s_add_u32 s34, s42, 0xfff80080
	s_addc_u32 s35, s43, -1
	s_cmp_eq_u32 s74, 28
	s_cselect_b32 s35, s27, s35
	s_cselect_b32 s34, s66, s34
	s_cselect_b32 s45, s25, s73
	s_cselect_b32 s44, s67, s72
	v_lshl_add_u64 v[190:191], s[42:43], 0, v[158:159]
	s_add_i32 m0, s41, 0xc000
	ds_read_b128 v[182:185], v195
	ds_read_b128 v[186:189], v195 offset:1024
	ds_read_b128 v[196:199], v195 offset:2048
	ds_read_b128 v[200:203], v195 offset:3072
	ds_read_b128 v[204:207], v195 offset:4096
	ds_read_b128 v[208:211], v195 offset:5120
	ds_read_b128 v[212:215], v195 offset:6144
	ds_read_b128 v[216:219], v195 offset:7168
	global_load_lds_dwordx4 v[190:191], off
	v_lshl_add_u64 v[190:191], s[42:43], 0, v[160:161]
	s_add_i32 m0, s41, 0xe000
	s_nop 0
	global_load_lds_dwordx4 v[190:191], off
	s_waitcnt vmcnt(8)
	s_waitcnt lgkmcnt(0)
	s_barrier
	s_waitcnt lgkmcnt(0)
	v_mfma_f32_16x16x32_bf16 v[124:127], v[128:131], v[182:185], v[124:127]
	v_mfma_f32_16x16x32_bf16 v[120:123], v[136:139], v[182:185], v[120:123]
	v_mfma_f32_16x16x32_bf16 v[116:119], v[128:131], v[196:199], v[116:119]
	v_mfma_f32_16x16x32_bf16 v[112:115], v[136:139], v[196:199], v[112:115]
	v_mfma_f32_16x16x32_bf16 v[108:111], v[128:131], v[204:207], v[108:111]
	v_mfma_f32_16x16x32_bf16 v[104:107], v[136:139], v[204:207], v[104:107]
	v_mfma_f32_16x16x32_bf16 v[100:103], v[128:131], v[212:215], v[100:103]
	v_mfma_f32_16x16x32_bf16 v[96:99], v[136:139], v[212:215], v[96:99]
	v_mfma_f32_16x16x32_bf16 v[124:127], v[132:135], v[186:189], v[124:127]
	v_mfma_f32_16x16x32_bf16 v[120:123], v[140:143], v[186:189], v[120:123]
	v_mfma_f32_16x16x32_bf16 v[116:119], v[132:135], v[200:203], v[116:119]
	v_mfma_f32_16x16x32_bf16 v[112:115], v[140:143], v[200:203], v[112:115]
	v_mfma_f32_16x16x32_bf16 v[108:111], v[132:135], v[208:211], v[108:111]
	v_mfma_f32_16x16x32_bf16 v[104:107], v[140:143], v[208:211], v[104:107]
	v_mfma_f32_16x16x32_bf16 v[100:103], v[132:135], v[216:219], v[100:103]
	v_mfma_f32_16x16x32_bf16 v[96:99], v[140:143], v[216:219], v[96:99]
	v_mfma_f32_16x16x32_bf16 v[60:63], v[166:169], v[182:185], v[60:63]
	v_mfma_f32_16x16x32_bf16 v[56:59], v[174:177], v[182:185], v[56:59]
	v_mfma_f32_16x16x32_bf16 v[52:55], v[166:169], v[196:199], v[52:55]
	v_mfma_f32_16x16x32_bf16 v[48:51], v[174:177], v[196:199], v[48:51]
	v_mfma_f32_16x16x32_bf16 v[44:47], v[166:169], v[204:207], v[44:47]
	v_mfma_f32_16x16x32_bf16 v[40:43], v[174:177], v[204:207], v[40:43]
	v_mfma_f32_16x16x32_bf16 v[36:39], v[166:169], v[212:215], v[36:39]
	v_mfma_f32_16x16x32_bf16 v[32:35], v[174:177], v[212:215], v[32:35]
	v_mfma_f32_16x16x32_bf16 v[60:63], v[170:173], v[186:189], v[60:63]
	v_mfma_f32_16x16x32_bf16 v[56:59], v[178:181], v[186:189], v[56:59]
	v_mfma_f32_16x16x32_bf16 v[52:55], v[170:173], v[200:203], v[52:55]
	v_mfma_f32_16x16x32_bf16 v[48:51], v[178:181], v[200:203], v[48:51]
	v_mfma_f32_16x16x32_bf16 v[44:47], v[170:173], v[208:211], v[44:47]
	v_mfma_f32_16x16x32_bf16 v[40:43], v[178:181], v[208:211], v[40:43]
	v_mfma_f32_16x16x32_bf16 v[36:39], v[170:173], v[216:219], v[36:39]
	v_mfma_f32_16x16x32_bf16 v[32:35], v[178:181], v[216:219], v[32:35]
	s_barrier
	s_add_i32 s75, s64, s52
	v_lshl_add_u64 v[190:191], s[44:45], 0, v[152:153]
	s_mov_b32 m0, s75
	ds_read_b128 v[182:185], v195 offset:16384
	ds_read_b128 v[186:189], v195 offset:17408
	ds_read_b128 v[196:199], v195 offset:18432
	ds_read_b128 v[200:203], v195 offset:19456
	ds_read_b128 v[204:207], v195 offset:20480
	ds_read_b128 v[208:211], v195 offset:21504
	ds_read_b128 v[212:215], v195 offset:22528
	ds_read_b128 v[216:219], v195 offset:23552
	global_load_lds_dwordx4 v[190:191], off
	s_add_i32 m0, s75, 0x2000
	s_add_u32 s76, s44, 0x80000
	v_lshl_add_u64 v[220:221], s[44:45], 0, v[156:157]
	s_addc_u32 s77, s45, 0
	s_add_i32 s75, s65, s52
	global_load_lds_dwordx4 v[220:221], off
	v_lshl_add_u64 v[222:223], s[76:77], 0, v[152:153]
	s_mov_b32 m0, s75
	v_lshl_add_u64 v[224:225], s[34:35], 0, v[154:155]
	global_load_lds_dwordx4 v[222:223], off
	v_lshl_add_u64 v[222:223], s[76:77], 0, v[156:157]
	s_add_i32 m0, s75, 0x2000
	s_nop 0
	global_load_lds_dwordx4 v[222:223], off
	v_lshl_add_u64 v[222:223], s[34:35], 0, v[150:151]
	s_mov_b32 m0, s41
	s_nop 0
	global_load_lds_dwordx4 v[222:223], off
	s_mov_b32 m0, s54
	s_nop 0
	global_load_lds_dwordx4 v[224:225], off
	s_waitcnt vmcnt(8)
	s_waitcnt lgkmcnt(0)
	s_barrier
	s_waitcnt lgkmcnt(0)
	v_mfma_f32_16x16x32_bf16 v[92:95], v[128:131], v[182:185], v[92:95]
	v_mfma_f32_16x16x32_bf16 v[88:91], v[136:139], v[182:185], v[88:91]
	v_mfma_f32_16x16x32_bf16 v[84:87], v[128:131], v[196:199], v[84:87]
	v_mfma_f32_16x16x32_bf16 v[80:83], v[136:139], v[196:199], v[80:83]
	v_mfma_f32_16x16x32_bf16 v[76:79], v[128:131], v[204:207], v[76:79]
	v_mfma_f32_16x16x32_bf16 v[72:75], v[136:139], v[204:207], v[72:75]
	v_mfma_f32_16x16x32_bf16 v[68:71], v[128:131], v[212:215], v[68:71]
	v_mfma_f32_16x16x32_bf16 v[64:67], v[136:139], v[212:215], v[64:67]
	v_mfma_f32_16x16x32_bf16 v[92:95], v[132:135], v[186:189], v[92:95]
	v_mfma_f32_16x16x32_bf16 v[88:91], v[140:143], v[186:189], v[88:91]
	v_mfma_f32_16x16x32_bf16 v[84:87], v[132:135], v[200:203], v[84:87]
	v_mfma_f32_16x16x32_bf16 v[80:83], v[140:143], v[200:203], v[80:83]
	v_mfma_f32_16x16x32_bf16 v[76:79], v[132:135], v[208:211], v[76:79]
	v_mfma_f32_16x16x32_bf16 v[72:75], v[140:143], v[208:211], v[72:75]
	v_mfma_f32_16x16x32_bf16 v[68:71], v[132:135], v[216:219], v[68:71]
	v_mfma_f32_16x16x32_bf16 v[64:67], v[140:143], v[216:219], v[64:67]
	v_mfma_f32_16x16x32_bf16 v[28:31], v[166:169], v[182:185], v[28:31]
	v_mfma_f32_16x16x32_bf16 v[24:27], v[174:177], v[182:185], v[24:27]
	v_mfma_f32_16x16x32_bf16 v[20:23], v[166:169], v[196:199], v[20:23]
	v_mfma_f32_16x16x32_bf16 v[16:19], v[174:177], v[196:199], v[16:19]
	v_mfma_f32_16x16x32_bf16 v[12:15], v[166:169], v[204:207], v[12:15]
	v_mfma_f32_16x16x32_bf16 v[8:11], v[174:177], v[204:207], v[8:11]
	v_mfma_f32_16x16x32_bf16 v[4:7], v[166:169], v[212:215], v[4:7]
	v_mfma_f32_16x16x32_bf16 v[0:3], v[174:177], v[212:215], v[0:3]
	v_mfma_f32_16x16x32_bf16 v[28:31], v[170:173], v[186:189], v[28:31]
	v_mfma_f32_16x16x32_bf16 v[24:27], v[178:181], v[186:189], v[24:27]
	v_mfma_f32_16x16x32_bf16 v[20:23], v[170:173], v[200:203], v[20:23]
	v_mfma_f32_16x16x32_bf16 v[16:19], v[178:181], v[200:203], v[16:19]
	v_mfma_f32_16x16x32_bf16 v[12:15], v[170:173], v[208:211], v[12:15]
	v_mfma_f32_16x16x32_bf16 v[8:11], v[178:181], v[208:211], v[8:11]
	v_mfma_f32_16x16x32_bf16 v[4:7], v[170:173], v[216:219], v[4:7]
	v_mfma_f32_16x16x32_bf16 v[0:3], v[178:181], v[216:219], v[0:3]
	s_barrier
	s_add_i32 s75, 0, 0x18000
	s_add_i32 s76, 0, 0x1c000
	v_add_u32_e32 v140, s75, v149
	v_add_u32_e32 v178, s76, v149
	ds_read_b128 v[128:131], v140
	ds_read_b128 v[132:135], v140 offset:1024
	ds_read_b128 v[136:139], v140 offset:2048
	ds_read_b128 v[140:143], v140 offset:3072
	ds_read_b128 v[166:169], v178
	ds_read_b128 v[170:173], v178 offset:1024
	ds_read_b128 v[174:177], v178 offset:2048
	ds_read_b128 v[178:181], v178 offset:3072
	s_add_u32 s34, s34, 0x80000
	s_addc_u32 s35, s35, 0
	s_mov_b32 m0, s55
	v_lshl_add_u64 v[226:227], s[34:35], 0, v[150:151]
	ds_read_b128 v[182:185], v195 offset:32768
	ds_read_b128 v[186:189], v195 offset:33792
	ds_read_b128 v[196:199], v195 offset:34816
	ds_read_b128 v[200:203], v195 offset:35840
	ds_read_b128 v[204:207], v195 offset:36864
	ds_read_b128 v[208:211], v195 offset:37888
	ds_read_b128 v[212:215], v195 offset:38912
	ds_read_b128 v[216:219], v195 offset:39936
	global_load_lds_dwordx4 v[226:227], off
	v_lshl_add_u64 v[226:227], s[34:35], 0, v[154:155]
	s_mov_b32 m0, s56
	s_nop 0
	global_load_lds_dwordx4 v[226:227], off
	s_waitcnt vmcnt(8)
	s_waitcnt lgkmcnt(0)
	s_barrier
	s_waitcnt lgkmcnt(0)
	v_mfma_f32_16x16x32_bf16 v[124:127], v[128:131], v[182:185], v[124:127]
	v_mfma_f32_16x16x32_bf16 v[120:123], v[136:139], v[182:185], v[120:123]
	v_mfma_f32_16x16x32_bf16 v[116:119], v[128:131], v[196:199], v[116:119]
	v_mfma_f32_16x16x32_bf16 v[112:115], v[136:139], v[196:199], v[112:115]
	v_mfma_f32_16x16x32_bf16 v[108:111], v[128:131], v[204:207], v[108:111]
	v_mfma_f32_16x16x32_bf16 v[104:107], v[136:139], v[204:207], v[104:107]
	v_mfma_f32_16x16x32_bf16 v[100:103], v[128:131], v[212:215], v[100:103]
	v_mfma_f32_16x16x32_bf16 v[96:99], v[136:139], v[212:215], v[96:99]
	v_mfma_f32_16x16x32_bf16 v[124:127], v[132:135], v[186:189], v[124:127]
	v_mfma_f32_16x16x32_bf16 v[120:123], v[140:143], v[186:189], v[120:123]
	v_mfma_f32_16x16x32_bf16 v[116:119], v[132:135], v[200:203], v[116:119]
	v_mfma_f32_16x16x32_bf16 v[112:115], v[140:143], v[200:203], v[112:115]
	v_mfma_f32_16x16x32_bf16 v[108:111], v[132:135], v[208:211], v[108:111]
	v_mfma_f32_16x16x32_bf16 v[104:107], v[140:143], v[208:211], v[104:107]
	v_mfma_f32_16x16x32_bf16 v[100:103], v[132:135], v[216:219], v[100:103]
	v_mfma_f32_16x16x32_bf16 v[96:99], v[140:143], v[216:219], v[96:99]
	v_mfma_f32_16x16x32_bf16 v[60:63], v[166:169], v[182:185], v[60:63]
	v_mfma_f32_16x16x32_bf16 v[56:59], v[174:177], v[182:185], v[56:59]
	v_mfma_f32_16x16x32_bf16 v[52:55], v[166:169], v[196:199], v[52:55]
	v_mfma_f32_16x16x32_bf16 v[48:51], v[174:177], v[196:199], v[48:51]
	v_mfma_f32_16x16x32_bf16 v[44:47], v[166:169], v[204:207], v[44:47]
	v_mfma_f32_16x16x32_bf16 v[40:43], v[174:177], v[204:207], v[40:43]
	v_mfma_f32_16x16x32_bf16 v[36:39], v[166:169], v[212:215], v[36:39]
	v_mfma_f32_16x16x32_bf16 v[32:35], v[174:177], v[212:215], v[32:35]
	v_mfma_f32_16x16x32_bf16 v[60:63], v[170:173], v[186:189], v[60:63]
	v_mfma_f32_16x16x32_bf16 v[56:59], v[178:181], v[186:189], v[56:59]
	v_mfma_f32_16x16x32_bf16 v[52:55], v[170:173], v[200:203], v[52:55]
	v_mfma_f32_16x16x32_bf16 v[48:51], v[178:181], v[200:203], v[48:51]
	v_mfma_f32_16x16x32_bf16 v[44:47], v[170:173], v[208:211], v[44:47]
	v_mfma_f32_16x16x32_bf16 v[40:43], v[178:181], v[208:211], v[40:43]
	v_mfma_f32_16x16x32_bf16 v[36:39], v[170:173], v[216:219], v[36:39]
	v_mfma_f32_16x16x32_bf16 v[32:35], v[178:181], v[216:219], v[32:35]
	s_barrier
	s_add_i32 s34, s75, s52
	v_lshl_add_u64 v[190:191], v[190:191], 0, s[18:19]
	s_mov_b32 m0, s34
	ds_read_b128 v[182:185], v195 offset:49152
	ds_read_b128 v[186:189], v195 offset:50176
	ds_read_b128 v[196:199], v195 offset:51200
	ds_read_b128 v[200:203], v195 offset:52224
	ds_read_b128 v[204:207], v195 offset:53248
	ds_read_b128 v[208:211], v195 offset:54272
	ds_read_b128 v[212:215], v195 offset:55296
	ds_read_b128 v[216:219], v195 offset:56320
	global_load_lds_dwordx4 v[190:191], off
	s_add_i32 m0, s34, 0x2000
	s_add_u32 s34, s44, 0x80080
	v_lshl_add_u64 v[190:191], v[220:221], 0, s[18:19]
	s_addc_u32 s35, s45, 0
	s_add_i32 s44, s76, s52
	global_load_lds_dwordx4 v[190:191], off
	v_lshl_add_u64 v[190:191], s[34:35], 0, v[152:153]
	s_mov_b32 m0, s44
	s_nop 0
	global_load_lds_dwordx4 v[190:191], off
	v_lshl_add_u64 v[190:191], s[34:35], 0, v[156:157]
	s_add_i32 m0, s44, 0x2000
	s_nop 0
	global_load_lds_dwordx4 v[190:191], off
	v_lshl_add_u64 v[190:191], v[222:223], 0, s[18:19]
	s_mov_b32 m0, s61
	s_nop 0
	global_load_lds_dwordx4 v[190:191], off
	v_lshl_add_u64 v[190:191], v[224:225], 0, s[18:19]
	s_mov_b32 m0, s62
	s_nop 0
	global_load_lds_dwordx4 v[190:191], off
	s_waitcnt vmcnt(8)
	s_waitcnt lgkmcnt(0)
	s_barrier
	s_waitcnt lgkmcnt(0)
	v_mfma_f32_16x16x32_bf16 v[92:95], v[128:131], v[182:185], v[92:95]
	v_mfma_f32_16x16x32_bf16 v[88:91], v[136:139], v[182:185], v[88:91]
	v_mfma_f32_16x16x32_bf16 v[84:87], v[128:131], v[196:199], v[84:87]
	v_mfma_f32_16x16x32_bf16 v[80:83], v[136:139], v[196:199], v[80:83]
	v_mfma_f32_16x16x32_bf16 v[76:79], v[128:131], v[204:207], v[76:79]
	v_mfma_f32_16x16x32_bf16 v[72:75], v[136:139], v[204:207], v[72:75]
	v_mfma_f32_16x16x32_bf16 v[68:71], v[128:131], v[212:215], v[68:71]
	v_mfma_f32_16x16x32_bf16 v[64:67], v[136:139], v[212:215], v[64:67]
	v_mfma_f32_16x16x32_bf16 v[92:95], v[132:135], v[186:189], v[92:95]
	v_mfma_f32_16x16x32_bf16 v[88:91], v[140:143], v[186:189], v[88:91]
	v_mfma_f32_16x16x32_bf16 v[84:87], v[132:135], v[200:203], v[84:87]
	v_mfma_f32_16x16x32_bf16 v[80:83], v[140:143], v[200:203], v[80:83]
	v_mfma_f32_16x16x32_bf16 v[76:79], v[132:135], v[208:211], v[76:79]
	v_mfma_f32_16x16x32_bf16 v[72:75], v[140:143], v[208:211], v[72:75]
	v_mfma_f32_16x16x32_bf16 v[68:71], v[132:135], v[216:219], v[68:71]
	v_mfma_f32_16x16x32_bf16 v[64:67], v[140:143], v[216:219], v[64:67]
	v_mfma_f32_16x16x32_bf16 v[28:31], v[166:169], v[182:185], v[28:31]
	v_mfma_f32_16x16x32_bf16 v[24:27], v[174:177], v[182:185], v[24:27]
	v_mfma_f32_16x16x32_bf16 v[20:23], v[166:169], v[196:199], v[20:23]
	v_mfma_f32_16x16x32_bf16 v[16:19], v[174:177], v[196:199], v[16:19]
	v_mfma_f32_16x16x32_bf16 v[12:15], v[166:169], v[204:207], v[12:15]
	v_mfma_f32_16x16x32_bf16 v[8:11], v[174:177], v[204:207], v[8:11]
	v_mfma_f32_16x16x32_bf16 v[4:7], v[166:169], v[212:215], v[4:7]
	v_mfma_f32_16x16x32_bf16 v[0:3], v[174:177], v[212:215], v[0:3]
	v_mfma_f32_16x16x32_bf16 v[28:31], v[170:173], v[186:189], v[28:31]
	v_mfma_f32_16x16x32_bf16 v[24:27], v[178:181], v[186:189], v[24:27]
	v_mfma_f32_16x16x32_bf16 v[20:23], v[170:173], v[200:203], v[20:23]
	v_mfma_f32_16x16x32_bf16 v[16:19], v[178:181], v[200:203], v[16:19]
	v_mfma_f32_16x16x32_bf16 v[12:15], v[170:173], v[208:211], v[12:15]
	v_mfma_f32_16x16x32_bf16 v[8:11], v[178:181], v[208:211], v[8:11]
	v_mfma_f32_16x16x32_bf16 v[4:7], v[170:173], v[216:219], v[4:7]
	v_mfma_f32_16x16x32_bf16 v[0:3], v[178:181], v[216:219], v[0:3]
	s_barrier
	s_add_i32 s74, s74, 2
	s_add_u32 s42, s42, 0x100
	s_addc_u32 s43, s43, 0
	s_add_u32 s72, s72, 0x100
	s_addc_u32 s73, s73, 0
	s_cmp_gt_u32 s74, 29
	s_cbranch_scc0 .LBB0_2422
	s_and_b64 vcc, exec, s[20:21]
	s_cbranch_vccz .LBB0_2425
	s_barrier

.LBB0_2429:
	s_setprio 0
	s_cmp_gt_i32 s69, 13
	s_cselect_b64 s[0:1], -1, 0
	s_and_b64 s[4:5], s[4:5], s[0:1]
	s_andn2_b64 vcc, exec, s[4:5]
	s_cbranch_vccnz .LBB0_2479
	s_waitcnt vmcnt(0)
	v_cmp_eq_u32_e32 vcc, 0, v146
	s_waitcnt vmcnt(0) lgkmcnt(0)
	s_barrier
	s_and_saveexec_b64 s[4:5], vcc
	s_cbranch_execz .LBB0_2478
	s_add_i32 s3, 0, 0x23fc0
	v_mov_b32_e32 v0, s3
	s_waitcnt vmcnt(0) expcnt(0) lgkmcnt(0)
	ds_read_b32 v2, v0
	s_add_i32 s3, 0, 0x23fc4
	v_mov_b32_e32 v0, s3
	ds_read_b32 v0, v0
	s_waitcnt lgkmcnt(1)
	v_cmp_ne_u32_e32 vcc, 0, v2
	s_cbranch_vccnz .LBB0_2446
	s_add_u32 s6, s30, 0x32200
	s_addc_u32 s7, s31, 0
	s_add_u32 s8, s30, 0x32400
	s_addc_u32 s9, s31, 0
	s_add_u32 s10, s30, 0x32500
	s_addc_u32 s11, s31, 0
	s_add_u32 s12, s30, 0x32600
	s_addc_u32 s13, s31, 0
	s_add_u32 s14, s30, 0x32700
	s_addc_u32 s15, s31, 0
	s_add_u32 s16, s30, 0x32800
	s_addc_u32 s17, s31, 0
	s_add_u32 s18, s30, 0x32900
	s_addc_u32 s19, s31, 0
	s_add_u32 s20, s30, 0x32a00
	s_addc_u32 s21, s31, 0
	s_add_u32 s22, s30, 0x32b00
	s_addc_u32 s23, s31, 0
	s_add_u32 s24, s30, 0x32c00
	s_addc_u32 s25, s31, 0
	s_add_u32 s26, s30, 0x32d00
	s_addc_u32 s27, s31, 0
	s_add_u32 s34, s30, 0x32e00
	s_addc_u32 s35, s31, 0
	s_add_u32 s36, s30, 0x32f00
	s_addc_u32 s37, s31, 0
	s_add_u32 s38, s30, 0x33000
	s_addc_u32 s39, s31, 0
	s_add_u32 s40, s30, 0x33100
	s_addc_u32 s41, s31, 0
	s_add_u32 s42, s30, 0x33200
	s_addc_u32 s43, s31, 0
	s_mul_i32 s3, s71, s85
	s_add_u32 s44, s30, 0x33300
	s_mul_i32 s3, s3, s70
	s_addc_u32 s45, s31, 0
	s_mov_b32 s33, 1
	v_mov_b32_e32 v16, 0
	s_branch .LBB0_2434

.LBB0_2536:
	s_cmp_lt_i32 s68, 15
	s_cselect_b64 s[4:5], -1, 0
	s_and_b64 s[4:5], s[4:5], s[0:1]
	s_andn2_b64 vcc, exec, s[4:5]
	s_cbranch_vccnz .LBB0_2553
	v_readfirstlane_b32 s101, v145
	s_cmp_lt_u32 s101, 4
	s_cbranch_scc1 .Lprio_14
	s_setprio 1
.Lprio_14:
	s_cmpk_gt_i32 s2, 0xaff
	v_readfirstlane_b32 s1, v146
	s_cbranch_scc1 .LBB0_2553
	v_lshrrev_b32_e32 v2, 1, v146
	v_and_b32_e32 v11, 24, v2
	v_lshrrev_b32_e32 v2, 5, v146
	v_and_b32_e32 v2, 4, v2
	v_bfe_u32 v3, v146, 2, 2
	s_add_u32 s3, s30, 0x1f000000
	v_lshlrev_b32_e32 v0, 4, v146
	v_and_b32_e32 v1, 32, v146
	v_bfe_u32 v10, v146, 2, 4
	v_or3_b32 v2, v2, v3, v11
	v_lshrrev_b32_e32 v3, 3, v146
	s_movk_i32 s0, 0x70
	s_addc_u32 s33, s31, 0
	v_bitop3_b32 v8, v0, v1, 48 bitop3:0x6c
	v_and_b32_e32 v9, 64, v146
	v_and_or_b32 v4, v3, s0, v10
	s_movk_i32 s0, 0x60
	v_add_u32_e32 v12, 0x2000, v0
	s_waitcnt lgkmcnt(0)
	s_add_u32 s36, s30, 0x7300000
	v_or_b32_e32 v1, v8, v9
	v_and_or_b32 v3, v3, s0, v2
	v_lshrrev_b32_e32 v0, 7, v12
	s_movk_i32 s0, 0xf0
	s_addc_u32 s37, s31, 0
	v_lshl_or_b32 v130, v3, 12, v1
	v_and_or_b32 v3, v0, s0, v10
	s_movk_i32 s0, 0xe0
	s_ashr_i32 s39, s2, 31
	v_and_or_b32 v0, v0, s0, v2
	s_lshr_b32 s0, s39, 29
	s_add_i32 s0, s2, s0
	s_lshr_b32 s10, s1, 6
	s_ashr_i32 s6, s0, 3
	s_and_b32 s0, s0, -8
	s_lshr_b32 s12, s1, 8
	s_lshl_b32 s38, s10, 10
	s_sub_i32 s0, s2, s0
	s_cmp_lt_i32 s0, 0
	s_movk_i32 s40, 0x161
	s_cselect_b32 s7, s40, 0x160
	s_mul_i32 s0, s0, s7
	s_add_i32 s0, s0, s6
	s_mul_hi_i32 s6, s0, 0x2e8ba2e9
	s_lshr_b32 s7, s6, 31
	s_ashr_i32 s6, s6, 6
	s_add_i32 s6, s6, s7
	s_lshl_b32 s7, s6, 3
	s_mulk_i32 s6, 0x160
	s_sub_i32 s6, s0, s6
	s_sext_i32_i16 s0, s6
	s_bfe_u32 s0, s0, 0x3001c
	s_add_i32 s8, s6, s0
	s_sext_i32_i16 s0, s8
	s_and_b32 s8, s8, 0xfff8
	s_sub_i32 s6, s6, s8
	s_sext_i32_i16 s6, s6
	s_lshr_b32 s0, s0, 3
	s_add_i32 s22, s7, s6
	s_ashr_i32 s23, s22, 31
	s_bfe_i64 s[8:9], s[0:1], 0x100000
	s_lshl_b64 s[6:7], s[22:23], 20
	s_lshl_b64 s[8:9], s[8:9], 20
	s_add_u32 s26, s36, s8
	s_addc_u32 s27, s37, s9
	s_add_i32 s23, s38, 0
	s_add_i32 m0, s23, 0x10000
	v_lshl_or_b32 v134, v0, 12, v1
	global_load_lds_dwordx4 v130, s[26:27]
	s_add_i32 m0, s23, 0x12000
	s_add_u32 s8, s26, 0x80000
	global_load_lds_dwordx4 v134, s[26:27]
	s_addc_u32 s9, s27, 0
	s_add_i32 m0, s23, 0x14000
	s_waitcnt vmcnt(0)
	v_lshl_or_b32 v128, v4, 12, v1
	global_load_lds_dwordx4 v130, s[8:9]
	s_add_i32 m0, s23, 0x16000
	s_add_u32 s24, s3, s6
	s_addc_u32 s25, s33, s7
	s_add_i32 s41, s23, 0x2000
	global_load_lds_dwordx4 v134, s[8:9]
	s_mov_b32 m0, s23
	s_add_u32 s6, s24, 0x80000
	v_lshl_or_b32 v132, v3, 12, v1
	global_load_lds_dwordx4 v128, s[24:25]
	s_mov_b32 m0, s41
	s_addc_u32 s7, s25, 0
	s_add_i32 s42, s23, 0x4000
	global_load_lds_dwordx4 v132, s[24:25]
	s_mov_b32 m0, s42
	s_add_i32 s43, s23, 0x6000
	global_load_lds_dwordx4 v128, s[6:7]
	s_mov_b32 m0, s43
	v_mov_b32_e32 v131, 0
	global_load_lds_dwordx4 v132, s[6:7]
	v_mov_b32_e32 v135, v131
	v_mov_b32_e32 v129, v131
	v_mov_b32_e32 v133, v131
	s_cmp_eq_u32 s12, 1
	s_mov_b32 s44, 0
	v_lshl_add_u64 v[6:7], s[26:27], 0, v[130:131]
	v_lshl_add_u64 v[4:5], s[26:27], 0, v[134:135]
	v_lshl_add_u64 v[0:1], s[24:25], 0, v[128:129]
	s_cselect_b64 s[6:7], -1, 0
	s_cmp_lg_u32 s12, 1
	v_lshl_add_u64 v[2:3], s[24:25], 0, v[132:133]
	s_cbranch_scc1 .LBB0_2540
	s_barrier

.LBB0_2546:
	ds_read_b128 v[154:157], v150
	ds_read_b128 v[158:161], v150 offset:1024
	ds_read_b128 v[162:165], v150 offset:2048
	ds_read_b128 v[166:169], v150 offset:3072
	ds_read_b128 v[170:173], v151
	ds_read_b128 v[174:177], v151 offset:1024
	ds_read_b128 v[178:181], v151 offset:2048
	ds_read_b128 v[182:185], v151 offset:3072
	s_add_u32 s26, s24, 0xfff80080
	s_addc_u32 s27, s25, -1
	s_cmp_eq_u32 s61, 28
	s_cselect_b32 s35, s17, s27
	s_cselect_b32 s34, s57, s26
	s_cselect_b32 s27, s15, s60
	s_cselect_b32 s26, s58, s59
	v_lshl_add_u64 v[218:219], s[24:25], 0, v[136:137]
	s_add_i32 m0, s23, 0xc000
	ds_read_b128 v[186:189], v152
	ds_read_b128 v[190:193], v152 offset:1024
	ds_read_b128 v[194:197], v152 offset:2048
	ds_read_b128 v[198:201], v152 offset:3072
	ds_read_b128 v[202:205], v152 offset:4096
	ds_read_b128 v[206:209], v152 offset:5120
	ds_read_b128 v[210:213], v152 offset:6144
	ds_read_b128 v[214:217], v152 offset:7168
	global_load_lds_dwordx4 v[218:219], off
	v_lshl_add_u64 v[218:219], s[24:25], 0, v[138:139]
	s_add_i32 m0, s23, 0xe000
	s_nop 0
	global_load_lds_dwordx4 v[218:219], off
	s_waitcnt vmcnt(8)
	s_waitcnt lgkmcnt(0)
	s_barrier
	s_waitcnt lgkmcnt(0)
	v_mfma_f32_16x16x32_bf16 v[124:127], v[154:157], v[186:189], v[124:127]
	v_mfma_f32_16x16x32_bf16 v[120:123], v[162:165], v[186:189], v[120:123]
	v_mfma_f32_16x16x32_bf16 v[108:111], v[154:157], v[194:197], v[108:111]
	v_mfma_f32_16x16x32_bf16 v[104:107], v[162:165], v[194:197], v[104:107]
	v_mfma_f32_16x16x32_bf16 v[92:95], v[154:157], v[202:205], v[92:95]
	v_mfma_f32_16x16x32_bf16 v[88:91], v[162:165], v[202:205], v[88:91]
	v_mfma_f32_16x16x32_bf16 v[76:79], v[154:157], v[210:213], v[76:79]
	v_mfma_f32_16x16x32_bf16 v[72:75], v[162:165], v[210:213], v[72:75]
	v_mfma_f32_16x16x32_bf16 v[124:127], v[158:161], v[190:193], v[124:127]
	v_mfma_f32_16x16x32_bf16 v[120:123], v[166:169], v[190:193], v[120:123]
	v_mfma_f32_16x16x32_bf16 v[108:111], v[158:161], v[198:201], v[108:111]
	v_mfma_f32_16x16x32_bf16 v[104:107], v[166:169], v[198:201], v[104:107]
	v_mfma_f32_16x16x32_bf16 v[92:95], v[158:161], v[206:209], v[92:95]
	v_mfma_f32_16x16x32_bf16 v[88:91], v[166:169], v[206:209], v[88:91]
	v_mfma_f32_16x16x32_bf16 v[76:79], v[158:161], v[214:217], v[76:79]
	v_mfma_f32_16x16x32_bf16 v[72:75], v[166:169], v[214:217], v[72:75]
	v_mfma_f32_16x16x32_bf16 v[116:119], v[170:173], v[186:189], v[116:119]
	v_mfma_f32_16x16x32_bf16 v[112:115], v[178:181], v[186:189], v[112:115]
	v_mfma_f32_16x16x32_bf16 v[100:103], v[170:173], v[194:197], v[100:103]
	v_mfma_f32_16x16x32_bf16 v[96:99], v[178:181], v[194:197], v[96:99]
	v_mfma_f32_16x16x32_bf16 v[84:87], v[170:173], v[202:205], v[84:87]
	v_mfma_f32_16x16x32_bf16 v[80:83], v[178:181], v[202:205], v[80:83]
	v_mfma_f32_16x16x32_bf16 v[68:71], v[170:173], v[210:213], v[68:71]
	v_mfma_f32_16x16x32_bf16 v[64:67], v[178:181], v[210:213], v[64:67]
	v_mfma_f32_16x16x32_bf16 v[116:119], v[174:177], v[190:193], v[116:119]
	v_mfma_f32_16x16x32_bf16 v[112:115], v[182:185], v[190:193], v[112:115]
	v_mfma_f32_16x16x32_bf16 v[100:103], v[174:177], v[198:201], v[100:103]
	v_mfma_f32_16x16x32_bf16 v[96:99], v[182:185], v[198:201], v[96:99]
	v_mfma_f32_16x16x32_bf16 v[84:87], v[174:177], v[206:209], v[84:87]
	v_mfma_f32_16x16x32_bf16 v[80:83], v[182:185], v[206:209], v[80:83]
	v_mfma_f32_16x16x32_bf16 v[68:71], v[174:177], v[214:217], v[68:71]
	v_mfma_f32_16x16x32_bf16 v[64:67], v[182:185], v[214:217], v[64:67]
	s_barrier
	s_add_i32 s62, s53, s38
	v_lshl_add_u64 v[218:219], s[26:27], 0, v[130:131]
	s_mov_b32 m0, s62
	ds_read_b128 v[186:189], v152 offset:16384
	ds_read_b128 v[190:193], v152 offset:17408
	ds_read_b128 v[194:197], v152 offset:18432
	ds_read_b128 v[198:201], v152 offset:19456
	ds_read_b128 v[202:205], v152 offset:20480
	ds_read_b128 v[206:209], v152 offset:21504
	ds_read_b128 v[210:213], v152 offset:22528
	ds_read_b128 v[214:217], v152 offset:23552
	global_load_lds_dwordx4 v[218:219], off
	s_add_i32 m0, s62, 0x2000
	s_add_u32 s62, s26, 0x80000
	v_lshl_add_u64 v[220:221], s[26:27], 0, v[134:135]
	s_addc_u32 s63, s27, 0
	s_add_i32 s64, s54, s38
	global_load_lds_dwordx4 v[220:221], off
	v_lshl_add_u64 v[222:223], s[62:63], 0, v[130:131]
	s_mov_b32 m0, s64
	v_lshl_add_u64 v[224:225], s[34:35], 0, v[132:133]
	global_load_lds_dwordx4 v[222:223], off
	v_lshl_add_u64 v[222:223], s[62:63], 0, v[134:135]
	s_add_i32 m0, s64, 0x2000
	s_nop 0
	global_load_lds_dwordx4 v[222:223], off
	v_lshl_add_u64 v[222:223], s[34:35], 0, v[128:129]
	s_mov_b32 m0, s23
	s_nop 0
	global_load_lds_dwordx4 v[222:223], off
	s_mov_b32 m0, s41
	s_nop 0
	global_load_lds_dwordx4 v[224:225], off
	s_waitcnt vmcnt(8)
	s_waitcnt lgkmcnt(0)
	s_barrier
	s_waitcnt lgkmcnt(0)
	v_mfma_f32_16x16x32_bf16 v[60:63], v[154:157], v[186:189], v[60:63]
	v_mfma_f32_16x16x32_bf16 v[56:59], v[162:165], v[186:189], v[56:59]
	v_mfma_f32_16x16x32_bf16 v[44:47], v[154:157], v[194:197], v[44:47]
	v_mfma_f32_16x16x32_bf16 v[40:43], v[162:165], v[194:197], v[40:43]
	v_mfma_f32_16x16x32_bf16 v[28:31], v[154:157], v[202:205], v[28:31]
	v_mfma_f32_16x16x32_bf16 v[24:27], v[162:165], v[202:205], v[24:27]
	v_mfma_f32_16x16x32_bf16 v[12:15], v[154:157], v[210:213], v[12:15]
	v_mfma_f32_16x16x32_bf16 v[8:11], v[162:165], v[210:213], v[8:11]
	v_mfma_f32_16x16x32_bf16 v[60:63], v[158:161], v[190:193], v[60:63]
	v_mfma_f32_16x16x32_bf16 v[56:59], v[166:169], v[190:193], v[56:59]
	v_mfma_f32_16x16x32_bf16 v[44:47], v[158:161], v[198:201], v[44:47]
	v_mfma_f32_16x16x32_bf16 v[40:43], v[166:169], v[198:201], v[40:43]
	v_mfma_f32_16x16x32_bf16 v[28:31], v[158:161], v[206:209], v[28:31]
	v_mfma_f32_16x16x32_bf16 v[24:27], v[166:169], v[206:209], v[24:27]
	v_mfma_f32_16x16x32_bf16 v[12:15], v[158:161], v[214:217], v[12:15]
	v_mfma_f32_16x16x32_bf16 v[8:11], v[166:169], v[214:217], v[8:11]
	v_mfma_f32_16x16x32_bf16 v[52:55], v[170:173], v[186:189], v[52:55]
	v_mfma_f32_16x16x32_bf16 v[48:51], v[178:181], v[186:189], v[48:51]
	v_mfma_f32_16x16x32_bf16 v[36:39], v[170:173], v[194:197], v[36:39]
	v_mfma_f32_16x16x32_bf16 v[32:35], v[178:181], v[194:197], v[32:35]
	v_mfma_f32_16x16x32_bf16 v[20:23], v[170:173], v[202:205], v[20:23]
	v_mfma_f32_16x16x32_bf16 v[16:19], v[178:181], v[202:205], v[16:19]
	v_mfma_f32_16x16x32_bf16 v[4:7], v[170:173], v[210:213], v[4:7]
	v_mfma_f32_16x16x32_bf16 v[0:3], v[178:181], v[210:213], v[0:3]
	v_mfma_f32_16x16x32_bf16 v[52:55], v[174:177], v[190:193], v[52:55]
	v_mfma_f32_16x16x32_bf16 v[48:51], v[182:185], v[190:193], v[48:51]
	v_mfma_f32_16x16x32_bf16 v[36:39], v[174:177], v[198:201], v[36:39]
	v_mfma_f32_16x16x32_bf16 v[32:35], v[182:185], v[198:201], v[32:35]
	v_mfma_f32_16x16x32_bf16 v[20:23], v[174:177], v[206:209], v[20:23]
	v_mfma_f32_16x16x32_bf16 v[16:19], v[182:185], v[206:209], v[16:19]
	v_mfma_f32_16x16x32_bf16 v[4:7], v[174:177], v[214:217], v[4:7]
	v_mfma_f32_16x16x32_bf16 v[0:3], v[182:185], v[214:217], v[0:3]
	s_barrier
	s_add_i32 s62, 0, 0x18000
	v_add_u32_e32 v153, s62, v147
	s_add_i32 s63, 0, 0x1c000
	ds_read_b128 v[154:157], v153
	ds_read_b128 v[158:161], v153 offset:1024
	ds_read_b128 v[162:165], v153 offset:2048
	ds_read_b128 v[166:169], v153 offset:3072
	v_add_u32_e32 v153, s63, v147
	ds_read_b128 v[170:173], v153
	ds_read_b128 v[174:177], v153 offset:1024
	ds_read_b128 v[178:181], v153 offset:2048
	ds_read_b128 v[182:185], v153 offset:3072
	s_add_u32 s34, s34, 0x80000
	s_addc_u32 s35, s35, 0
	s_mov_b32 m0, s42
	v_lshl_add_u64 v[226:227], s[34:35], 0, v[128:129]
	ds_read_b128 v[186:189], v152 offset:32768
	ds_read_b128 v[190:193], v152 offset:33792
	ds_read_b128 v[194:197], v152 offset:34816
	ds_read_b128 v[198:201], v152 offset:35840
	ds_read_b128 v[202:205], v152 offset:36864
	ds_read_b128 v[206:209], v152 offset:37888
	ds_read_b128 v[210:213], v152 offset:38912
	ds_read_b128 v[214:217], v152 offset:39936
	global_load_lds_dwordx4 v[226:227], off
	v_lshl_add_u64 v[226:227], s[34:35], 0, v[132:133]
	s_mov_b32 m0, s43
	s_nop 0
	global_load_lds_dwordx4 v[226:227], off
	s_waitcnt vmcnt(8)
	s_waitcnt lgkmcnt(0)
	s_barrier
	s_waitcnt lgkmcnt(0)
	v_mfma_f32_16x16x32_bf16 v[124:127], v[154:157], v[186:189], v[124:127]
	v_mfma_f32_16x16x32_bf16 v[120:123], v[162:165], v[186:189], v[120:123]
	v_mfma_f32_16x16x32_bf16 v[108:111], v[154:157], v[194:197], v[108:111]
	v_mfma_f32_16x16x32_bf16 v[104:107], v[162:165], v[194:197], v[104:107]
	v_mfma_f32_16x16x32_bf16 v[92:95], v[154:157], v[202:205], v[92:95]
	v_mfma_f32_16x16x32_bf16 v[88:91], v[162:165], v[202:205], v[88:91]
	v_mfma_f32_16x16x32_bf16 v[76:79], v[154:157], v[210:213], v[76:79]
	v_mfma_f32_16x16x32_bf16 v[72:75], v[162:165], v[210:213], v[72:75]
	v_mfma_f32_16x16x32_bf16 v[124:127], v[158:161], v[190:193], v[124:127]
	v_mfma_f32_16x16x32_bf16 v[120:123], v[166:169], v[190:193], v[120:123]
	v_mfma_f32_16x16x32_bf16 v[108:111], v[158:161], v[198:201], v[108:111]
	v_mfma_f32_16x16x32_bf16 v[104:107], v[166:169], v[198:201], v[104:107]
	v_mfma_f32_16x16x32_bf16 v[92:95], v[158:161], v[206:209], v[92:95]
	v_mfma_f32_16x16x32_bf16 v[88:91], v[166:169], v[206:209], v[88:91]
	v_mfma_f32_16x16x32_bf16 v[76:79], v[158:161], v[214:217], v[76:79]
	v_mfma_f32_16x16x32_bf16 v[72:75], v[166:169], v[214:217], v[72:75]
	v_mfma_f32_16x16x32_bf16 v[116:119], v[170:173], v[186:189], v[116:119]
	v_mfma_f32_16x16x32_bf16 v[112:115], v[178:181], v[186:189], v[112:115]
	v_mfma_f32_16x16x32_bf16 v[100:103], v[170:173], v[194:197], v[100:103]
	v_mfma_f32_16x16x32_bf16 v[96:99], v[178:181], v[194:197], v[96:99]
	v_mfma_f32_16x16x32_bf16 v[84:87], v[170:173], v[202:205], v[84:87]
	v_mfma_f32_16x16x32_bf16 v[80:83], v[178:181], v[202:205], v[80:83]
	v_mfma_f32_16x16x32_bf16 v[68:71], v[170:173], v[210:213], v[68:71]
	v_mfma_f32_16x16x32_bf16 v[64:67], v[178:181], v[210:213], v[64:67]
	v_mfma_f32_16x16x32_bf16 v[116:119], v[174:177], v[190:193], v[116:119]
	v_mfma_f32_16x16x32_bf16 v[112:115], v[182:185], v[190:193], v[112:115]
	v_mfma_f32_16x16x32_bf16 v[100:103], v[174:177], v[198:201], v[100:103]
	v_mfma_f32_16x16x32_bf16 v[96:99], v[182:185], v[198:201], v[96:99]
	v_mfma_f32_16x16x32_bf16 v[84:87], v[174:177], v[206:209], v[84:87]
	v_mfma_f32_16x16x32_bf16 v[80:83], v[182:185], v[206:209], v[80:83]
	v_mfma_f32_16x16x32_bf16 v[68:71], v[174:177], v[214:217], v[68:71]
	v_mfma_f32_16x16x32_bf16 v[64:67], v[182:185], v[214:217], v[64:67]
	s_barrier
	s_add_i32 s34, s62, s38
	v_lshl_add_u64 v[218:219], v[218:219], 0, s[10:11]
	s_mov_b32 m0, s34
	ds_read_b128 v[186:189], v152 offset:49152
	ds_read_b128 v[190:193], v152 offset:50176
	ds_read_b128 v[194:197], v152 offset:51200
	ds_read_b128 v[198:201], v152 offset:52224
	ds_read_b128 v[202:205], v152 offset:53248
	ds_read_b128 v[206:209], v152 offset:54272
	ds_read_b128 v[210:213], v152 offset:55296
	ds_read_b128 v[214:217], v152 offset:56320
	global_load_lds_dwordx4 v[218:219], off
	s_add_i32 m0, s34, 0x2000
	s_add_u32 s26, s26, 0x80080
	v_lshl_add_u64 v[218:219], v[220:221], 0, s[10:11]
	s_addc_u32 s27, s27, 0
	s_add_i32 s34, s63, s38
	global_load_lds_dwordx4 v[218:219], off
	v_lshl_add_u64 v[218:219], s[26:27], 0, v[130:131]
	s_mov_b32 m0, s34
	s_nop 0
	global_load_lds_dwordx4 v[218:219], off
	v_lshl_add_u64 v[218:219], s[26:27], 0, v[134:135]
	s_add_i32 m0, s34, 0x2000
	s_nop 0
	global_load_lds_dwordx4 v[218:219], off
	v_lshl_add_u64 v[218:219], v[222:223], 0, s[10:11]
	s_mov_b32 m0, s50
	s_nop 0
	global_load_lds_dwordx4 v[218:219], off
	v_lshl_add_u64 v[218:219], v[224:225], 0, s[10:11]
	s_mov_b32 m0, s51
	s_nop 0
	global_load_lds_dwordx4 v[218:219], off
	s_waitcnt vmcnt(8)
	s_waitcnt lgkmcnt(0)
	s_barrier
	s_waitcnt lgkmcnt(0)
	v_mfma_f32_16x16x32_bf16 v[60:63], v[154:157], v[186:189], v[60:63]
	v_mfma_f32_16x16x32_bf16 v[56:59], v[162:165], v[186:189], v[56:59]
	v_mfma_f32_16x16x32_bf16 v[44:47], v[154:157], v[194:197], v[44:47]
	v_mfma_f32_16x16x32_bf16 v[40:43], v[162:165], v[194:197], v[40:43]
	v_mfma_f32_16x16x32_bf16 v[28:31], v[154:157], v[202:205], v[28:31]
	v_mfma_f32_16x16x32_bf16 v[24:27], v[162:165], v[202:205], v[24:27]
	v_mfma_f32_16x16x32_bf16 v[12:15], v[154:157], v[210:213], v[12:15]
	v_mfma_f32_16x16x32_bf16 v[8:11], v[162:165], v[210:213], v[8:11]
	v_mfma_f32_16x16x32_bf16 v[60:63], v[158:161], v[190:193], v[60:63]
	v_mfma_f32_16x16x32_bf16 v[56:59], v[166:169], v[190:193], v[56:59]
	v_mfma_f32_16x16x32_bf16 v[44:47], v[158:161], v[198:201], v[44:47]
	v_mfma_f32_16x16x32_bf16 v[40:43], v[166:169], v[198:201], v[40:43]
	v_mfma_f32_16x16x32_bf16 v[28:31], v[158:161], v[206:209], v[28:31]
	v_mfma_f32_16x16x32_bf16 v[24:27], v[166:169], v[206:209], v[24:27]
	v_mfma_f32_16x16x32_bf16 v[12:15], v[158:161], v[214:217], v[12:15]
	v_mfma_f32_16x16x32_bf16 v[8:11], v[166:169], v[214:217], v[8:11]
	v_mfma_f32_16x16x32_bf16 v[52:55], v[170:173], v[186:189], v[52:55]
	v_mfma_f32_16x16x32_bf16 v[48:51], v[178:181], v[186:189], v[48:51]
	v_mfma_f32_16x16x32_bf16 v[36:39], v[170:173], v[194:197], v[36:39]
	v_mfma_f32_16x16x32_bf16 v[32:35], v[178:181], v[194:197], v[32:35]
	v_mfma_f32_16x16x32_bf16 v[20:23], v[170:173], v[202:205], v[20:23]
	v_mfma_f32_16x16x32_bf16 v[16:19], v[178:181], v[202:205], v[16:19]
	v_mfma_f32_16x16x32_bf16 v[4:7], v[170:173], v[210:213], v[4:7]
	v_mfma_f32_16x16x32_bf16 v[0:3], v[178:181], v[210:213], v[0:3]
	v_mfma_f32_16x16x32_bf16 v[52:55], v[174:177], v[190:193], v[52:55]
	v_mfma_f32_16x16x32_bf16 v[48:51], v[182:185], v[190:193], v[48:51]
	v_mfma_f32_16x16x32_bf16 v[36:39], v[174:177], v[198:201], v[36:39]
	v_mfma_f32_16x16x32_bf16 v[32:35], v[182:185], v[198:201], v[32:35]
	v_mfma_f32_16x16x32_bf16 v[20:23], v[174:177], v[206:209], v[20:23]
	v_mfma_f32_16x16x32_bf16 v[16:19], v[182:185], v[206:209], v[16:19]
	v_mfma_f32_16x16x32_bf16 v[4:7], v[174:177], v[214:217], v[4:7]
	v_mfma_f32_16x16x32_bf16 v[0:3], v[182:185], v[214:217], v[0:3]
	s_barrier
	s_add_i32 s61, s61, 2
	s_add_u32 s24, s24, 0x100
	s_addc_u32 s25, s25, 0
	s_add_u32 s59, s59, 0x100
	s_addc_u32 s60, s60, 0
	s_cmp_gt_u32 s61, 29
	s_cbranch_scc0 .LBB0_2546
	s_and_b64 vcc, exec, s[12:13]
	s_cbranch_vccz .LBB0_2549
	s_barrier

.LBB0_2553:
	s_setprio 0
	s_cmp_gt_i32 s69, 15
	s_cselect_b64 s[0:1], -1, 0
	s_and_b64 s[4:5], s[4:5], s[0:1]
	s_andn2_b64 vcc, exec, s[4:5]
	s_cbranch_vccnz .LBB0_2603
	s_waitcnt vmcnt(0)
	v_cmp_eq_u32_e32 vcc, 0, v146
	s_waitcnt vmcnt(0) lgkmcnt(0)
	s_barrier
	s_and_saveexec_b64 s[4:5], vcc
	s_cbranch_execz .LBB0_2602
	s_add_i32 s3, 0, 0x23fc0
	v_mov_b32_e32 v0, s3
	s_waitcnt vmcnt(0) expcnt(0) lgkmcnt(0)
	ds_read_b32 v2, v0
	s_add_i32 s3, 0, 0x23fc4
	v_mov_b32_e32 v0, s3
	ds_read_b32 v0, v0
	s_waitcnt lgkmcnt(1)
	v_cmp_ne_u32_e32 vcc, 0, v2
	s_cbranch_vccnz .LBB0_2570
	s_add_u32 s6, s30, 0x32200
	s_addc_u32 s7, s31, 0
	s_add_u32 s8, s30, 0x32400
	s_addc_u32 s9, s31, 0
	s_add_u32 s10, s30, 0x32500
	s_addc_u32 s11, s31, 0
	s_add_u32 s12, s30, 0x32600
	s_addc_u32 s13, s31, 0
	s_add_u32 s14, s30, 0x32700
	s_addc_u32 s15, s31, 0
	s_add_u32 s16, s30, 0x32800
	s_addc_u32 s17, s31, 0
	s_add_u32 s18, s30, 0x32900
	s_addc_u32 s19, s31, 0
	s_add_u32 s20, s30, 0x32a00
	s_addc_u32 s21, s31, 0
	s_add_u32 s22, s30, 0x32b00
	s_addc_u32 s23, s31, 0
	s_add_u32 s24, s30, 0x32c00
	s_addc_u32 s25, s31, 0
	s_add_u32 s26, s30, 0x32d00
	s_addc_u32 s27, s31, 0
	s_add_u32 s34, s30, 0x32e00
	s_addc_u32 s35, s31, 0
	s_add_u32 s36, s30, 0x32f00
	s_addc_u32 s37, s31, 0
	s_add_u32 s38, s30, 0x33000
	s_addc_u32 s39, s31, 0
	s_add_u32 s40, s30, 0x33100
	s_addc_u32 s41, s31, 0
	s_add_u32 s42, s30, 0x33200
	s_addc_u32 s43, s31, 0
	s_mul_i32 s3, s71, s85
	s_add_u32 s44, s30, 0x33300
	s_mul_i32 s3, s3, s70
	s_addc_u32 s45, s31, 0
	s_mov_b32 s33, 1
	v_mov_b32_e32 v16, 0
	s_branch .LBB0_2558

.LBB0_2603:
	s_cmp_lt_i32 s68, 16
	s_cselect_b64 s[4:5], -1, 0
	s_and_b64 s[6:7], s[4:5], s[0:1]
	s_andn2_b64 vcc, exec, s[6:7]
	s_cbranch_vccnz .LBB0_2628
	v_readfirstlane_b32 s101, v145
	s_cmp_lt_u32 s101, 4
	s_cbranch_scc1 .Lprio_15
	s_setprio 1
.Lprio_15:
	s_cmpk_gt_i32 s2, 0x1ff
	v_readfirstlane_b32 s0, v146
	s_cbranch_scc1 .LBB0_2628
	s_add_u32 s3, s30, 0x23000000
	s_addc_u32 s25, s31, 0
	v_lshrrev_b32_e32 v3, 1, v146
	s_waitcnt lgkmcnt(0)
	s_add_u32 s40, s30, 0xb500000
	v_and_b32_e32 v10, 24, v3
	v_lshrrev_b32_e32 v3, 5, v146
	s_addc_u32 s41, s31, 0
	v_and_b32_e32 v3, 4, v3
	v_bfe_u32 v4, v146, 2, 2
	s_ashr_i32 s43, s2, 31
	v_lshlrev_b32_e32 v0, 4, v146
	v_and_b32_e32 v1, 32, v146
	v_bfe_u32 v2, v146, 2, 4
	v_or3_b32 v3, v3, v4, v10
	v_lshrrev_b32_e32 v4, 3, v146
	s_movk_i32 s1, 0x70
	s_lshr_b32 s4, s43, 29
	v_bitop3_b32 v8, v0, v1, 48 bitop3:0x6c
	v_and_or_b32 v5, v4, s1, v2
	s_movk_i32 s1, 0x60
	v_add_u32_e32 v0, 0x2000, v0
	s_add_i32 s4, s2, s4
	v_and_or_b32 v4, v4, s1, v3
	v_lshrrev_b32_e32 v0, 7, v0
	s_movk_i32 s1, 0xf0
	s_ashr_i32 s8, s4, 3
	s_and_b32 s4, s4, -8
	v_and_or_b32 v2, v0, s1, v2
	s_movk_i32 s1, 0xe0
	s_lshr_b32 s5, s0, 6
	s_sub_i32 s4, s2, s4
	v_and_or_b32 v0, v0, s1, v3
	s_lshr_b32 s1, s0, 8
	s_lshl_b32 s42, s5, 10
	s_lshl_b32 s10, s4, 6
	s_mul_i32 s9, s4, 0x41
	s_cmp_lt_i32 s4, 0
	s_cselect_b32 s4, s9, s10
	s_add_i32 s4, s4, s8
	s_ashr_i32 s8, s4, 31
	s_lshr_b32 s8, s8, 26
	s_add_i32 s8, s4, s8
	s_ashr_i32 s9, s8, 6
	s_and_b32 s8, s8, 0xffc0
	s_sub_i32 s8, s4, s8
	s_bfe_i32 s4, s8, 0x80000
	s_bfe_u32 s4, s4, 0x3000c
	s_add_i32 s10, s8, s4
	s_bfe_i32 s4, s10, 0x80000
	s_and_b32 s10, s10, 0xf8
	s_sub_i32 s8, s8, s10
	s_lshl_b32 s9, s9, 3
	s_sext_i32_i16 s11, s4
	s_sext_i32_i8 s8, s8
	v_and_b32_e32 v9, 64, v146
	s_add_i32 s33, s9, s8
	s_ashr_i32 s8, s11, 3
	v_or_b32_e32 v1, v8, v9
	s_lshr_b32 s4, s11, 3
	s_mul_hi_i32 s9, s8, 0x2c0000
	s_mul_i32 s8, s8, 0x2c0000
	v_lshrrev_b32_e32 v1, 1, v1
	v_mul_u32_u24_e32 v4, 0x1600, v4
	s_add_u32 s38, s40, s8
	v_or_b32_e32 v4, v4, v1
	s_addc_u32 s39, s41, s9
	s_add_i32 s44, s42, 0
	v_lshlrev_b32_e32 v152, 1, v4
	v_mul_u32_u24_e32 v0, 0x1600, v0
	s_add_i32 m0, s44, 0x10000
	v_or_b32_e32 v0, v0, v1
	global_load_lds_dwordx4 v152, s[38:39]
	s_add_i32 m0, s44, 0x12000
	v_lshlrev_b32_e32 v156, 1, v0
	s_add_u32 s8, s38, 0x160000
	global_load_lds_dwordx4 v156, s[38:39]
	s_addc_u32 s9, s39, 0
	s_add_i32 m0, s44, 0x14000
	s_mul_i32 s12, s33, 0x2c0000
	global_load_lds_dwordx4 v152, s[8:9]
	s_add_i32 m0, s44, 0x16000
	v_mul_u32_u24_e32 v11, 0x1600, v5
	s_mul_hi_i32 s10, s33, 0x2c0000
	s_add_u32 s36, s3, s12
	v_or_b32_e32 v5, v1, v11
	v_mul_u32_u24_e32 v12, 0x1600, v2
	s_addc_u32 s37, s25, s10
	s_add_i32 s45, s44, 0x2000
	v_lshlrev_b32_e32 v150, 1, v5
	v_or_b32_e32 v2, v12, v1
	global_load_lds_dwordx4 v156, s[8:9]
	s_mov_b32 m0, s44
	s_add_u32 s8, s36, 0x160000
	v_lshlrev_b32_e32 v154, 1, v2
	global_load_lds_dwordx4 v150, s[36:37]
	s_mov_b32 m0, s45
	s_addc_u32 s9, s37, 0
	s_add_i32 s50, s44, 0x4000
	global_load_lds_dwordx4 v154, s[36:37]
	s_mov_b32 m0, s50
	s_add_i32 s51, s44, 0x6000
	global_load_lds_dwordx4 v150, s[8:9]
	s_mov_b32 m0, s51
	v_mov_b32_e32 v153, 0
	global_load_lds_dwordx4 v154, s[8:9]
	v_mov_b32_e32 v157, v153
	v_mov_b32_e32 v151, v153
	v_mov_b32_e32 v155, v153
	s_cmp_eq_u32 s1, 1
	s_mov_b32 s52, 0
	v_lshl_add_u64 v[6:7], s[38:39], 0, v[152:153]
	v_lshl_add_u64 v[4:5], s[38:39], 0, v[156:157]
	v_lshl_add_u64 v[0:1], s[36:37], 0, v[150:151]
	s_cselect_b64 s[8:9], -1, 0
	s_cmp_lg_u32 s1, 1
	v_lshl_add_u64 v[2:3], s[36:37], 0, v[154:155]
	s_cbranch_scc1 .LBB0_2607
	s_barrier

.LBB0_2621:
	ds_read_b128 v[128:131], v192
	ds_read_b128 v[132:135], v192 offset:1024
	ds_read_b128 v[136:139], v192 offset:2048
	ds_read_b128 v[140:143], v192 offset:3072
	ds_read_b128 v[166:169], v193
	ds_read_b128 v[170:173], v193 offset:1024
	ds_read_b128 v[174:177], v193 offset:2048
	ds_read_b128 v[178:181], v193 offset:3072
	s_add_u32 s34, s36, 0xffea0080
	s_addc_u32 s35, s37, -1
	s_cmpk_eq_i32 s66, 0x54
	s_cselect_b32 s35, s5, s35
	s_cselect_b32 s34, s4, s34
	s_cselect_b32 s39, s27, s65
	s_cselect_b32 s38, s26, s64
	v_lshl_add_u64 v[190:191], s[36:37], 0, v[158:159]
	s_add_i32 m0, s44, 0xc000
	ds_read_b128 v[182:185], v194
	ds_read_b128 v[186:189], v194 offset:1024
	ds_read_b128 v[196:199], v194 offset:2048
	ds_read_b128 v[200:203], v194 offset:3072
	ds_read_b128 v[204:207], v194 offset:4096
	ds_read_b128 v[208:211], v194 offset:5120
	ds_read_b128 v[212:215], v194 offset:6144
	ds_read_b128 v[216:219], v194 offset:7168
	global_load_lds_dwordx4 v[190:191], off
	v_lshl_add_u64 v[190:191], s[36:37], 0, v[160:161]
	s_add_i32 m0, s44, 0xe000
	s_nop 0
	global_load_lds_dwordx4 v[190:191], off
	s_waitcnt vmcnt(8)
	s_waitcnt lgkmcnt(0)
	s_barrier
	s_waitcnt lgkmcnt(0)
	v_mfma_f32_16x16x32_bf16 v[124:127], v[128:131], v[182:185], v[124:127]
	v_mfma_f32_16x16x32_bf16 v[120:123], v[136:139], v[182:185], v[120:123]
	v_mfma_f32_16x16x32_bf16 v[116:119], v[128:131], v[196:199], v[116:119]
	v_mfma_f32_16x16x32_bf16 v[112:115], v[136:139], v[196:199], v[112:115]
	v_mfma_f32_16x16x32_bf16 v[108:111], v[128:131], v[204:207], v[108:111]
	v_mfma_f32_16x16x32_bf16 v[104:107], v[136:139], v[204:207], v[104:107]
	v_mfma_f32_16x16x32_bf16 v[100:103], v[128:131], v[212:215], v[100:103]
	v_mfma_f32_16x16x32_bf16 v[96:99], v[136:139], v[212:215], v[96:99]
	v_mfma_f32_16x16x32_bf16 v[124:127], v[132:135], v[186:189], v[124:127]
	v_mfma_f32_16x16x32_bf16 v[120:123], v[140:143], v[186:189], v[120:123]
	v_mfma_f32_16x16x32_bf16 v[116:119], v[132:135], v[200:203], v[116:119]
	v_mfma_f32_16x16x32_bf16 v[112:115], v[140:143], v[200:203], v[112:115]
	v_mfma_f32_16x16x32_bf16 v[108:111], v[132:135], v[208:211], v[108:111]
	v_mfma_f32_16x16x32_bf16 v[104:107], v[140:143], v[208:211], v[104:107]
	v_mfma_f32_16x16x32_bf16 v[100:103], v[132:135], v[216:219], v[100:103]
	v_mfma_f32_16x16x32_bf16 v[96:99], v[140:143], v[216:219], v[96:99]
	v_mfma_f32_16x16x32_bf16 v[60:63], v[166:169], v[182:185], v[60:63]
	v_mfma_f32_16x16x32_bf16 v[56:59], v[174:177], v[182:185], v[56:59]
	v_mfma_f32_16x16x32_bf16 v[52:55], v[166:169], v[196:199], v[52:55]
	v_mfma_f32_16x16x32_bf16 v[48:51], v[174:177], v[196:199], v[48:51]
	v_mfma_f32_16x16x32_bf16 v[44:47], v[166:169], v[204:207], v[44:47]
	v_mfma_f32_16x16x32_bf16 v[40:43], v[174:177], v[204:207], v[40:43]
	v_mfma_f32_16x16x32_bf16 v[36:39], v[166:169], v[212:215], v[36:39]
	v_mfma_f32_16x16x32_bf16 v[32:35], v[174:177], v[212:215], v[32:35]
	v_mfma_f32_16x16x32_bf16 v[60:63], v[170:173], v[186:189], v[60:63]
	v_mfma_f32_16x16x32_bf16 v[56:59], v[178:181], v[186:189], v[56:59]
	v_mfma_f32_16x16x32_bf16 v[52:55], v[170:173], v[200:203], v[52:55]
	v_mfma_f32_16x16x32_bf16 v[48:51], v[178:181], v[200:203], v[48:51]
	v_mfma_f32_16x16x32_bf16 v[44:47], v[170:173], v[208:211], v[44:47]
	v_mfma_f32_16x16x32_bf16 v[40:43], v[178:181], v[208:211], v[40:43]
	v_mfma_f32_16x16x32_bf16 v[36:39], v[170:173], v[216:219], v[36:39]
	v_mfma_f32_16x16x32_bf16 v[32:35], v[178:181], v[216:219], v[32:35]
	s_barrier
	s_add_i32 s67, s59, s42
	v_lshl_add_u64 v[190:191], s[38:39], 0, v[152:153]
	s_mov_b32 m0, s67
	ds_read_b128 v[182:185], v194 offset:16384
	ds_read_b128 v[186:189], v194 offset:17408
	ds_read_b128 v[196:199], v194 offset:18432
	ds_read_b128 v[200:203], v194 offset:19456
	ds_read_b128 v[204:207], v194 offset:20480
	ds_read_b128 v[208:211], v194 offset:21504
	ds_read_b128 v[212:215], v194 offset:22528
	ds_read_b128 v[216:219], v194 offset:23552
	global_load_lds_dwordx4 v[190:191], off
	s_add_i32 m0, s67, 0x2000
	s_add_u32 s72, s38, 0x160000
	v_lshl_add_u64 v[220:221], s[38:39], 0, v[156:157]
	s_addc_u32 s73, s39, 0
	s_add_i32 s67, s60, s42
	global_load_lds_dwordx4 v[220:221], off
	v_lshl_add_u64 v[222:223], s[72:73], 0, v[152:153]
	s_mov_b32 m0, s67
	v_lshl_add_u64 v[224:225], s[34:35], 0, v[154:155]
	global_load_lds_dwordx4 v[222:223], off
	v_lshl_add_u64 v[222:223], s[72:73], 0, v[156:157]
	s_add_i32 m0, s67, 0x2000
	s_nop 0
	global_load_lds_dwordx4 v[222:223], off
	v_lshl_add_u64 v[222:223], s[34:35], 0, v[150:151]
	s_mov_b32 m0, s44
	s_nop 0
	global_load_lds_dwordx4 v[222:223], off
	s_mov_b32 m0, s45
	s_nop 0
	global_load_lds_dwordx4 v[224:225], off
	s_waitcnt vmcnt(8)
	s_waitcnt lgkmcnt(0)
	s_barrier
	s_waitcnt lgkmcnt(0)
	v_mfma_f32_16x16x32_bf16 v[92:95], v[128:131], v[182:185], v[92:95]
	v_mfma_f32_16x16x32_bf16 v[88:91], v[136:139], v[182:185], v[88:91]
	v_mfma_f32_16x16x32_bf16 v[84:87], v[128:131], v[196:199], v[84:87]
	v_mfma_f32_16x16x32_bf16 v[80:83], v[136:139], v[196:199], v[80:83]
	v_mfma_f32_16x16x32_bf16 v[76:79], v[128:131], v[204:207], v[76:79]
	v_mfma_f32_16x16x32_bf16 v[72:75], v[136:139], v[204:207], v[72:75]
	v_mfma_f32_16x16x32_bf16 v[68:71], v[128:131], v[212:215], v[68:71]
	v_mfma_f32_16x16x32_bf16 v[64:67], v[136:139], v[212:215], v[64:67]
	v_mfma_f32_16x16x32_bf16 v[92:95], v[132:135], v[186:189], v[92:95]
	v_mfma_f32_16x16x32_bf16 v[88:91], v[140:143], v[186:189], v[88:91]
	v_mfma_f32_16x16x32_bf16 v[84:87], v[132:135], v[200:203], v[84:87]
	v_mfma_f32_16x16x32_bf16 v[80:83], v[140:143], v[200:203], v[80:83]
	v_mfma_f32_16x16x32_bf16 v[76:79], v[132:135], v[208:211], v[76:79]
	v_mfma_f32_16x16x32_bf16 v[72:75], v[140:143], v[208:211], v[72:75]
	v_mfma_f32_16x16x32_bf16 v[68:71], v[132:135], v[216:219], v[68:71]
	v_mfma_f32_16x16x32_bf16 v[64:67], v[140:143], v[216:219], v[64:67]
	v_mfma_f32_16x16x32_bf16 v[28:31], v[166:169], v[182:185], v[28:31]
	v_mfma_f32_16x16x32_bf16 v[24:27], v[174:177], v[182:185], v[24:27]
	v_mfma_f32_16x16x32_bf16 v[20:23], v[166:169], v[196:199], v[20:23]
	v_mfma_f32_16x16x32_bf16 v[16:19], v[174:177], v[196:199], v[16:19]
	v_mfma_f32_16x16x32_bf16 v[12:15], v[166:169], v[204:207], v[12:15]
	v_mfma_f32_16x16x32_bf16 v[8:11], v[174:177], v[204:207], v[8:11]
	v_mfma_f32_16x16x32_bf16 v[4:7], v[166:169], v[212:215], v[4:7]
	v_mfma_f32_16x16x32_bf16 v[0:3], v[174:177], v[212:215], v[0:3]
	v_mfma_f32_16x16x32_bf16 v[28:31], v[170:173], v[186:189], v[28:31]
	v_mfma_f32_16x16x32_bf16 v[24:27], v[178:181], v[186:189], v[24:27]
	v_mfma_f32_16x16x32_bf16 v[20:23], v[170:173], v[200:203], v[20:23]
	v_mfma_f32_16x16x32_bf16 v[16:19], v[178:181], v[200:203], v[16:19]
	v_mfma_f32_16x16x32_bf16 v[12:15], v[170:173], v[208:211], v[12:15]
	v_mfma_f32_16x16x32_bf16 v[8:11], v[178:181], v[208:211], v[8:11]
	v_mfma_f32_16x16x32_bf16 v[4:7], v[170:173], v[216:219], v[4:7]
	v_mfma_f32_16x16x32_bf16 v[0:3], v[178:181], v[216:219], v[0:3]
	s_barrier
	s_add_i32 s67, 0, 0x18000
	s_add_i32 s72, 0, 0x1c000
	v_add_u32_e32 v140, s67, v147
	v_add_u32_e32 v178, s72, v147
	ds_read_b128 v[128:131], v140
	ds_read_b128 v[132:135], v140 offset:1024
	ds_read_b128 v[136:139], v140 offset:2048
	ds_read_b128 v[140:143], v140 offset:3072
	ds_read_b128 v[166:169], v178
	ds_read_b128 v[170:173], v178 offset:1024
	ds_read_b128 v[174:177], v178 offset:2048
	ds_read_b128 v[178:181], v178 offset:3072
	s_add_u32 s34, s34, 0x160000
	s_addc_u32 s35, s35, 0
	s_mov_b32 m0, s50
	v_lshl_add_u64 v[226:227], s[34:35], 0, v[150:151]
	ds_read_b128 v[182:185], v194 offset:32768
	ds_read_b128 v[186:189], v194 offset:33792
	ds_read_b128 v[196:199], v194 offset:34816
	ds_read_b128 v[200:203], v194 offset:35840
	ds_read_b128 v[204:207], v194 offset:36864
	ds_read_b128 v[208:211], v194 offset:37888
	ds_read_b128 v[212:215], v194 offset:38912
	ds_read_b128 v[216:219], v194 offset:39936
	global_load_lds_dwordx4 v[226:227], off
	v_lshl_add_u64 v[226:227], s[34:35], 0, v[154:155]
	s_mov_b32 m0, s51
	s_nop 0
	global_load_lds_dwordx4 v[226:227], off
	s_waitcnt vmcnt(8)
	s_waitcnt lgkmcnt(0)
	s_barrier
	s_waitcnt lgkmcnt(0)
	v_mfma_f32_16x16x32_bf16 v[124:127], v[128:131], v[182:185], v[124:127]
	v_mfma_f32_16x16x32_bf16 v[120:123], v[136:139], v[182:185], v[120:123]
	v_mfma_f32_16x16x32_bf16 v[116:119], v[128:131], v[196:199], v[116:119]
	v_mfma_f32_16x16x32_bf16 v[112:115], v[136:139], v[196:199], v[112:115]
	v_mfma_f32_16x16x32_bf16 v[108:111], v[128:131], v[204:207], v[108:111]
	v_mfma_f32_16x16x32_bf16 v[104:107], v[136:139], v[204:207], v[104:107]
	v_mfma_f32_16x16x32_bf16 v[100:103], v[128:131], v[212:215], v[100:103]
	v_mfma_f32_16x16x32_bf16 v[96:99], v[136:139], v[212:215], v[96:99]
	v_mfma_f32_16x16x32_bf16 v[124:127], v[132:135], v[186:189], v[124:127]
	v_mfma_f32_16x16x32_bf16 v[120:123], v[140:143], v[186:189], v[120:123]
	v_mfma_f32_16x16x32_bf16 v[116:119], v[132:135], v[200:203], v[116:119]
	v_mfma_f32_16x16x32_bf16 v[112:115], v[140:143], v[200:203], v[112:115]
	v_mfma_f32_16x16x32_bf16 v[108:111], v[132:135], v[208:211], v[108:111]
	v_mfma_f32_16x16x32_bf16 v[104:107], v[140:143], v[208:211], v[104:107]
	v_mfma_f32_16x16x32_bf16 v[100:103], v[132:135], v[216:219], v[100:103]
	v_mfma_f32_16x16x32_bf16 v[96:99], v[140:143], v[216:219], v[96:99]
	v_mfma_f32_16x16x32_bf16 v[60:63], v[166:169], v[182:185], v[60:63]
	v_mfma_f32_16x16x32_bf16 v[56:59], v[174:177], v[182:185], v[56:59]
	v_mfma_f32_16x16x32_bf16 v[52:55], v[166:169], v[196:199], v[52:55]
	v_mfma_f32_16x16x32_bf16 v[48:51], v[174:177], v[196:199], v[48:51]
	v_mfma_f32_16x16x32_bf16 v[44:47], v[166:169], v[204:207], v[44:47]
	v_mfma_f32_16x16x32_bf16 v[40:43], v[174:177], v[204:207], v[40:43]
	v_mfma_f32_16x16x32_bf16 v[36:39], v[166:169], v[212:215], v[36:39]
	v_mfma_f32_16x16x32_bf16 v[32:35], v[174:177], v[212:215], v[32:35]
	v_mfma_f32_16x16x32_bf16 v[60:63], v[170:173], v[186:189], v[60:63]
	v_mfma_f32_16x16x32_bf16 v[56:59], v[178:181], v[186:189], v[56:59]
	v_mfma_f32_16x16x32_bf16 v[52:55], v[170:173], v[200:203], v[52:55]
	v_mfma_f32_16x16x32_bf16 v[48:51], v[178:181], v[200:203], v[48:51]
	v_mfma_f32_16x16x32_bf16 v[44:47], v[170:173], v[208:211], v[44:47]
	v_mfma_f32_16x16x32_bf16 v[40:43], v[178:181], v[208:211], v[40:43]
	v_mfma_f32_16x16x32_bf16 v[36:39], v[170:173], v[216:219], v[36:39]
	v_mfma_f32_16x16x32_bf16 v[32:35], v[178:181], v[216:219], v[32:35]
	s_barrier
	s_add_i32 s34, s67, s42
	v_lshl_add_u64 v[190:191], v[190:191], 0, s[20:21]
	s_mov_b32 m0, s34
	ds_read_b128 v[182:185], v194 offset:49152
	ds_read_b128 v[186:189], v194 offset:50176
	ds_read_b128 v[196:199], v194 offset:51200
	ds_read_b128 v[200:203], v194 offset:52224
	ds_read_b128 v[204:207], v194 offset:53248
	ds_read_b128 v[208:211], v194 offset:54272
	ds_read_b128 v[212:215], v194 offset:55296
	ds_read_b128 v[216:219], v194 offset:56320
	global_load_lds_dwordx4 v[190:191], off
	s_add_i32 m0, s34, 0x2000
	s_add_u32 s34, s38, 0x160080
	v_lshl_add_u64 v[190:191], v[220:221], 0, s[20:21]
	s_addc_u32 s35, s39, 0
	s_add_i32 s38, s72, s42
	global_load_lds_dwordx4 v[190:191], off
	v_lshl_add_u64 v[190:191], s[34:35], 0, v[152:153]
	s_mov_b32 m0, s38
	s_nop 0
	global_load_lds_dwordx4 v[190:191], off
	v_lshl_add_u64 v[190:191], s[34:35], 0, v[156:157]
	s_add_i32 m0, s38, 0x2000
	s_nop 0
	global_load_lds_dwordx4 v[190:191], off
	v_lshl_add_u64 v[190:191], v[222:223], 0, s[20:21]
	s_mov_b32 m0, s56
	s_nop 0
	global_load_lds_dwordx4 v[190:191], off
	v_lshl_add_u64 v[190:191], v[224:225], 0, s[20:21]
	s_mov_b32 m0, s57
	s_nop 0
	global_load_lds_dwordx4 v[190:191], off
	s_waitcnt vmcnt(8)
	s_waitcnt lgkmcnt(0)
	s_barrier
	s_waitcnt lgkmcnt(0)
	v_mfma_f32_16x16x32_bf16 v[92:95], v[128:131], v[182:185], v[92:95]
	v_mfma_f32_16x16x32_bf16 v[88:91], v[136:139], v[182:185], v[88:91]
	v_mfma_f32_16x16x32_bf16 v[84:87], v[128:131], v[196:199], v[84:87]
	v_mfma_f32_16x16x32_bf16 v[80:83], v[136:139], v[196:199], v[80:83]
	v_mfma_f32_16x16x32_bf16 v[76:79], v[128:131], v[204:207], v[76:79]
	v_mfma_f32_16x16x32_bf16 v[72:75], v[136:139], v[204:207], v[72:75]
	v_mfma_f32_16x16x32_bf16 v[68:71], v[128:131], v[212:215], v[68:71]
	v_mfma_f32_16x16x32_bf16 v[64:67], v[136:139], v[212:215], v[64:67]
	v_mfma_f32_16x16x32_bf16 v[92:95], v[132:135], v[186:189], v[92:95]
	v_mfma_f32_16x16x32_bf16 v[88:91], v[140:143], v[186:189], v[88:91]
	v_mfma_f32_16x16x32_bf16 v[84:87], v[132:135], v[200:203], v[84:87]
	v_mfma_f32_16x16x32_bf16 v[80:83], v[140:143], v[200:203], v[80:83]
	v_mfma_f32_16x16x32_bf16 v[76:79], v[132:135], v[208:211], v[76:79]
	v_mfma_f32_16x16x32_bf16 v[72:75], v[140:143], v[208:211], v[72:75]
	v_mfma_f32_16x16x32_bf16 v[68:71], v[132:135], v[216:219], v[68:71]
	v_mfma_f32_16x16x32_bf16 v[64:67], v[140:143], v[216:219], v[64:67]
	v_mfma_f32_16x16x32_bf16 v[28:31], v[166:169], v[182:185], v[28:31]
	v_mfma_f32_16x16x32_bf16 v[24:27], v[174:177], v[182:185], v[24:27]
	v_mfma_f32_16x16x32_bf16 v[20:23], v[166:169], v[196:199], v[20:23]
	v_mfma_f32_16x16x32_bf16 v[16:19], v[174:177], v[196:199], v[16:19]
	v_mfma_f32_16x16x32_bf16 v[12:15], v[166:169], v[204:207], v[12:15]
	v_mfma_f32_16x16x32_bf16 v[8:11], v[174:177], v[204:207], v[8:11]
	v_mfma_f32_16x16x32_bf16 v[4:7], v[166:169], v[212:215], v[4:7]
	v_mfma_f32_16x16x32_bf16 v[0:3], v[174:177], v[212:215], v[0:3]
	v_mfma_f32_16x16x32_bf16 v[28:31], v[170:173], v[186:189], v[28:31]
	v_mfma_f32_16x16x32_bf16 v[24:27], v[178:181], v[186:189], v[24:27]
	v_mfma_f32_16x16x32_bf16 v[20:23], v[170:173], v[200:203], v[20:23]
	v_mfma_f32_16x16x32_bf16 v[16:19], v[178:181], v[200:203], v[16:19]
	v_mfma_f32_16x16x32_bf16 v[12:15], v[170:173], v[208:211], v[12:15]
	v_mfma_f32_16x16x32_bf16 v[8:11], v[178:181], v[208:211], v[8:11]
	v_mfma_f32_16x16x32_bf16 v[4:7], v[170:173], v[216:219], v[4:7]
	v_mfma_f32_16x16x32_bf16 v[0:3], v[178:181], v[216:219], v[0:3]
	s_barrier
	s_add_i32 s66, s66, 2
	s_add_u32 s36, s36, 0x100
	s_addc_u32 s37, s37, 0
	s_add_u32 s64, s64, 0x100
	s_addc_u32 s65, s65, 0
	s_cmpk_gt_u32 s66, 0x55
	s_cbranch_scc0 .LBB0_2621
	s_and_b64 vcc, exec, s[22:23]
	s_cbranch_vccz .LBB0_2624
	s_barrier

.LBB0_2628:
	s_setprio 0
	s_cmp_gt_i32 s69, 16
	s_cselect_b64 s[0:1], -1, 0
	s_and_b64 s[2:3], s[6:7], s[0:1]
	s_andn2_b64 vcc, exec, s[2:3]
	s_cbranch_vccnz .LBB0_2678
	s_waitcnt vmcnt(0)
	v_cmp_eq_u32_e32 vcc, 0, v146
	s_waitcnt vmcnt(0) lgkmcnt(0)
	s_barrier
	s_and_saveexec_b64 s[2:3], vcc
	s_cbranch_execz .LBB0_2677
	s_add_i32 s4, 0, 0x23fc0
	v_mov_b32_e32 v0, s4
	s_waitcnt vmcnt(0) expcnt(0) lgkmcnt(0)
	ds_read_b32 v2, v0
	s_add_i32 s4, 0, 0x23fc4
	v_mov_b32_e32 v0, s4
	ds_read_b32 v0, v0
	s_waitcnt lgkmcnt(1)
	v_cmp_ne_u32_e32 vcc, 0, v2
	s_cbranch_vccnz .LBB0_2645
	s_add_u32 s4, s30, 0x32200
	s_addc_u32 s5, s31, 0
	s_add_u32 s6, s30, 0x32400
	s_addc_u32 s7, s31, 0
	s_add_u32 s8, s30, 0x32500
	s_addc_u32 s9, s31, 0
	s_add_u32 s10, s30, 0x32600
	s_addc_u32 s11, s31, 0
	s_add_u32 s12, s30, 0x32700
	s_addc_u32 s13, s31, 0
	s_add_u32 s14, s30, 0x32800
	s_addc_u32 s15, s31, 0
	s_add_u32 s16, s30, 0x32900
	s_addc_u32 s17, s31, 0
	s_add_u32 s18, s30, 0x32a00
	s_addc_u32 s19, s31, 0
	s_add_u32 s20, s30, 0x32b00
	s_addc_u32 s21, s31, 0
	s_add_u32 s22, s30, 0x32c00
	s_addc_u32 s23, s31, 0
	s_add_u32 s24, s30, 0x32d00
	s_addc_u32 s25, s31, 0
	s_add_u32 s26, s30, 0x32e00
	s_addc_u32 s27, s31, 0
	s_add_u32 s34, s30, 0x32f00
	s_addc_u32 s35, s31, 0
	s_add_u32 s36, s30, 0x33000
	s_addc_u32 s37, s31, 0
	s_add_u32 s38, s30, 0x33100
	s_addc_u32 s39, s31, 0
	s_add_u32 s40, s30, 0x33200
	s_addc_u32 s41, s31, 0
	s_mul_i32 s33, s71, s85
	s_add_u32 s42, s30, 0x33300
	s_mul_i32 s33, s33, s70
	s_addc_u32 s43, s31, 0
	s_mov_b32 s54, 1
	v_mov_b32_e32 v16, 0
	s_branch .LBB0_2633
